# GEMM K-loops: deleted the 36 adjacent s_setprio 0 / s_setprio 1 no-op pairs between the two 16-MFMA groups of each super-phase
# baseline (speedup 1.0000x reference)
; #define PG8_STAGE(bufoff, gbase, voff) do { _Pragma("unroll") for (int _i = 0; _i < 2; ++_i) \
;         __builtin_amdgcn_global_load_lds((const unsigned*)((const char*)(gbase) + (voff)[_i]), (PG8_LAS unsigned*)(lds + (bufoff) + ldsw + _i * 8192), 16, 0, 0); } while (0)
; #define PG8_LDA(dst, b, h) do { _Pragma("unroll") for (int m = 0; m < 4; ++m) _Pragma("unroll") for (int k = 0; k < 2; ++k) dst[m][k] = *(const PG8_LAS bf16x8*)(lds + PG8_SA(b, h) + aoff + m * 2048 + k * 1024); } while (0)
; #define PG8_LDB(dst, b, h) do { _Pragma("unroll") for (int n = 0; n < 2; ++n) _Pragma("unroll") for (int k = 0; k < 2; ++k) dst[n][k] = *(const PG8_LAS bf16x8*)(lds + PG8_SB(b, h) + boff + n * 2048 + k * 1024); } while (0)
; #define PG8_MMA(ai, bj, At, Bt) do { __builtin_amdgcn_s_setprio(1); _Pragma("unroll") for (int m = 0; m < 4; ++m) _Pragma("unroll") for (int n = 0; n < 2; ++n) _Pragma("unroll") for (int k = 0; k < 2; ++k) \
;         acc[ai][bj][m][n] = __builtin_amdgcn_mfma_f32_16x16x32_bf16(Bt[n][k], At[m][k], acc[ai][bj][m][n], 0, 0, 0); __builtin_amdgcn_s_setprio(0); } while (0)
; #define PG8_BAR __builtin_amdgcn_s_barrier()
; template <class Epi, class Sched, bool ALIGN_EPI = false, bool SP2 = false>
; __device__ __forceinline__ void gemm_phase(PG8_LAS unsigned char* lds, const Gemm g, const Sched& S, const Epi& E, const int tid_in) {
;     ...
;             PG8_LDB(B0, 0, 0); PG8_LDB(B1, 0, 1); PG8_SCHED; PG8_LDA(At, 0, 0); PG8_STAGE(PG8_SA(1, 1), a1 + hstepA, voffA);
;             PG8_WAIT_V(8); PG8_WAIT_L(0); PG8_BAR; PG8_MMA(0, 0, At, B0); PG8_MMA(0, 1, At, B1); PG8_BAR; PG8_SCHED;
;             PG8_LDA(At, 0, 1); PG8_STAGE(PG8_SB(0, 0), b2, voffB); PG8_STAGE(PG8_SB(0, 1), b2 + hstepB, voffB); PG8_STAGE(PG8_SA(0, 0), a2, voffA);
;             PG8_WAIT_V(8); PG8_WAIT_L(0); PG8_BAR; PG8_MMA(1, 0, At, B0); PG8_MMA(1, 1, At, B1); PG8_BAR; PG8_SCHED;
;             PG8_LDB(B0, 1, 0); PG8_LDB(B1, 1, 1); PG8_SCHED; PG8_LDA(At, 1, 0); PG8_STAGE(PG8_SA(0, 1), a2 + hstepA, voffA);
;             PG8_WAIT_V(8); PG8_WAIT_L(0); PG8_BAR; PG8_MMA(0, 0, At, B0); PG8_MMA(0, 1, At, B1); PG8_BAR; PG8_SCHED;
;             PG8_LDA(At, 1, 1); PG8_STAGE(PG8_SB(1, 0), b3, voffB); PG8_STAGE(PG8_SB(1, 1), b3 + hstepB, voffB); PG8_STAGE(PG8_SA(1, 0), a3, voffA);
;             PG8_WAIT_V(8); PG8_WAIT_L(0); PG8_BAR; PG8_MMA(1, 0, At, B0); PG8_MMA(1, 1, At, B1); PG8_BAR; PG8_SCHED;
.LBB0_286:
	s_add_u32 s22, s20, 0xfffc0080
	s_addc_u32 s23, s21, -1
	s_add_i32 s47, 0, 0x10000
	s_cmp_eq_u32 s46, 12
	s_cselect_b32 s25, s15, s23
	s_cselect_b32 s24, s42, s22
	v_add_u32_e32 v142, s47, v143
	s_cselect_b32 s23, s13, s45
	s_cselect_b32 s22, s43, s44
	s_add_i32 s52, 0, 0x14000
	ds_read_b128 v[146:149], v142
	ds_read_b128 v[150:153], v142 offset:1024
	ds_read_b128 v[154:157], v142 offset:2048
	ds_read_b128 v[158:161], v142 offset:3072
	v_add_u32_e32 v142, s52, v143
	ds_read_b128 v[162:165], v142
	ds_read_b128 v[166:169], v142 offset:1024
	ds_read_b128 v[170:173], v142 offset:2048
	ds_read_b128 v[174:177], v142 offset:3072
	v_lshl_add_u64 v[194:195], s[20:21], 0, v[138:139]
	s_add_i32 m0, s29, 0xc000
	ds_read_b128 v[178:181], v145
	ds_read_b128 v[182:185], v145 offset:1024
	ds_read_b128 v[186:189], v145 offset:2048
	ds_read_b128 v[190:193], v145 offset:3072
	ds_read_b128 v[200:203], v145 offset:4096
	ds_read_b128 v[204:207], v145 offset:5120
	ds_read_b128 v[208:211], v145 offset:6144
	ds_read_b128 v[212:215], v145 offset:7168
	global_load_lds_dwordx4 v[194:195], off
	v_lshl_add_u64 v[194:195], s[20:21], 0, v[140:141]
	s_add_i32 m0, s29, 0xe000
	s_nop 0
	global_load_lds_dwordx4 v[194:195], off
	s_waitcnt vmcnt(8)
	s_waitcnt lgkmcnt(0)
	s_barrier
	s_setprio 1
	s_waitcnt lgkmcnt(0)
	v_mfma_f32_16x16x32_bf16 v[128:131], v[146:149], v[178:181], v[128:131]
	v_mfma_f32_16x16x32_bf16 v[124:127], v[154:157], v[178:181], v[124:127]
	v_mfma_f32_16x16x32_bf16 v[112:115], v[146:149], v[186:189], v[112:115]
	v_mfma_f32_16x16x32_bf16 v[108:111], v[154:157], v[186:189], v[108:111]
	v_mfma_f32_16x16x32_bf16 v[92:95], v[146:149], v[200:203], v[92:95]
	v_mfma_f32_16x16x32_bf16 v[88:91], v[154:157], v[200:203], v[88:91]
	v_mfma_f32_16x16x32_bf16 v[84:87], v[146:149], v[208:211], v[84:87]
	v_mfma_f32_16x16x32_bf16 v[76:79], v[154:157], v[208:211], v[76:79]
	v_mfma_f32_16x16x32_bf16 v[128:131], v[150:153], v[182:185], v[128:131]
	v_mfma_f32_16x16x32_bf16 v[124:127], v[158:161], v[182:185], v[124:127]
	v_mfma_f32_16x16x32_bf16 v[112:115], v[150:153], v[190:193], v[112:115]
	v_mfma_f32_16x16x32_bf16 v[108:111], v[158:161], v[190:193], v[108:111]
	v_mfma_f32_16x16x32_bf16 v[92:95], v[150:153], v[204:207], v[92:95]
	v_mfma_f32_16x16x32_bf16 v[88:91], v[158:161], v[204:207], v[88:91]
	v_mfma_f32_16x16x32_bf16 v[84:87], v[150:153], v[212:215], v[84:87]
	v_mfma_f32_16x16x32_bf16 v[76:79], v[158:161], v[212:215], v[76:79]
	v_mfma_f32_16x16x32_bf16 v[120:123], v[162:165], v[178:181], v[120:123]
	v_mfma_f32_16x16x32_bf16 v[116:119], v[170:173], v[178:181], v[116:119]
	v_mfma_f32_16x16x32_bf16 v[104:107], v[162:165], v[186:189], v[104:107]
	v_mfma_f32_16x16x32_bf16 v[100:103], v[170:173], v[186:189], v[100:103]
	v_mfma_f32_16x16x32_bf16 v[80:83], v[162:165], v[200:203], v[80:83]
	v_mfma_f32_16x16x32_bf16 v[72:75], v[170:173], v[200:203], v[72:75]
	v_mfma_f32_16x16x32_bf16 v[68:71], v[162:165], v[208:211], v[68:71]
	v_mfma_f32_16x16x32_bf16 v[64:67], v[170:173], v[208:211], v[64:67]
	v_mfma_f32_16x16x32_bf16 v[120:123], v[166:169], v[182:185], v[120:123]
	v_mfma_f32_16x16x32_bf16 v[116:119], v[174:177], v[182:185], v[116:119]
	v_mfma_f32_16x16x32_bf16 v[104:107], v[166:169], v[190:193], v[104:107]
	v_mfma_f32_16x16x32_bf16 v[100:103], v[174:177], v[190:193], v[100:103]
	v_mfma_f32_16x16x32_bf16 v[80:83], v[166:169], v[204:207], v[80:83]
	v_mfma_f32_16x16x32_bf16 v[72:75], v[174:177], v[204:207], v[72:75]
	v_mfma_f32_16x16x32_bf16 v[68:71], v[166:169], v[212:215], v[68:71]
	v_mfma_f32_16x16x32_bf16 v[64:67], v[174:177], v[212:215], v[64:67]
	s_setprio 0
	s_barrier
	s_add_i32 s47, s47, s28
	v_lshl_add_u64 v[194:195], s[22:23], 0, v[134:135]
	s_mov_b32 m0, s47
	ds_read_b128 v[178:181], v145 offset:16384
	ds_read_b128 v[182:185], v145 offset:17408
	ds_read_b128 v[186:189], v145 offset:18432
	ds_read_b128 v[190:193], v145 offset:19456
	ds_read_b128 v[200:203], v145 offset:20480
	ds_read_b128 v[204:207], v145 offset:21504
	ds_read_b128 v[208:211], v145 offset:22528
	ds_read_b128 v[212:215], v145 offset:23552
	global_load_lds_dwordx4 v[194:195], off
	s_add_i32 m0, s47, 0x2000
	s_add_u32 s48, s22, 0x40000
	v_lshl_add_u64 v[196:197], s[22:23], 0, v[96:97]
	s_addc_u32 s49, s23, 0
	s_add_i32 s47, s52, s28
	global_load_lds_dwordx4 v[196:197], off
	v_lshl_add_u64 v[216:217], s[48:49], 0, v[134:135]
	s_mov_b32 m0, s47
	v_lshl_add_u64 v[218:219], s[24:25], 0, v[132:133]
	global_load_lds_dwordx4 v[216:217], off
	v_lshl_add_u64 v[216:217], s[48:49], 0, v[96:97]
	s_add_i32 m0, s47, 0x2000
	s_nop 0
	global_load_lds_dwordx4 v[216:217], off
	v_lshl_add_u64 v[216:217], s[24:25], 0, v[136:137]
	s_mov_b32 m0, s29
	s_nop 0
	global_load_lds_dwordx4 v[216:217], off
	s_mov_b32 m0, s30
	s_nop 0
	global_load_lds_dwordx4 v[218:219], off
	s_waitcnt vmcnt(8)
	s_waitcnt lgkmcnt(0)
	s_barrier
; #define PG8_STAGE(bufoff, gbase, voff) do { _Pragma("unroll") for (int _i = 0; _i < 2; ++_i) \
;         __builtin_amdgcn_global_load_lds((const unsigned*)((const char*)(gbase) + (voff)[_i]), (PG8_LAS unsigned*)(lds + (bufoff) + ldsw + _i * 8192), 16, 0, 0); } while (0)
; #define PG8_LDA(dst, b, h) do { _Pragma("unroll") for (int m = 0; m < 4; ++m) _Pragma("unroll") for (int k = 0; k < 2; ++k) dst[m][k] = *(const PG8_LAS bf16x8*)(lds + PG8_SA(b, h) + aoff + m * 2048 + k * 1024); } while (0)
; #define PG8_LDB(dst, b, h) do { _Pragma("unroll") for (int n = 0; n < 2; ++n) _Pragma("unroll") for (int k = 0; k < 2; ++k) dst[n][k] = *(const PG8_LAS bf16x8*)(lds + PG8_SB(b, h) + boff + n * 2048 + k * 1024); } while (0)
; #define PG8_MMA(ai, bj, At, Bt) do { __builtin_amdgcn_s_setprio(1); _Pragma("unroll") for (int m = 0; m < 4; ++m) _Pragma("unroll") for (int n = 0; n < 2; ++n) _Pragma("unroll") for (int k = 0; k < 2; ++k) \
;         acc[ai][bj][m][n] = __builtin_amdgcn_mfma_f32_16x16x32_bf16(Bt[n][k], At[m][k], acc[ai][bj][m][n], 0, 0, 0); __builtin_amdgcn_s_setprio(0); } while (0)
; #define PG8_BAR __builtin_amdgcn_s_barrier()
; template <class Epi, class Sched, bool ALIGN_EPI = false, bool SP2 = false>
; __device__ __forceinline__ void gemm_phase(PG8_LAS unsigned char* lds, const Gemm g, const Sched& S, const Epi& E, const int tid_in) {
;     ...
;             PG8_LDB(B0, 0, 0); PG8_LDB(B1, 0, 1); PG8_SCHED; PG8_LDA(At, 0, 0); PG8_STAGE(PG8_SA(1, 1), a1 + hstepA, voffA);
;             PG8_WAIT_V(8); PG8_WAIT_L(0); PG8_BAR; PG8_MMA(0, 0, At, B0); PG8_MMA(0, 1, At, B1); PG8_BAR; PG8_SCHED;
;             PG8_LDA(At, 0, 1); PG8_STAGE(PG8_SB(0, 0), b2, voffB); PG8_STAGE(PG8_SB(0, 1), b2 + hstepB, voffB); PG8_STAGE(PG8_SA(0, 0), a2, voffA);
;             PG8_WAIT_V(8); PG8_WAIT_L(0); PG8_BAR; PG8_MMA(1, 0, At, B0); PG8_MMA(1, 1, At, B1); PG8_BAR; PG8_SCHED;
;             PG8_LDB(B0, 1, 0); PG8_LDB(B1, 1, 1); PG8_SCHED; PG8_LDA(At, 1, 0); PG8_STAGE(PG8_SA(0, 1), a2 + hstepA, voffA);
;             PG8_WAIT_V(8); PG8_WAIT_L(0); PG8_BAR; PG8_MMA(0, 0, At, B0); PG8_MMA(0, 1, At, B1); PG8_BAR; PG8_SCHED;
;             PG8_LDA(At, 1, 1); PG8_STAGE(PG8_SB(1, 0), b3, voffB); PG8_STAGE(PG8_SB(1, 1), b3 + hstepB, voffB); PG8_STAGE(PG8_SA(1, 0), a3, voffA);
;             PG8_WAIT_V(8); PG8_WAIT_L(0); PG8_BAR; PG8_MMA(1, 0, At, B0); PG8_MMA(1, 1, At, B1); PG8_BAR; PG8_SCHED;
	s_setprio 1
	s_waitcnt lgkmcnt(0)
	v_mfma_f32_16x16x32_bf16 v[60:63], v[146:149], v[178:181], v[60:63]
	v_mfma_f32_16x16x32_bf16 v[56:59], v[154:157], v[178:181], v[56:59]
	v_mfma_f32_16x16x32_bf16 v[52:55], v[146:149], v[186:189], v[52:55]
	v_mfma_f32_16x16x32_bf16 v[44:47], v[154:157], v[186:189], v[44:47]
	v_mfma_f32_16x16x32_bf16 v[36:39], v[146:149], v[200:203], v[36:39]
	v_mfma_f32_16x16x32_bf16 v[28:31], v[154:157], v[200:203], v[28:31]
	v_mfma_f32_16x16x32_bf16 v[20:23], v[146:149], v[208:211], v[20:23]
	v_mfma_f32_16x16x32_bf16 v[12:15], v[154:157], v[208:211], v[12:15]
	v_mfma_f32_16x16x32_bf16 v[60:63], v[150:153], v[182:185], v[60:63]
	v_mfma_f32_16x16x32_bf16 v[56:59], v[158:161], v[182:185], v[56:59]
	v_mfma_f32_16x16x32_bf16 v[52:55], v[150:153], v[190:193], v[52:55]
	v_mfma_f32_16x16x32_bf16 v[44:47], v[158:161], v[190:193], v[44:47]
	v_mfma_f32_16x16x32_bf16 v[36:39], v[150:153], v[204:207], v[36:39]
	v_mfma_f32_16x16x32_bf16 v[28:31], v[158:161], v[204:207], v[28:31]
	v_mfma_f32_16x16x32_bf16 v[20:23], v[150:153], v[212:215], v[20:23]
	v_mfma_f32_16x16x32_bf16 v[12:15], v[158:161], v[212:215], v[12:15]
	v_mfma_f32_16x16x32_bf16 v[48:51], v[162:165], v[178:181], v[48:51]
	v_mfma_f32_16x16x32_bf16 v[40:43], v[170:173], v[178:181], v[40:43]
	v_mfma_f32_16x16x32_bf16 v[32:35], v[162:165], v[186:189], v[32:35]
	v_mfma_f32_16x16x32_bf16 v[24:27], v[170:173], v[186:189], v[24:27]
	v_mfma_f32_16x16x32_bf16 v[16:19], v[162:165], v[200:203], v[16:19]
	v_mfma_f32_16x16x32_bf16 v[8:11], v[170:173], v[200:203], v[8:11]
	v_mfma_f32_16x16x32_bf16 v[4:7], v[162:165], v[208:211], v[4:7]
	v_mfma_f32_16x16x32_bf16 v[0:3], v[170:173], v[208:211], v[0:3]
	v_mfma_f32_16x16x32_bf16 v[48:51], v[166:169], v[182:185], v[48:51]
	v_mfma_f32_16x16x32_bf16 v[40:43], v[174:177], v[182:185], v[40:43]
	v_mfma_f32_16x16x32_bf16 v[32:35], v[166:169], v[190:193], v[32:35]
	v_mfma_f32_16x16x32_bf16 v[24:27], v[174:177], v[190:193], v[24:27]
	v_mfma_f32_16x16x32_bf16 v[16:19], v[166:169], v[204:207], v[16:19]
	v_mfma_f32_16x16x32_bf16 v[8:11], v[174:177], v[204:207], v[8:11]
	v_mfma_f32_16x16x32_bf16 v[4:7], v[166:169], v[212:215], v[4:7]
	v_mfma_f32_16x16x32_bf16 v[0:3], v[174:177], v[212:215], v[0:3]
	s_setprio 0
	s_barrier
	s_add_i32 s47, 0, 0x18000
	v_add_u32_e32 v142, s47, v143
	s_add_i32 s48, 0, 0x1c000
	ds_read_b128 v[146:149], v142
	ds_read_b128 v[150:153], v142 offset:1024
	ds_read_b128 v[154:157], v142 offset:2048
	ds_read_b128 v[158:161], v142 offset:3072
	v_add_u32_e32 v142, s48, v143
	ds_read_b128 v[162:165], v142
	ds_read_b128 v[166:169], v142 offset:1024
	ds_read_b128 v[170:173], v142 offset:2048
	ds_read_b128 v[174:177], v142 offset:3072
	s_add_u32 s24, s24, 0x40000
	s_addc_u32 s25, s25, 0
	s_mov_b32 m0, s31
	v_lshl_add_u64 v[220:221], s[24:25], 0, v[136:137]
	ds_read_b128 v[178:181], v145 offset:32768
	ds_read_b128 v[182:185], v145 offset:33792
	ds_read_b128 v[186:189], v145 offset:34816
	ds_read_b128 v[190:193], v145 offset:35840
	ds_read_b128 v[200:203], v145 offset:36864
	ds_read_b128 v[204:207], v145 offset:37888
	ds_read_b128 v[208:211], v145 offset:38912
	ds_read_b128 v[212:215], v145 offset:39936
	global_load_lds_dwordx4 v[220:221], off
	v_lshl_add_u64 v[220:221], s[24:25], 0, v[132:133]
	s_mov_b32 m0, s34
	s_nop 0
	global_load_lds_dwordx4 v[220:221], off
	s_waitcnt vmcnt(8)
	s_waitcnt lgkmcnt(0)
	s_barrier
	s_setprio 1
	s_waitcnt lgkmcnt(0)
	v_mfma_f32_16x16x32_bf16 v[128:131], v[146:149], v[178:181], v[128:131]
	v_mfma_f32_16x16x32_bf16 v[124:127], v[154:157], v[178:181], v[124:127]
	v_mfma_f32_16x16x32_bf16 v[112:115], v[146:149], v[186:189], v[112:115]
	v_mfma_f32_16x16x32_bf16 v[108:111], v[154:157], v[186:189], v[108:111]
	v_mfma_f32_16x16x32_bf16 v[92:95], v[146:149], v[200:203], v[92:95]
	v_mfma_f32_16x16x32_bf16 v[88:91], v[154:157], v[200:203], v[88:91]
	v_mfma_f32_16x16x32_bf16 v[84:87], v[146:149], v[208:211], v[84:87]
	v_mfma_f32_16x16x32_bf16 v[76:79], v[154:157], v[208:211], v[76:79]
	v_mfma_f32_16x16x32_bf16 v[128:131], v[150:153], v[182:185], v[128:131]
	v_mfma_f32_16x16x32_bf16 v[124:127], v[158:161], v[182:185], v[124:127]
	v_mfma_f32_16x16x32_bf16 v[112:115], v[150:153], v[190:193], v[112:115]
	v_mfma_f32_16x16x32_bf16 v[108:111], v[158:161], v[190:193], v[108:111]
	v_mfma_f32_16x16x32_bf16 v[92:95], v[150:153], v[204:207], v[92:95]
	v_mfma_f32_16x16x32_bf16 v[88:91], v[158:161], v[204:207], v[88:91]
	v_mfma_f32_16x16x32_bf16 v[84:87], v[150:153], v[212:215], v[84:87]
	v_mfma_f32_16x16x32_bf16 v[76:79], v[158:161], v[212:215], v[76:79]
	v_mfma_f32_16x16x32_bf16 v[120:123], v[162:165], v[178:181], v[120:123]
	v_mfma_f32_16x16x32_bf16 v[116:119], v[170:173], v[178:181], v[116:119]
	v_mfma_f32_16x16x32_bf16 v[104:107], v[162:165], v[186:189], v[104:107]
	v_mfma_f32_16x16x32_bf16 v[100:103], v[170:173], v[186:189], v[100:103]
	v_mfma_f32_16x16x32_bf16 v[80:83], v[162:165], v[200:203], v[80:83]
	v_mfma_f32_16x16x32_bf16 v[72:75], v[170:173], v[200:203], v[72:75]
	v_mfma_f32_16x16x32_bf16 v[68:71], v[162:165], v[208:211], v[68:71]
	v_mfma_f32_16x16x32_bf16 v[64:67], v[170:173], v[208:211], v[64:67]
	v_mfma_f32_16x16x32_bf16 v[120:123], v[166:169], v[182:185], v[120:123]
	v_mfma_f32_16x16x32_bf16 v[116:119], v[174:177], v[182:185], v[116:119]
	v_mfma_f32_16x16x32_bf16 v[104:107], v[166:169], v[190:193], v[104:107]
	v_mfma_f32_16x16x32_bf16 v[100:103], v[174:177], v[190:193], v[100:103]
	v_mfma_f32_16x16x32_bf16 v[80:83], v[166:169], v[204:207], v[80:83]
	v_mfma_f32_16x16x32_bf16 v[72:75], v[174:177], v[204:207], v[72:75]
	v_mfma_f32_16x16x32_bf16 v[68:71], v[166:169], v[212:215], v[68:71]
	v_mfma_f32_16x16x32_bf16 v[64:67], v[174:177], v[212:215], v[64:67]
	s_setprio 0
	s_barrier
; #define PG8_STAGE(bufoff, gbase, voff) do { _Pragma("unroll") for (int _i = 0; _i < 2; ++_i) \
;         __builtin_amdgcn_global_load_lds((const unsigned*)((const char*)(gbase) + (voff)[_i]), (PG8_LAS unsigned*)(lds + (bufoff) + ldsw + _i * 8192), 16, 0, 0); } while (0)
; #define PG8_LDA(dst, b, h) do { _Pragma("unroll") for (int m = 0; m < 4; ++m) _Pragma("unroll") for (int k = 0; k < 2; ++k) dst[m][k] = *(const PG8_LAS bf16x8*)(lds + PG8_SA(b, h) + aoff + m * 2048 + k * 1024); } while (0)
; #define PG8_LDB(dst, b, h) do { _Pragma("unroll") for (int n = 0; n < 2; ++n) _Pragma("unroll") for (int k = 0; k < 2; ++k) dst[n][k] = *(const PG8_LAS bf16x8*)(lds + PG8_SB(b, h) + boff + n * 2048 + k * 1024); } while (0)
; #define PG8_MMA(ai, bj, At, Bt) do { __builtin_amdgcn_s_setprio(1); _Pragma("unroll") for (int m = 0; m < 4; ++m) _Pragma("unroll") for (int n = 0; n < 2; ++n) _Pragma("unroll") for (int k = 0; k < 2; ++k) \
;         acc[ai][bj][m][n] = __builtin_amdgcn_mfma_f32_16x16x32_bf16(Bt[n][k], At[m][k], acc[ai][bj][m][n], 0, 0, 0); __builtin_amdgcn_s_setprio(0); } while (0)
; #define PG8_BAR __builtin_amdgcn_s_barrier()
; template <class Epi, class Sched, bool ALIGN_EPI = false, bool SP2 = false>
; __device__ __forceinline__ void gemm_phase(PG8_LAS unsigned char* lds, const Gemm g, const Sched& S, const Epi& E, const int tid_in) {
;     ...
;             PG8_LDB(B0, 0, 0); PG8_LDB(B1, 0, 1); PG8_SCHED; PG8_LDA(At, 0, 0); PG8_STAGE(PG8_SA(1, 1), a1 + hstepA, voffA);
;             PG8_WAIT_V(8); PG8_WAIT_L(0); PG8_BAR; PG8_MMA(0, 0, At, B0); PG8_MMA(0, 1, At, B1); PG8_BAR; PG8_SCHED;
;             PG8_LDA(At, 0, 1); PG8_STAGE(PG8_SB(0, 0), b2, voffB); PG8_STAGE(PG8_SB(0, 1), b2 + hstepB, voffB); PG8_STAGE(PG8_SA(0, 0), a2, voffA);
;             PG8_WAIT_V(8); PG8_WAIT_L(0); PG8_BAR; PG8_MMA(1, 0, At, B0); PG8_MMA(1, 1, At, B1); PG8_BAR; PG8_SCHED;
;             PG8_LDB(B0, 1, 0); PG8_LDB(B1, 1, 1); PG8_SCHED; PG8_LDA(At, 1, 0); PG8_STAGE(PG8_SA(0, 1), a2 + hstepA, voffA);
;             PG8_WAIT_V(8); PG8_WAIT_L(0); PG8_BAR; PG8_MMA(0, 0, At, B0); PG8_MMA(0, 1, At, B1); PG8_BAR; PG8_SCHED;
;             PG8_LDA(At, 1, 1); PG8_STAGE(PG8_SB(1, 0), b3, voffB); PG8_STAGE(PG8_SB(1, 1), b3 + hstepB, voffB); PG8_STAGE(PG8_SA(1, 0), a3, voffA);
;             PG8_WAIT_V(8); PG8_WAIT_L(0); PG8_BAR; PG8_MMA(1, 0, At, B0); PG8_MMA(1, 1, At, B1); PG8_BAR; PG8_SCHED;
	s_add_i32 s24, s47, s28
	v_lshl_add_u64 v[194:195], v[194:195], 0, s[50:51]
	s_mov_b32 m0, s24
	ds_read_b128 v[178:181], v145 offset:49152
	ds_read_b128 v[182:185], v145 offset:50176
	ds_read_b128 v[186:189], v145 offset:51200
	ds_read_b128 v[190:193], v145 offset:52224
	ds_read_b128 v[200:203], v145 offset:53248
	ds_read_b128 v[204:207], v145 offset:54272
	ds_read_b128 v[208:211], v145 offset:55296
	ds_read_b128 v[212:215], v145 offset:56320
	global_load_lds_dwordx4 v[194:195], off
	s_add_i32 m0, s24, 0x2000
	s_add_u32 s22, s22, 0x40080
	v_lshl_add_u64 v[194:195], v[196:197], 0, s[50:51]
	s_addc_u32 s23, s23, 0
	s_add_i32 s24, s48, s28
	global_load_lds_dwordx4 v[194:195], off
	v_lshl_add_u64 v[194:195], s[22:23], 0, v[134:135]
	s_mov_b32 m0, s24
	s_nop 0
	global_load_lds_dwordx4 v[194:195], off
	v_lshl_add_u64 v[194:195], s[22:23], 0, v[96:97]
	s_add_i32 m0, s24, 0x2000
	s_nop 0
	global_load_lds_dwordx4 v[194:195], off
	v_lshl_add_u64 v[194:195], v[216:217], 0, s[50:51]
	s_mov_b32 m0, s37
	s_nop 0
	global_load_lds_dwordx4 v[194:195], off
	v_lshl_add_u64 v[194:195], v[218:219], 0, s[50:51]
	s_mov_b32 m0, s38
	s_nop 0
	global_load_lds_dwordx4 v[194:195], off
	s_waitcnt vmcnt(8)
	s_waitcnt lgkmcnt(0)
	s_barrier
	s_setprio 1
	s_waitcnt lgkmcnt(0)
	v_mfma_f32_16x16x32_bf16 v[60:63], v[146:149], v[178:181], v[60:63]
	v_mfma_f32_16x16x32_bf16 v[56:59], v[154:157], v[178:181], v[56:59]
	v_mfma_f32_16x16x32_bf16 v[52:55], v[146:149], v[186:189], v[52:55]
	v_mfma_f32_16x16x32_bf16 v[44:47], v[154:157], v[186:189], v[44:47]
	v_mfma_f32_16x16x32_bf16 v[36:39], v[146:149], v[200:203], v[36:39]
	v_mfma_f32_16x16x32_bf16 v[28:31], v[154:157], v[200:203], v[28:31]
	v_mfma_f32_16x16x32_bf16 v[20:23], v[146:149], v[208:211], v[20:23]
	v_mfma_f32_16x16x32_bf16 v[12:15], v[154:157], v[208:211], v[12:15]
	v_mfma_f32_16x16x32_bf16 v[60:63], v[150:153], v[182:185], v[60:63]
	v_mfma_f32_16x16x32_bf16 v[56:59], v[158:161], v[182:185], v[56:59]
	v_mfma_f32_16x16x32_bf16 v[52:55], v[150:153], v[190:193], v[52:55]
	v_mfma_f32_16x16x32_bf16 v[44:47], v[158:161], v[190:193], v[44:47]
	v_mfma_f32_16x16x32_bf16 v[36:39], v[150:153], v[204:207], v[36:39]
	v_mfma_f32_16x16x32_bf16 v[28:31], v[158:161], v[204:207], v[28:31]
	v_mfma_f32_16x16x32_bf16 v[20:23], v[150:153], v[212:215], v[20:23]
	v_mfma_f32_16x16x32_bf16 v[12:15], v[158:161], v[212:215], v[12:15]
	v_mfma_f32_16x16x32_bf16 v[48:51], v[162:165], v[178:181], v[48:51]
	v_mfma_f32_16x16x32_bf16 v[40:43], v[170:173], v[178:181], v[40:43]
	v_mfma_f32_16x16x32_bf16 v[32:35], v[162:165], v[186:189], v[32:35]
	v_mfma_f32_16x16x32_bf16 v[24:27], v[170:173], v[186:189], v[24:27]
	v_mfma_f32_16x16x32_bf16 v[16:19], v[162:165], v[200:203], v[16:19]
	v_mfma_f32_16x16x32_bf16 v[8:11], v[170:173], v[200:203], v[8:11]
	v_mfma_f32_16x16x32_bf16 v[4:7], v[162:165], v[208:211], v[4:7]
	v_mfma_f32_16x16x32_bf16 v[0:3], v[170:173], v[208:211], v[0:3]
	v_mfma_f32_16x16x32_bf16 v[48:51], v[166:169], v[182:185], v[48:51]
	v_mfma_f32_16x16x32_bf16 v[40:43], v[174:177], v[182:185], v[40:43]
	v_mfma_f32_16x16x32_bf16 v[32:35], v[166:169], v[190:193], v[32:35]
	v_mfma_f32_16x16x32_bf16 v[24:27], v[174:177], v[190:193], v[24:27]
	v_mfma_f32_16x16x32_bf16 v[16:19], v[166:169], v[204:207], v[16:19]
	v_mfma_f32_16x16x32_bf16 v[8:11], v[174:177], v[204:207], v[8:11]
	v_mfma_f32_16x16x32_bf16 v[4:7], v[166:169], v[212:215], v[4:7]
	v_mfma_f32_16x16x32_bf16 v[0:3], v[174:177], v[212:215], v[0:3]
	s_setprio 0
	s_barrier
	s_add_i32 s46, s46, 2
	s_add_u32 s20, s20, 0x100
	s_addc_u32 s21, s21, 0
	s_add_u32 s44, s44, 0x100
	s_addc_u32 s45, s45, 0
	s_cmp_gt_u32 s46, 13
	s_cbranch_scc0 .LBB0_286
	s_and_b64 vcc, exec, s[10:11]
	s_cbranch_vccz .LBB0_289
	s_barrier

; #define PG8_STAGE(bufoff, gbase, voff) do { _Pragma("unroll") for (int _i = 0; _i < 2; ++_i) \
;         __builtin_amdgcn_global_load_lds((const unsigned*)((const char*)(gbase) + (voff)[_i]), (PG8_LAS unsigned*)(lds + (bufoff) + ldsw + _i * 8192), 16, 0, 0); } while (0)
; #define PG8_LDA(dst, b, h) do { _Pragma("unroll") for (int m = 0; m < 4; ++m) _Pragma("unroll") for (int k = 0; k < 2; ++k) dst[m][k] = *(const PG8_LAS bf16x8*)(lds + PG8_SA(b, h) + aoff + m * 2048 + k * 1024); } while (0)
; #define PG8_LDB(dst, b, h) do { _Pragma("unroll") for (int n = 0; n < 2; ++n) _Pragma("unroll") for (int k = 0; k < 2; ++k) dst[n][k] = *(const PG8_LAS bf16x8*)(lds + PG8_SB(b, h) + boff + n * 2048 + k * 1024); } while (0)
; #define PG8_MMA(ai, bj, At, Bt) do { __builtin_amdgcn_s_setprio(1); _Pragma("unroll") for (int m = 0; m < 4; ++m) _Pragma("unroll") for (int n = 0; n < 2; ++n) _Pragma("unroll") for (int k = 0; k < 2; ++k) \
;         acc[ai][bj][m][n] = __builtin_amdgcn_mfma_f32_16x16x32_bf16(Bt[n][k], At[m][k], acc[ai][bj][m][n], 0, 0, 0); __builtin_amdgcn_s_setprio(0); } while (0)
; #define PG8_BAR __builtin_amdgcn_s_barrier()
; template <class Epi, class Sched, bool ALIGN_EPI = false, bool SP2 = false>
; __device__ __forceinline__ void gemm_phase(PG8_LAS unsigned char* lds, const Gemm g, const Sched& S, const Epi& E, const int tid_in) {
;     ...
;             PG8_LDB(B0, 0, 0); PG8_LDB(B1, 0, 1); PG8_SCHED; PG8_LDA(At, 0, 0); PG8_STAGE(PG8_SA(1, 1), a1 + hstepA, voffA);
;             PG8_WAIT_V(8); PG8_WAIT_L(0); PG8_BAR; PG8_MMA(0, 0, At, B0); PG8_MMA(0, 1, At, B1); PG8_BAR; PG8_SCHED;
;             PG8_LDA(At, 0, 1); PG8_STAGE(PG8_SB(0, 0), b2, voffB); PG8_STAGE(PG8_SB(0, 1), b2 + hstepB, voffB); PG8_STAGE(PG8_SA(0, 0), a2, voffA);
;             PG8_WAIT_V(8); PG8_WAIT_L(0); PG8_BAR; PG8_MMA(1, 0, At, B0); PG8_MMA(1, 1, At, B1); PG8_BAR; PG8_SCHED;
;             PG8_LDB(B0, 1, 0); PG8_LDB(B1, 1, 1); PG8_SCHED; PG8_LDA(At, 1, 0); PG8_STAGE(PG8_SA(0, 1), a2 + hstepA, voffA);
;             PG8_WAIT_V(8); PG8_WAIT_L(0); PG8_BAR; PG8_MMA(0, 0, At, B0); PG8_MMA(0, 1, At, B1); PG8_BAR; PG8_SCHED;
;             PG8_LDA(At, 1, 1); PG8_STAGE(PG8_SB(1, 0), b3, voffB); PG8_STAGE(PG8_SB(1, 1), b3 + hstepB, voffB); PG8_STAGE(PG8_SA(1, 0), a3, voffA);
;             PG8_WAIT_V(8); PG8_WAIT_L(0); PG8_BAR; PG8_MMA(1, 0, At, B0); PG8_MMA(1, 1, At, B1); PG8_BAR; PG8_SCHED;
.LBB0_593:
	s_add_u32 s0, s22, 0x100
	s_addc_u32 s1, s23, 0
	s_add_i32 s53, 0, 0x10000
	s_cmp_eq_u32 s52, 4
	s_cselect_b32 s27, s19, s1
	s_cselect_b32 s26, s18, s0
	s_cselect_b32 s25, s17, s49
	s_cselect_b32 s24, s47, s48
	s_add_i32 s54, 0, 0x14000
	v_add_u32_e32 v136, s53, v182
	v_add_u32_e32 v170, s54, v182
	ds_read_b128 v[112:115], v136
	ds_read_b128 v[116:119], v136 offset:1024
	ds_read_b128 v[128:131], v136 offset:2048
	ds_read_b128 v[136:139], v136 offset:3072
	ds_read_b128 v[140:143], v170
	ds_read_b128 v[144:147], v170 offset:1024
	ds_read_b128 v[156:159], v170 offset:2048
	ds_read_b128 v[170:173], v170 offset:3072
	v_lshl_add_u64 v[196:197], s[22:23], 0, v[166:167]
	s_add_i32 m0, s35, 0xc000
	ds_read_b128 v[174:177], v183
	ds_read_b128 v[178:181], v183 offset:1024
	ds_read_b128 v[184:187], v183 offset:2048
	ds_read_b128 v[188:191], v183 offset:3072
	ds_read_b128 v[192:195], v183 offset:4096
	ds_read_b128 v[200:203], v183 offset:5120
	ds_read_b128 v[204:207], v183 offset:6144
	ds_read_b128 v[208:211], v183 offset:7168
	global_load_lds_dwordx4 v[196:197], off
	v_lshl_add_u64 v[196:197], s[22:23], 0, v[168:169]
	s_add_i32 m0, s35, 0xe000
	s_nop 0
	global_load_lds_dwordx4 v[196:197], off
	s_waitcnt vmcnt(8)
	s_waitcnt lgkmcnt(0)
	s_barrier
	s_setprio 1
	s_waitcnt lgkmcnt(0)
	v_mfma_f32_16x16x32_bf16 v[152:155], v[112:115], v[174:177], v[152:155]
	v_mfma_f32_16x16x32_bf16 v[148:151], v[128:131], v[174:177], v[148:151]
	v_mfma_f32_16x16x32_bf16 v[120:123], v[112:115], v[184:187], v[120:123]
	v_mfma_f32_16x16x32_bf16 v[108:111], v[128:131], v[184:187], v[108:111]
	v_mfma_f32_16x16x32_bf16 v[92:95], v[112:115], v[192:195], v[92:95]
	v_mfma_f32_16x16x32_bf16 v[88:91], v[128:131], v[192:195], v[88:91]
	v_mfma_f32_16x16x32_bf16 v[76:79], v[112:115], v[204:207], v[76:79]
	v_mfma_f32_16x16x32_bf16 v[72:75], v[128:131], v[204:207], v[72:75]
	v_mfma_f32_16x16x32_bf16 v[152:155], v[116:119], v[178:181], v[152:155]
	v_mfma_f32_16x16x32_bf16 v[148:151], v[136:139], v[178:181], v[148:151]
	v_mfma_f32_16x16x32_bf16 v[120:123], v[116:119], v[188:191], v[120:123]
	v_mfma_f32_16x16x32_bf16 v[108:111], v[136:139], v[188:191], v[108:111]
	v_mfma_f32_16x16x32_bf16 v[92:95], v[116:119], v[200:203], v[92:95]
	v_mfma_f32_16x16x32_bf16 v[88:91], v[136:139], v[200:203], v[88:91]
	v_mfma_f32_16x16x32_bf16 v[76:79], v[116:119], v[208:211], v[76:79]
	v_mfma_f32_16x16x32_bf16 v[72:75], v[136:139], v[208:211], v[72:75]
	v_mfma_f32_16x16x32_bf16 v[132:135], v[140:143], v[174:177], v[132:135]
	v_mfma_f32_16x16x32_bf16 v[124:127], v[156:159], v[174:177], v[124:127]
	v_mfma_f32_16x16x32_bf16 v[104:107], v[140:143], v[184:187], v[104:107]
	v_mfma_f32_16x16x32_bf16 v[100:103], v[156:159], v[184:187], v[100:103]
	v_mfma_f32_16x16x32_bf16 v[84:87], v[140:143], v[192:195], v[84:87]
	v_mfma_f32_16x16x32_bf16 v[80:83], v[156:159], v[192:195], v[80:83]
	v_mfma_f32_16x16x32_bf16 v[68:71], v[140:143], v[204:207], v[68:71]
	v_mfma_f32_16x16x32_bf16 v[64:67], v[156:159], v[204:207], v[64:67]
	v_mfma_f32_16x16x32_bf16 v[132:135], v[144:147], v[178:181], v[132:135]
	v_mfma_f32_16x16x32_bf16 v[124:127], v[170:173], v[178:181], v[124:127]
	v_mfma_f32_16x16x32_bf16 v[104:107], v[144:147], v[188:191], v[104:107]
	v_mfma_f32_16x16x32_bf16 v[100:103], v[170:173], v[188:191], v[100:103]
	v_mfma_f32_16x16x32_bf16 v[84:87], v[144:147], v[200:203], v[84:87]
	v_mfma_f32_16x16x32_bf16 v[80:83], v[170:173], v[200:203], v[80:83]
	v_mfma_f32_16x16x32_bf16 v[68:71], v[144:147], v[208:211], v[68:71]
	v_mfma_f32_16x16x32_bf16 v[64:67], v[170:173], v[208:211], v[64:67]
	s_setprio 0
	s_barrier
	s_add_i32 s22, s53, s34
	v_lshl_add_u64 v[196:197], s[24:25], 0, v[162:163]
	s_mov_b32 m0, s22
	ds_read_b128 v[174:177], v183 offset:16384
	ds_read_b128 v[178:181], v183 offset:17408
	ds_read_b128 v[184:187], v183 offset:18432
	ds_read_b128 v[188:191], v183 offset:19456
	ds_read_b128 v[192:195], v183 offset:20480
	ds_read_b128 v[200:203], v183 offset:21504
	ds_read_b128 v[204:207], v183 offset:22528
	ds_read_b128 v[208:211], v183 offset:23552
	global_load_lds_dwordx4 v[196:197], off
	s_add_i32 m0, s22, 0x2000
	s_add_u32 s22, s24, 0x20000
	v_lshl_add_u64 v[212:213], s[24:25], 0, v[96:97]
	s_addc_u32 s23, s25, 0
	s_add_i32 s53, s54, s34
	global_load_lds_dwordx4 v[212:213], off
	v_lshl_add_u64 v[214:215], s[22:23], 0, v[162:163]
	s_mov_b32 m0, s53
	v_lshl_add_u64 v[216:217], s[26:27], 0, v[160:161]
	global_load_lds_dwordx4 v[214:215], off
	v_lshl_add_u64 v[214:215], s[22:23], 0, v[96:97]
	s_add_i32 m0, s53, 0x2000
	s_nop 0
	global_load_lds_dwordx4 v[214:215], off
	v_lshl_add_u64 v[214:215], s[26:27], 0, v[164:165]
	s_mov_b32 m0, s35
	s_nop 0
	global_load_lds_dwordx4 v[214:215], off
	s_mov_b32 m0, s36
	s_nop 0
	global_load_lds_dwordx4 v[216:217], off
	s_waitcnt vmcnt(8)
	s_waitcnt lgkmcnt(0)
	s_barrier
; #define PG8_STAGE(bufoff, gbase, voff) do { _Pragma("unroll") for (int _i = 0; _i < 2; ++_i) \
;         __builtin_amdgcn_global_load_lds((const unsigned*)((const char*)(gbase) + (voff)[_i]), (PG8_LAS unsigned*)(lds + (bufoff) + ldsw + _i * 8192), 16, 0, 0); } while (0)
; #define PG8_LDA(dst, b, h) do { _Pragma("unroll") for (int m = 0; m < 4; ++m) _Pragma("unroll") for (int k = 0; k < 2; ++k) dst[m][k] = *(const PG8_LAS bf16x8*)(lds + PG8_SA(b, h) + aoff + m * 2048 + k * 1024); } while (0)
; #define PG8_LDB(dst, b, h) do { _Pragma("unroll") for (int n = 0; n < 2; ++n) _Pragma("unroll") for (int k = 0; k < 2; ++k) dst[n][k] = *(const PG8_LAS bf16x8*)(lds + PG8_SB(b, h) + boff + n * 2048 + k * 1024); } while (0)
; #define PG8_MMA(ai, bj, At, Bt) do { __builtin_amdgcn_s_setprio(1); _Pragma("unroll") for (int m = 0; m < 4; ++m) _Pragma("unroll") for (int n = 0; n < 2; ++n) _Pragma("unroll") for (int k = 0; k < 2; ++k) \
;         acc[ai][bj][m][n] = __builtin_amdgcn_mfma_f32_16x16x32_bf16(Bt[n][k], At[m][k], acc[ai][bj][m][n], 0, 0, 0); __builtin_amdgcn_s_setprio(0); } while (0)
; #define PG8_BAR __builtin_amdgcn_s_barrier()
; template <class Epi, class Sched, bool ALIGN_EPI = false, bool SP2 = false>
; __device__ __forceinline__ void gemm_phase(PG8_LAS unsigned char* lds, const Gemm g, const Sched& S, const Epi& E, const int tid_in) {
;     ...
;             PG8_LDB(B0, 0, 0); PG8_LDB(B1, 0, 1); PG8_SCHED; PG8_LDA(At, 0, 0); PG8_STAGE(PG8_SA(1, 1), a1 + hstepA, voffA);
;             PG8_WAIT_V(8); PG8_WAIT_L(0); PG8_BAR; PG8_MMA(0, 0, At, B0); PG8_MMA(0, 1, At, B1); PG8_BAR; PG8_SCHED;
;             PG8_LDA(At, 0, 1); PG8_STAGE(PG8_SB(0, 0), b2, voffB); PG8_STAGE(PG8_SB(0, 1), b2 + hstepB, voffB); PG8_STAGE(PG8_SA(0, 0), a2, voffA);
;             PG8_WAIT_V(8); PG8_WAIT_L(0); PG8_BAR; PG8_MMA(1, 0, At, B0); PG8_MMA(1, 1, At, B1); PG8_BAR; PG8_SCHED;
;             PG8_LDB(B0, 1, 0); PG8_LDB(B1, 1, 1); PG8_SCHED; PG8_LDA(At, 1, 0); PG8_STAGE(PG8_SA(0, 1), a2 + hstepA, voffA);
;             PG8_WAIT_V(8); PG8_WAIT_L(0); PG8_BAR; PG8_MMA(0, 0, At, B0); PG8_MMA(0, 1, At, B1); PG8_BAR; PG8_SCHED;
;             PG8_LDA(At, 1, 1); PG8_STAGE(PG8_SB(1, 0), b3, voffB); PG8_STAGE(PG8_SB(1, 1), b3 + hstepB, voffB); PG8_STAGE(PG8_SA(1, 0), a3, voffA);
;             PG8_WAIT_V(8); PG8_WAIT_L(0); PG8_BAR; PG8_MMA(1, 0, At, B0); PG8_MMA(1, 1, At, B1); PG8_BAR; PG8_SCHED;
	s_setprio 1
	s_waitcnt lgkmcnt(0)
	v_mfma_f32_16x16x32_bf16 v[60:63], v[112:115], v[174:177], v[60:63]
	v_mfma_f32_16x16x32_bf16 v[56:59], v[128:131], v[174:177], v[56:59]
	v_mfma_f32_16x16x32_bf16 v[44:47], v[112:115], v[184:187], v[44:47]
	v_mfma_f32_16x16x32_bf16 v[40:43], v[128:131], v[184:187], v[40:43]
	v_mfma_f32_16x16x32_bf16 v[28:31], v[112:115], v[192:195], v[28:31]
	v_mfma_f32_16x16x32_bf16 v[24:27], v[128:131], v[192:195], v[24:27]
	v_mfma_f32_16x16x32_bf16 v[12:15], v[112:115], v[204:207], v[12:15]
	v_mfma_f32_16x16x32_bf16 v[8:11], v[128:131], v[204:207], v[8:11]
	v_mfma_f32_16x16x32_bf16 v[60:63], v[116:119], v[178:181], v[60:63]
	v_mfma_f32_16x16x32_bf16 v[56:59], v[136:139], v[178:181], v[56:59]
	v_mfma_f32_16x16x32_bf16 v[44:47], v[116:119], v[188:191], v[44:47]
	v_mfma_f32_16x16x32_bf16 v[40:43], v[136:139], v[188:191], v[40:43]
	v_mfma_f32_16x16x32_bf16 v[28:31], v[116:119], v[200:203], v[28:31]
	v_mfma_f32_16x16x32_bf16 v[24:27], v[136:139], v[200:203], v[24:27]
	v_mfma_f32_16x16x32_bf16 v[12:15], v[116:119], v[208:211], v[12:15]
	v_mfma_f32_16x16x32_bf16 v[8:11], v[136:139], v[208:211], v[8:11]
	v_mfma_f32_16x16x32_bf16 v[52:55], v[140:143], v[174:177], v[52:55]
	v_mfma_f32_16x16x32_bf16 v[48:51], v[156:159], v[174:177], v[48:51]
	v_mfma_f32_16x16x32_bf16 v[36:39], v[140:143], v[184:187], v[36:39]
	v_mfma_f32_16x16x32_bf16 v[32:35], v[156:159], v[184:187], v[32:35]
	v_mfma_f32_16x16x32_bf16 v[20:23], v[140:143], v[192:195], v[20:23]
	v_mfma_f32_16x16x32_bf16 v[16:19], v[156:159], v[192:195], v[16:19]
	v_mfma_f32_16x16x32_bf16 v[4:7], v[140:143], v[204:207], v[4:7]
	v_mfma_f32_16x16x32_bf16 v[0:3], v[156:159], v[204:207], v[0:3]
	v_mfma_f32_16x16x32_bf16 v[52:55], v[144:147], v[178:181], v[52:55]
	v_mfma_f32_16x16x32_bf16 v[48:51], v[170:173], v[178:181], v[48:51]
	v_mfma_f32_16x16x32_bf16 v[36:39], v[144:147], v[188:191], v[36:39]
	v_mfma_f32_16x16x32_bf16 v[32:35], v[170:173], v[188:191], v[32:35]
	v_mfma_f32_16x16x32_bf16 v[20:23], v[144:147], v[200:203], v[20:23]
	v_mfma_f32_16x16x32_bf16 v[16:19], v[170:173], v[200:203], v[16:19]
	v_mfma_f32_16x16x32_bf16 v[4:7], v[144:147], v[208:211], v[4:7]
	v_mfma_f32_16x16x32_bf16 v[0:3], v[170:173], v[208:211], v[0:3]
	s_setprio 0
	s_barrier
	s_add_i32 s53, 0, 0x18000
	s_add_i32 s54, 0, 0x1c000
	v_add_u32_e32 v136, s53, v182
	v_add_u32_e32 v170, s54, v182
	ds_read_b128 v[112:115], v136
	ds_read_b128 v[116:119], v136 offset:1024
	ds_read_b128 v[128:131], v136 offset:2048
	ds_read_b128 v[136:139], v136 offset:3072
	ds_read_b128 v[140:143], v170
	ds_read_b128 v[144:147], v170 offset:1024
	ds_read_b128 v[156:159], v170 offset:2048
	ds_read_b128 v[170:173], v170 offset:3072
	s_add_u32 s22, s26, 0x120000
	s_addc_u32 s23, s27, 0
	s_mov_b32 m0, s37
	v_lshl_add_u64 v[218:219], s[22:23], 0, v[164:165]
	ds_read_b128 v[174:177], v183 offset:32768
	ds_read_b128 v[178:181], v183 offset:33792
	ds_read_b128 v[184:187], v183 offset:34816
	ds_read_b128 v[188:191], v183 offset:35840
	ds_read_b128 v[192:195], v183 offset:36864
	ds_read_b128 v[200:203], v183 offset:37888
	ds_read_b128 v[204:207], v183 offset:38912
	ds_read_b128 v[208:211], v183 offset:39936
	global_load_lds_dwordx4 v[218:219], off
	v_lshl_add_u64 v[218:219], s[22:23], 0, v[160:161]
	s_mov_b32 m0, s38
	s_nop 0
	global_load_lds_dwordx4 v[218:219], off
	s_waitcnt vmcnt(8)
	s_waitcnt lgkmcnt(0)
	s_barrier
	s_setprio 1
	s_waitcnt lgkmcnt(0)
	v_mfma_f32_16x16x32_bf16 v[152:155], v[112:115], v[174:177], v[152:155]
	v_mfma_f32_16x16x32_bf16 v[148:151], v[128:131], v[174:177], v[148:151]
	v_mfma_f32_16x16x32_bf16 v[120:123], v[112:115], v[184:187], v[120:123]
	v_mfma_f32_16x16x32_bf16 v[108:111], v[128:131], v[184:187], v[108:111]
	v_mfma_f32_16x16x32_bf16 v[92:95], v[112:115], v[192:195], v[92:95]
	v_mfma_f32_16x16x32_bf16 v[88:91], v[128:131], v[192:195], v[88:91]
	v_mfma_f32_16x16x32_bf16 v[76:79], v[112:115], v[204:207], v[76:79]
	v_mfma_f32_16x16x32_bf16 v[72:75], v[128:131], v[204:207], v[72:75]
	v_mfma_f32_16x16x32_bf16 v[152:155], v[116:119], v[178:181], v[152:155]
	v_mfma_f32_16x16x32_bf16 v[148:151], v[136:139], v[178:181], v[148:151]
	v_mfma_f32_16x16x32_bf16 v[120:123], v[116:119], v[188:191], v[120:123]
	v_mfma_f32_16x16x32_bf16 v[108:111], v[136:139], v[188:191], v[108:111]
	v_mfma_f32_16x16x32_bf16 v[92:95], v[116:119], v[200:203], v[92:95]
	v_mfma_f32_16x16x32_bf16 v[88:91], v[136:139], v[200:203], v[88:91]
	v_mfma_f32_16x16x32_bf16 v[76:79], v[116:119], v[208:211], v[76:79]
	v_mfma_f32_16x16x32_bf16 v[72:75], v[136:139], v[208:211], v[72:75]
	v_mfma_f32_16x16x32_bf16 v[132:135], v[140:143], v[174:177], v[132:135]
	v_mfma_f32_16x16x32_bf16 v[124:127], v[156:159], v[174:177], v[124:127]
	v_mfma_f32_16x16x32_bf16 v[104:107], v[140:143], v[184:187], v[104:107]
	v_mfma_f32_16x16x32_bf16 v[100:103], v[156:159], v[184:187], v[100:103]
	v_mfma_f32_16x16x32_bf16 v[84:87], v[140:143], v[192:195], v[84:87]
	v_mfma_f32_16x16x32_bf16 v[80:83], v[156:159], v[192:195], v[80:83]
	v_mfma_f32_16x16x32_bf16 v[68:71], v[140:143], v[204:207], v[68:71]
	v_mfma_f32_16x16x32_bf16 v[64:67], v[156:159], v[204:207], v[64:67]
	v_mfma_f32_16x16x32_bf16 v[132:135], v[144:147], v[178:181], v[132:135]
	v_mfma_f32_16x16x32_bf16 v[124:127], v[170:173], v[178:181], v[124:127]
	v_mfma_f32_16x16x32_bf16 v[104:107], v[144:147], v[188:191], v[104:107]
	v_mfma_f32_16x16x32_bf16 v[100:103], v[170:173], v[188:191], v[100:103]
	v_mfma_f32_16x16x32_bf16 v[84:87], v[144:147], v[200:203], v[84:87]
	v_mfma_f32_16x16x32_bf16 v[80:83], v[170:173], v[200:203], v[80:83]
	v_mfma_f32_16x16x32_bf16 v[68:71], v[144:147], v[208:211], v[68:71]
	v_mfma_f32_16x16x32_bf16 v[64:67], v[170:173], v[208:211], v[64:67]
	s_setprio 0
	s_barrier
; #define PG8_STAGE(bufoff, gbase, voff) do { _Pragma("unroll") for (int _i = 0; _i < 2; ++_i) \
;         __builtin_amdgcn_global_load_lds((const unsigned*)((const char*)(gbase) + (voff)[_i]), (PG8_LAS unsigned*)(lds + (bufoff) + ldsw + _i * 8192), 16, 0, 0); } while (0)
; #define PG8_LDA(dst, b, h) do { _Pragma("unroll") for (int m = 0; m < 4; ++m) _Pragma("unroll") for (int k = 0; k < 2; ++k) dst[m][k] = *(const PG8_LAS bf16x8*)(lds + PG8_SA(b, h) + aoff + m * 2048 + k * 1024); } while (0)
; #define PG8_LDB(dst, b, h) do { _Pragma("unroll") for (int n = 0; n < 2; ++n) _Pragma("unroll") for (int k = 0; k < 2; ++k) dst[n][k] = *(const PG8_LAS bf16x8*)(lds + PG8_SB(b, h) + boff + n * 2048 + k * 1024); } while (0)
; #define PG8_MMA(ai, bj, At, Bt) do { __builtin_amdgcn_s_setprio(1); _Pragma("unroll") for (int m = 0; m < 4; ++m) _Pragma("unroll") for (int n = 0; n < 2; ++n) _Pragma("unroll") for (int k = 0; k < 2; ++k) \
;         acc[ai][bj][m][n] = __builtin_amdgcn_mfma_f32_16x16x32_bf16(Bt[n][k], At[m][k], acc[ai][bj][m][n], 0, 0, 0); __builtin_amdgcn_s_setprio(0); } while (0)
; #define PG8_BAR __builtin_amdgcn_s_barrier()
; template <class Epi, class Sched, bool ALIGN_EPI = false, bool SP2 = false>
; __device__ __forceinline__ void gemm_phase(PG8_LAS unsigned char* lds, const Gemm g, const Sched& S, const Epi& E, const int tid_in) {
;     ...
;             PG8_LDB(B0, 0, 0); PG8_LDB(B1, 0, 1); PG8_SCHED; PG8_LDA(At, 0, 0); PG8_STAGE(PG8_SA(1, 1), a1 + hstepA, voffA);
;             PG8_WAIT_V(8); PG8_WAIT_L(0); PG8_BAR; PG8_MMA(0, 0, At, B0); PG8_MMA(0, 1, At, B1); PG8_BAR; PG8_SCHED;
;             PG8_LDA(At, 0, 1); PG8_STAGE(PG8_SB(0, 0), b2, voffB); PG8_STAGE(PG8_SB(0, 1), b2 + hstepB, voffB); PG8_STAGE(PG8_SA(0, 0), a2, voffA);
;             PG8_WAIT_V(8); PG8_WAIT_L(0); PG8_BAR; PG8_MMA(1, 0, At, B0); PG8_MMA(1, 1, At, B1); PG8_BAR; PG8_SCHED;
;             PG8_LDB(B0, 1, 0); PG8_LDB(B1, 1, 1); PG8_SCHED; PG8_LDA(At, 1, 0); PG8_STAGE(PG8_SA(0, 1), a2 + hstepA, voffA);
;             PG8_WAIT_V(8); PG8_WAIT_L(0); PG8_BAR; PG8_MMA(0, 0, At, B0); PG8_MMA(0, 1, At, B1); PG8_BAR; PG8_SCHED;
;             PG8_LDA(At, 1, 1); PG8_STAGE(PG8_SB(1, 0), b3, voffB); PG8_STAGE(PG8_SB(1, 1), b3 + hstepB, voffB); PG8_STAGE(PG8_SA(1, 0), a3, voffA);
;             PG8_WAIT_V(8); PG8_WAIT_L(0); PG8_BAR; PG8_MMA(1, 0, At, B0); PG8_MMA(1, 1, At, B1); PG8_BAR; PG8_SCHED;
	s_add_i32 s22, s53, s34
	v_lshl_add_u64 v[196:197], v[196:197], 0, s[50:51]
	s_mov_b32 m0, s22
	ds_read_b128 v[174:177], v183 offset:49152
	ds_read_b128 v[178:181], v183 offset:50176
	ds_read_b128 v[184:187], v183 offset:51200
	ds_read_b128 v[188:191], v183 offset:52224
	ds_read_b128 v[192:195], v183 offset:53248
	ds_read_b128 v[200:203], v183 offset:54272
	ds_read_b128 v[204:207], v183 offset:55296
	ds_read_b128 v[208:211], v183 offset:56320
	global_load_lds_dwordx4 v[196:197], off
	s_add_i32 m0, s22, 0x2000
	s_add_u32 s22, s24, 0x20080
	v_lshl_add_u64 v[196:197], v[212:213], 0, s[50:51]
	s_addc_u32 s23, s25, 0
	s_add_i32 s24, s54, s34
	global_load_lds_dwordx4 v[196:197], off
	v_lshl_add_u64 v[196:197], s[22:23], 0, v[162:163]
	s_mov_b32 m0, s24
	s_nop 0
	global_load_lds_dwordx4 v[196:197], off
	v_lshl_add_u64 v[196:197], s[22:23], 0, v[96:97]
	s_add_i32 m0, s24, 0x2000
	s_nop 0
	global_load_lds_dwordx4 v[196:197], off
	v_lshl_add_u64 v[196:197], v[214:215], 0, s[50:51]
	s_mov_b32 m0, s41
	s_nop 0
	global_load_lds_dwordx4 v[196:197], off
	v_lshl_add_u64 v[196:197], v[216:217], 0, s[50:51]
	s_mov_b32 m0, s42
	s_nop 0
	global_load_lds_dwordx4 v[196:197], off
	s_waitcnt vmcnt(8)
	s_waitcnt lgkmcnt(0)
	s_barrier
	s_setprio 1
	s_waitcnt lgkmcnt(0)
	v_mfma_f32_16x16x32_bf16 v[60:63], v[112:115], v[174:177], v[60:63]
	v_mfma_f32_16x16x32_bf16 v[56:59], v[128:131], v[174:177], v[56:59]
	v_mfma_f32_16x16x32_bf16 v[44:47], v[112:115], v[184:187], v[44:47]
	v_mfma_f32_16x16x32_bf16 v[40:43], v[128:131], v[184:187], v[40:43]
	v_mfma_f32_16x16x32_bf16 v[28:31], v[112:115], v[192:195], v[28:31]
	v_mfma_f32_16x16x32_bf16 v[24:27], v[128:131], v[192:195], v[24:27]
	v_mfma_f32_16x16x32_bf16 v[12:15], v[112:115], v[204:207], v[12:15]
	v_mfma_f32_16x16x32_bf16 v[8:11], v[128:131], v[204:207], v[8:11]
	v_mfma_f32_16x16x32_bf16 v[60:63], v[116:119], v[178:181], v[60:63]
	v_mfma_f32_16x16x32_bf16 v[56:59], v[136:139], v[178:181], v[56:59]
	v_mfma_f32_16x16x32_bf16 v[44:47], v[116:119], v[188:191], v[44:47]
	v_mfma_f32_16x16x32_bf16 v[40:43], v[136:139], v[188:191], v[40:43]
	v_mfma_f32_16x16x32_bf16 v[28:31], v[116:119], v[200:203], v[28:31]
	v_mfma_f32_16x16x32_bf16 v[24:27], v[136:139], v[200:203], v[24:27]
	v_mfma_f32_16x16x32_bf16 v[12:15], v[116:119], v[208:211], v[12:15]
	v_mfma_f32_16x16x32_bf16 v[8:11], v[136:139], v[208:211], v[8:11]
	v_mfma_f32_16x16x32_bf16 v[52:55], v[140:143], v[174:177], v[52:55]
	v_mfma_f32_16x16x32_bf16 v[48:51], v[156:159], v[174:177], v[48:51]
	v_mfma_f32_16x16x32_bf16 v[36:39], v[140:143], v[184:187], v[36:39]
	v_mfma_f32_16x16x32_bf16 v[32:35], v[156:159], v[184:187], v[32:35]
	v_mfma_f32_16x16x32_bf16 v[20:23], v[140:143], v[192:195], v[20:23]
	v_mfma_f32_16x16x32_bf16 v[16:19], v[156:159], v[192:195], v[16:19]
	v_mfma_f32_16x16x32_bf16 v[4:7], v[140:143], v[204:207], v[4:7]
	v_mfma_f32_16x16x32_bf16 v[0:3], v[156:159], v[204:207], v[0:3]
	v_mfma_f32_16x16x32_bf16 v[52:55], v[144:147], v[178:181], v[52:55]
	v_mfma_f32_16x16x32_bf16 v[48:51], v[170:173], v[178:181], v[48:51]
	v_mfma_f32_16x16x32_bf16 v[36:39], v[144:147], v[188:191], v[36:39]
	v_mfma_f32_16x16x32_bf16 v[32:35], v[170:173], v[188:191], v[32:35]
	v_mfma_f32_16x16x32_bf16 v[20:23], v[144:147], v[200:203], v[20:23]
	v_mfma_f32_16x16x32_bf16 v[16:19], v[170:173], v[200:203], v[16:19]
	v_mfma_f32_16x16x32_bf16 v[4:7], v[144:147], v[208:211], v[4:7]
	v_mfma_f32_16x16x32_bf16 v[0:3], v[170:173], v[208:211], v[0:3]
	s_setprio 0
	s_barrier
	s_add_i32 s52, s52, 2
	s_add_u32 s48, s48, 0x100
	s_addc_u32 s49, s49, 0
	s_cmp_gt_u32 s52, 5
	s_mov_b64 s[22:23], s[0:1]
	s_cbranch_scc0 .LBB0_593
	s_and_b64 vcc, exec, s[14:15]
	s_cbranch_vccz .LBB0_596
	s_barrier

; #define PG8_STAGE(bufoff, gbase, voff) do { _Pragma("unroll") for (int _i = 0; _i < 2; ++_i) \
;         __builtin_amdgcn_global_load_lds((const unsigned*)((const char*)(gbase) + (voff)[_i]), (PG8_LAS unsigned*)(lds + (bufoff) + ldsw + _i * 8192), 16, 0, 0); } while (0)
; #define PG8_LDA(dst, b, h) do { _Pragma("unroll") for (int m = 0; m < 4; ++m) _Pragma("unroll") for (int k = 0; k < 2; ++k) dst[m][k] = *(const PG8_LAS bf16x8*)(lds + PG8_SA(b, h) + aoff + m * 2048 + k * 1024); } while (0)
; #define PG8_LDB(dst, b, h) do { _Pragma("unroll") for (int n = 0; n < 2; ++n) _Pragma("unroll") for (int k = 0; k < 2; ++k) dst[n][k] = *(const PG8_LAS bf16x8*)(lds + PG8_SB(b, h) + boff + n * 2048 + k * 1024); } while (0)
; #define PG8_MMA(ai, bj, At, Bt) do { __builtin_amdgcn_s_setprio(1); _Pragma("unroll") for (int m = 0; m < 4; ++m) _Pragma("unroll") for (int n = 0; n < 2; ++n) _Pragma("unroll") for (int k = 0; k < 2; ++k) \
;         acc[ai][bj][m][n] = __builtin_amdgcn_mfma_f32_16x16x32_bf16(Bt[n][k], At[m][k], acc[ai][bj][m][n], 0, 0, 0); __builtin_amdgcn_s_setprio(0); } while (0)
; #define PG8_BAR __builtin_amdgcn_s_barrier()
; template <class Epi, class Sched, bool ALIGN_EPI = false, bool SP2 = false>
; __device__ __forceinline__ void gemm_phase(PG8_LAS unsigned char* lds, const Gemm g, const Sched& S, const Epi& E, const int tid_in) {
;     ...
;             PG8_LDB(B0, 0, 0); PG8_LDB(B1, 0, 1); PG8_SCHED; PG8_LDA(At, 0, 0); PG8_STAGE(PG8_SA(1, 1), a1 + hstepA, voffA);
;             PG8_WAIT_V(8); PG8_WAIT_L(0); PG8_BAR; PG8_MMA(0, 0, At, B0); PG8_MMA(0, 1, At, B1); PG8_BAR; PG8_SCHED;
;             PG8_LDA(At, 0, 1); PG8_STAGE(PG8_SB(0, 0), b2, voffB); PG8_STAGE(PG8_SB(0, 1), b2 + hstepB, voffB); PG8_STAGE(PG8_SA(0, 0), a2, voffA);
;             PG8_WAIT_V(8); PG8_WAIT_L(0); PG8_BAR; PG8_MMA(1, 0, At, B0); PG8_MMA(1, 1, At, B1); PG8_BAR; PG8_SCHED;
;             PG8_LDB(B0, 1, 0); PG8_LDB(B1, 1, 1); PG8_SCHED; PG8_LDA(At, 1, 0); PG8_STAGE(PG8_SA(0, 1), a2 + hstepA, voffA);
;             PG8_WAIT_V(8); PG8_WAIT_L(0); PG8_BAR; PG8_MMA(0, 0, At, B0); PG8_MMA(0, 1, At, B1); PG8_BAR; PG8_SCHED;
;             PG8_LDA(At, 1, 1); PG8_STAGE(PG8_SB(1, 0), b3, voffB); PG8_STAGE(PG8_SB(1, 1), b3 + hstepB, voffB); PG8_STAGE(PG8_SA(1, 0), a3, voffA);
;             PG8_WAIT_V(8); PG8_WAIT_L(0); PG8_BAR; PG8_MMA(1, 0, At, B0); PG8_MMA(1, 1, At, B1); PG8_BAR; PG8_SCHED;
.LBB0_615:
	s_add_u32 s0, s20, 0x100
	s_addc_u32 s1, s21, 0
	s_add_i32 s49, 0, 0x10000
	s_cmp_eq_u32 s48, 4
	s_cselect_b32 s25, s17, s1
	s_cselect_b32 s24, s16, s0
	s_cselect_b32 s23, s15, s47
	s_cselect_b32 s22, s45, s46
	s_add_i32 s52, 0, 0x14000
	v_add_u32_e32 v136, s49, v237
	v_add_u32_e32 v156, s52, v237
	ds_read_b128 v[120:123], v136
	ds_read_b128 v[124:127], v136 offset:1024
	ds_read_b128 v[132:135], v136 offset:2048
	ds_read_b128 v[136:139], v136 offset:3072
	ds_read_b128 v[140:143], v156
	ds_read_b128 v[144:147], v156 offset:1024
	ds_read_b128 v[152:155], v156 offset:2048
	ds_read_b128 v[156:159], v156 offset:3072
	v_lshl_add_u64 v[196:197], s[20:21], 0, v[206:207]
	s_add_i32 m0, s31, 0xc000
	ds_read_b128 v[164:167], v238
	ds_read_b128 v[168:171], v238 offset:1024
	ds_read_b128 v[172:175], v238 offset:2048
	ds_read_b128 v[176:179], v238 offset:3072
	ds_read_b128 v[180:183], v238 offset:4096
	ds_read_b128 v[184:187], v238 offset:5120
	ds_read_b128 v[188:191], v238 offset:6144
	ds_read_b128 v[192:195], v238 offset:7168
	global_load_lds_dwordx4 v[196:197], off
	v_lshl_add_u64 v[196:197], s[20:21], 0, v[208:209]
	s_add_i32 m0, s31, 0xe000
	s_nop 0
	global_load_lds_dwordx4 v[196:197], off
	s_waitcnt vmcnt(8)
	s_waitcnt lgkmcnt(0)
	s_barrier
	s_setprio 1
	s_waitcnt lgkmcnt(0)
	v_mfma_f32_16x16x32_bf16 v[160:163], v[120:123], v[164:167], v[160:163]
	v_mfma_f32_16x16x32_bf16 v[148:151], v[132:135], v[164:167], v[148:151]
	v_mfma_f32_16x16x32_bf16 v[112:115], v[120:123], v[172:175], v[112:115]
	v_mfma_f32_16x16x32_bf16 v[108:111], v[132:135], v[172:175], v[108:111]
	v_mfma_f32_16x16x32_bf16 v[92:95], v[120:123], v[180:183], v[92:95]
	v_mfma_f32_16x16x32_bf16 v[88:91], v[132:135], v[180:183], v[88:91]
	v_mfma_f32_16x16x32_bf16 v[76:79], v[120:123], v[188:191], v[76:79]
	v_mfma_f32_16x16x32_bf16 v[72:75], v[132:135], v[188:191], v[72:75]
	v_mfma_f32_16x16x32_bf16 v[160:163], v[124:127], v[168:171], v[160:163]
	v_mfma_f32_16x16x32_bf16 v[148:151], v[136:139], v[168:171], v[148:151]
	v_mfma_f32_16x16x32_bf16 v[112:115], v[124:127], v[176:179], v[112:115]
	v_mfma_f32_16x16x32_bf16 v[108:111], v[136:139], v[176:179], v[108:111]
	v_mfma_f32_16x16x32_bf16 v[92:95], v[124:127], v[184:187], v[92:95]
	v_mfma_f32_16x16x32_bf16 v[88:91], v[136:139], v[184:187], v[88:91]
	v_mfma_f32_16x16x32_bf16 v[76:79], v[124:127], v[192:195], v[76:79]
	v_mfma_f32_16x16x32_bf16 v[72:75], v[136:139], v[192:195], v[72:75]
	v_mfma_f32_16x16x32_bf16 v[128:131], v[140:143], v[164:167], v[128:131]
	v_mfma_f32_16x16x32_bf16 v[116:119], v[152:155], v[164:167], v[116:119]
	v_mfma_f32_16x16x32_bf16 v[104:107], v[140:143], v[172:175], v[104:107]
	v_mfma_f32_16x16x32_bf16 v[100:103], v[152:155], v[172:175], v[100:103]
	v_mfma_f32_16x16x32_bf16 v[84:87], v[140:143], v[180:183], v[84:87]
	v_mfma_f32_16x16x32_bf16 v[80:83], v[152:155], v[180:183], v[80:83]
	v_mfma_f32_16x16x32_bf16 v[68:71], v[140:143], v[188:191], v[68:71]
	v_mfma_f32_16x16x32_bf16 v[64:67], v[152:155], v[188:191], v[64:67]
	v_mfma_f32_16x16x32_bf16 v[128:131], v[144:147], v[168:171], v[128:131]
	v_mfma_f32_16x16x32_bf16 v[116:119], v[156:159], v[168:171], v[116:119]
	v_mfma_f32_16x16x32_bf16 v[104:107], v[144:147], v[176:179], v[104:107]
	v_mfma_f32_16x16x32_bf16 v[100:103], v[156:159], v[176:179], v[100:103]
	v_mfma_f32_16x16x32_bf16 v[84:87], v[144:147], v[184:187], v[84:87]
	v_mfma_f32_16x16x32_bf16 v[80:83], v[156:159], v[184:187], v[80:83]
	v_mfma_f32_16x16x32_bf16 v[68:71], v[144:147], v[192:195], v[68:71]
	v_mfma_f32_16x16x32_bf16 v[64:67], v[156:159], v[192:195], v[64:67]
	s_setprio 0
	s_barrier
	s_add_i32 s20, s49, s30
	v_lshl_add_u64 v[196:197], s[22:23], 0, v[202:203]
	s_mov_b32 m0, s20
	ds_read_b128 v[164:167], v238 offset:16384
	ds_read_b128 v[168:171], v238 offset:17408
	ds_read_b128 v[172:175], v238 offset:18432
	ds_read_b128 v[176:179], v238 offset:19456
	ds_read_b128 v[180:183], v238 offset:20480
	ds_read_b128 v[184:187], v238 offset:21504
	ds_read_b128 v[188:191], v238 offset:22528
	ds_read_b128 v[192:195], v238 offset:23552
	global_load_lds_dwordx4 v[196:197], off
	s_add_i32 m0, s20, 0x2000
	s_add_u32 s20, s22, 0x20000
	v_lshl_add_u64 v[210:211], s[22:23], 0, v[96:97]
	s_addc_u32 s21, s23, 0
	s_add_i32 s49, s52, s30
	global_load_lds_dwordx4 v[210:211], off
	v_lshl_add_u64 v[212:213], s[20:21], 0, v[202:203]
	s_mov_b32 m0, s49
	v_lshl_add_u64 v[214:215], s[24:25], 0, v[200:201]
	global_load_lds_dwordx4 v[212:213], off
	v_lshl_add_u64 v[212:213], s[20:21], 0, v[96:97]
	s_add_i32 m0, s49, 0x2000
	s_nop 0
	global_load_lds_dwordx4 v[212:213], off
	v_lshl_add_u64 v[212:213], s[24:25], 0, v[204:205]
	s_mov_b32 m0, s31
	s_nop 0
	global_load_lds_dwordx4 v[212:213], off
	s_mov_b32 m0, s34
	s_nop 0
	global_load_lds_dwordx4 v[214:215], off
	s_waitcnt vmcnt(8)
	s_waitcnt lgkmcnt(0)
	s_barrier
; #define PG8_STAGE(bufoff, gbase, voff) do { _Pragma("unroll") for (int _i = 0; _i < 2; ++_i) \
;         __builtin_amdgcn_global_load_lds((const unsigned*)((const char*)(gbase) + (voff)[_i]), (PG8_LAS unsigned*)(lds + (bufoff) + ldsw + _i * 8192), 16, 0, 0); } while (0)
; #define PG8_LDA(dst, b, h) do { _Pragma("unroll") for (int m = 0; m < 4; ++m) _Pragma("unroll") for (int k = 0; k < 2; ++k) dst[m][k] = *(const PG8_LAS bf16x8*)(lds + PG8_SA(b, h) + aoff + m * 2048 + k * 1024); } while (0)
; #define PG8_LDB(dst, b, h) do { _Pragma("unroll") for (int n = 0; n < 2; ++n) _Pragma("unroll") for (int k = 0; k < 2; ++k) dst[n][k] = *(const PG8_LAS bf16x8*)(lds + PG8_SB(b, h) + boff + n * 2048 + k * 1024); } while (0)
; #define PG8_MMA(ai, bj, At, Bt) do { __builtin_amdgcn_s_setprio(1); _Pragma("unroll") for (int m = 0; m < 4; ++m) _Pragma("unroll") for (int n = 0; n < 2; ++n) _Pragma("unroll") for (int k = 0; k < 2; ++k) \
;         acc[ai][bj][m][n] = __builtin_amdgcn_mfma_f32_16x16x32_bf16(Bt[n][k], At[m][k], acc[ai][bj][m][n], 0, 0, 0); __builtin_amdgcn_s_setprio(0); } while (0)
; #define PG8_BAR __builtin_amdgcn_s_barrier()
; template <class Epi, class Sched, bool ALIGN_EPI = false, bool SP2 = false>
; __device__ __forceinline__ void gemm_phase(PG8_LAS unsigned char* lds, const Gemm g, const Sched& S, const Epi& E, const int tid_in) {
;     ...
;             PG8_LDB(B0, 0, 0); PG8_LDB(B1, 0, 1); PG8_SCHED; PG8_LDA(At, 0, 0); PG8_STAGE(PG8_SA(1, 1), a1 + hstepA, voffA);
;             PG8_WAIT_V(8); PG8_WAIT_L(0); PG8_BAR; PG8_MMA(0, 0, At, B0); PG8_MMA(0, 1, At, B1); PG8_BAR; PG8_SCHED;
;             PG8_LDA(At, 0, 1); PG8_STAGE(PG8_SB(0, 0), b2, voffB); PG8_STAGE(PG8_SB(0, 1), b2 + hstepB, voffB); PG8_STAGE(PG8_SA(0, 0), a2, voffA);
;             PG8_WAIT_V(8); PG8_WAIT_L(0); PG8_BAR; PG8_MMA(1, 0, At, B0); PG8_MMA(1, 1, At, B1); PG8_BAR; PG8_SCHED;
;             PG8_LDB(B0, 1, 0); PG8_LDB(B1, 1, 1); PG8_SCHED; PG8_LDA(At, 1, 0); PG8_STAGE(PG8_SA(0, 1), a2 + hstepA, voffA);
;             PG8_WAIT_V(8); PG8_WAIT_L(0); PG8_BAR; PG8_MMA(0, 0, At, B0); PG8_MMA(0, 1, At, B1); PG8_BAR; PG8_SCHED;
;             PG8_LDA(At, 1, 1); PG8_STAGE(PG8_SB(1, 0), b3, voffB); PG8_STAGE(PG8_SB(1, 1), b3 + hstepB, voffB); PG8_STAGE(PG8_SA(1, 0), a3, voffA);
;             PG8_WAIT_V(8); PG8_WAIT_L(0); PG8_BAR; PG8_MMA(1, 0, At, B0); PG8_MMA(1, 1, At, B1); PG8_BAR; PG8_SCHED;
	s_setprio 1
	s_waitcnt lgkmcnt(0)
	v_mfma_f32_16x16x32_bf16 v[60:63], v[120:123], v[164:167], v[60:63]
	v_mfma_f32_16x16x32_bf16 v[56:59], v[132:135], v[164:167], v[56:59]
	v_mfma_f32_16x16x32_bf16 v[44:47], v[120:123], v[172:175], v[44:47]
	v_mfma_f32_16x16x32_bf16 v[40:43], v[132:135], v[172:175], v[40:43]
	v_mfma_f32_16x16x32_bf16 v[28:31], v[120:123], v[180:183], v[28:31]
	v_mfma_f32_16x16x32_bf16 v[24:27], v[132:135], v[180:183], v[24:27]
	v_mfma_f32_16x16x32_bf16 v[12:15], v[120:123], v[188:191], v[12:15]
	v_mfma_f32_16x16x32_bf16 v[8:11], v[132:135], v[188:191], v[8:11]
	v_mfma_f32_16x16x32_bf16 v[60:63], v[124:127], v[168:171], v[60:63]
	v_mfma_f32_16x16x32_bf16 v[56:59], v[136:139], v[168:171], v[56:59]
	v_mfma_f32_16x16x32_bf16 v[44:47], v[124:127], v[176:179], v[44:47]
	v_mfma_f32_16x16x32_bf16 v[40:43], v[136:139], v[176:179], v[40:43]
	v_mfma_f32_16x16x32_bf16 v[28:31], v[124:127], v[184:187], v[28:31]
	v_mfma_f32_16x16x32_bf16 v[24:27], v[136:139], v[184:187], v[24:27]
	v_mfma_f32_16x16x32_bf16 v[12:15], v[124:127], v[192:195], v[12:15]
	v_mfma_f32_16x16x32_bf16 v[8:11], v[136:139], v[192:195], v[8:11]
	v_mfma_f32_16x16x32_bf16 v[52:55], v[140:143], v[164:167], v[52:55]
	v_mfma_f32_16x16x32_bf16 v[48:51], v[152:155], v[164:167], v[48:51]
	v_mfma_f32_16x16x32_bf16 v[36:39], v[140:143], v[172:175], v[36:39]
	v_mfma_f32_16x16x32_bf16 v[32:35], v[152:155], v[172:175], v[32:35]
	v_mfma_f32_16x16x32_bf16 v[20:23], v[140:143], v[180:183], v[20:23]
	v_mfma_f32_16x16x32_bf16 v[16:19], v[152:155], v[180:183], v[16:19]
	v_mfma_f32_16x16x32_bf16 v[4:7], v[140:143], v[188:191], v[4:7]
	v_mfma_f32_16x16x32_bf16 v[0:3], v[152:155], v[188:191], v[0:3]
	v_mfma_f32_16x16x32_bf16 v[52:55], v[144:147], v[168:171], v[52:55]
	v_mfma_f32_16x16x32_bf16 v[48:51], v[156:159], v[168:171], v[48:51]
	v_mfma_f32_16x16x32_bf16 v[36:39], v[144:147], v[176:179], v[36:39]
	v_mfma_f32_16x16x32_bf16 v[32:35], v[156:159], v[176:179], v[32:35]
	v_mfma_f32_16x16x32_bf16 v[20:23], v[144:147], v[184:187], v[20:23]
	v_mfma_f32_16x16x32_bf16 v[16:19], v[156:159], v[184:187], v[16:19]
	v_mfma_f32_16x16x32_bf16 v[4:7], v[144:147], v[192:195], v[4:7]
	v_mfma_f32_16x16x32_bf16 v[0:3], v[156:159], v[192:195], v[0:3]
	s_setprio 0
	s_barrier
	s_add_i32 s49, 0, 0x18000
	s_add_i32 s52, 0, 0x1c000
	v_add_u32_e32 v136, s49, v237
	v_add_u32_e32 v156, s52, v237
	ds_read_b128 v[120:123], v136
	ds_read_b128 v[124:127], v136 offset:1024
	ds_read_b128 v[132:135], v136 offset:2048
	ds_read_b128 v[136:139], v136 offset:3072
	ds_read_b128 v[140:143], v156
	ds_read_b128 v[144:147], v156 offset:1024
	ds_read_b128 v[152:155], v156 offset:2048
	ds_read_b128 v[156:159], v156 offset:3072
	s_add_u32 s20, s24, 0x120000
	s_addc_u32 s21, s25, 0
	s_mov_b32 m0, s35
	v_lshl_add_u64 v[216:217], s[20:21], 0, v[204:205]
	ds_read_b128 v[164:167], v238 offset:32768
	ds_read_b128 v[168:171], v238 offset:33792
	ds_read_b128 v[172:175], v238 offset:34816
	ds_read_b128 v[176:179], v238 offset:35840
	ds_read_b128 v[180:183], v238 offset:36864
	ds_read_b128 v[184:187], v238 offset:37888
	ds_read_b128 v[188:191], v238 offset:38912
	ds_read_b128 v[192:195], v238 offset:39936
	global_load_lds_dwordx4 v[216:217], off
	v_lshl_add_u64 v[216:217], s[20:21], 0, v[200:201]
	s_mov_b32 m0, s36
	s_nop 0
	global_load_lds_dwordx4 v[216:217], off
	s_waitcnt vmcnt(8)
	s_waitcnt lgkmcnt(0)
	s_barrier
	s_setprio 1
	s_waitcnt lgkmcnt(0)
	v_mfma_f32_16x16x32_bf16 v[160:163], v[120:123], v[164:167], v[160:163]
	v_mfma_f32_16x16x32_bf16 v[148:151], v[132:135], v[164:167], v[148:151]
	v_mfma_f32_16x16x32_bf16 v[112:115], v[120:123], v[172:175], v[112:115]
	v_mfma_f32_16x16x32_bf16 v[108:111], v[132:135], v[172:175], v[108:111]
	v_mfma_f32_16x16x32_bf16 v[92:95], v[120:123], v[180:183], v[92:95]
	v_mfma_f32_16x16x32_bf16 v[88:91], v[132:135], v[180:183], v[88:91]
	v_mfma_f32_16x16x32_bf16 v[76:79], v[120:123], v[188:191], v[76:79]
	v_mfma_f32_16x16x32_bf16 v[72:75], v[132:135], v[188:191], v[72:75]
	v_mfma_f32_16x16x32_bf16 v[160:163], v[124:127], v[168:171], v[160:163]
	v_mfma_f32_16x16x32_bf16 v[148:151], v[136:139], v[168:171], v[148:151]
	v_mfma_f32_16x16x32_bf16 v[112:115], v[124:127], v[176:179], v[112:115]
	v_mfma_f32_16x16x32_bf16 v[108:111], v[136:139], v[176:179], v[108:111]
	v_mfma_f32_16x16x32_bf16 v[92:95], v[124:127], v[184:187], v[92:95]
	v_mfma_f32_16x16x32_bf16 v[88:91], v[136:139], v[184:187], v[88:91]
	v_mfma_f32_16x16x32_bf16 v[76:79], v[124:127], v[192:195], v[76:79]
	v_mfma_f32_16x16x32_bf16 v[72:75], v[136:139], v[192:195], v[72:75]
	v_mfma_f32_16x16x32_bf16 v[128:131], v[140:143], v[164:167], v[128:131]
	v_mfma_f32_16x16x32_bf16 v[116:119], v[152:155], v[164:167], v[116:119]
	v_mfma_f32_16x16x32_bf16 v[104:107], v[140:143], v[172:175], v[104:107]
	v_mfma_f32_16x16x32_bf16 v[100:103], v[152:155], v[172:175], v[100:103]
	v_mfma_f32_16x16x32_bf16 v[84:87], v[140:143], v[180:183], v[84:87]
	v_mfma_f32_16x16x32_bf16 v[80:83], v[152:155], v[180:183], v[80:83]
	v_mfma_f32_16x16x32_bf16 v[68:71], v[140:143], v[188:191], v[68:71]
	v_mfma_f32_16x16x32_bf16 v[64:67], v[152:155], v[188:191], v[64:67]
	v_mfma_f32_16x16x32_bf16 v[128:131], v[144:147], v[168:171], v[128:131]
	v_mfma_f32_16x16x32_bf16 v[116:119], v[156:159], v[168:171], v[116:119]
	v_mfma_f32_16x16x32_bf16 v[104:107], v[144:147], v[176:179], v[104:107]
	v_mfma_f32_16x16x32_bf16 v[100:103], v[156:159], v[176:179], v[100:103]
	v_mfma_f32_16x16x32_bf16 v[84:87], v[144:147], v[184:187], v[84:87]
	v_mfma_f32_16x16x32_bf16 v[80:83], v[156:159], v[184:187], v[80:83]
	v_mfma_f32_16x16x32_bf16 v[68:71], v[144:147], v[192:195], v[68:71]
	v_mfma_f32_16x16x32_bf16 v[64:67], v[156:159], v[192:195], v[64:67]
	s_setprio 0
	s_barrier
; #define PG8_STAGE(bufoff, gbase, voff) do { _Pragma("unroll") for (int _i = 0; _i < 2; ++_i) \
;         __builtin_amdgcn_global_load_lds((const unsigned*)((const char*)(gbase) + (voff)[_i]), (PG8_LAS unsigned*)(lds + (bufoff) + ldsw + _i * 8192), 16, 0, 0); } while (0)
; #define PG8_LDA(dst, b, h) do { _Pragma("unroll") for (int m = 0; m < 4; ++m) _Pragma("unroll") for (int k = 0; k < 2; ++k) dst[m][k] = *(const PG8_LAS bf16x8*)(lds + PG8_SA(b, h) + aoff + m * 2048 + k * 1024); } while (0)
; #define PG8_MMA(ai, bj, At, Bt) do { __builtin_amdgcn_s_setprio(1); _Pragma("unroll") for (int m = 0; m < 4; ++m) _Pragma("unroll") for (int n = 0; n < 2; ++n) _Pragma("unroll") for (int k = 0; k < 2; ++k) \
;         acc[ai][bj][m][n] = __builtin_amdgcn_mfma_f32_16x16x32_bf16(Bt[n][k], At[m][k], acc[ai][bj][m][n], 0, 0, 0); __builtin_amdgcn_s_setprio(0); } while (0)
; #define PG8_WAIT_V(n) asm volatile("s_waitcnt vmcnt(" #n ")" ::: "memory")
; #define PG8_WAIT_L(n) asm volatile("s_waitcnt lgkmcnt(" #n ")" ::: "memory")
; #define PG8_BAR __builtin_amdgcn_s_barrier()
; #define PG8_SCHED __builtin_amdgcn_sched_barrier(0)
; template <class Epi, class Sched, bool ALIGN_EPI = false, bool SP2 = false>
; __device__ __forceinline__ void gemm_phase(PG8_LAS unsigned char* lds, const Gemm g, const Sched& S, const Epi& E, const int tid_in) {
;     ...
;             PG8_LDA(At, 1, 1); PG8_STAGE(PG8_SB(1, 0), b3, voffB); PG8_STAGE(PG8_SB(1, 1), b3 + hstepB, voffB); PG8_STAGE(PG8_SA(1, 0), a3, voffA);
;             PG8_WAIT_V(8); PG8_WAIT_L(0); PG8_BAR; PG8_MMA(1, 0, At, B0); PG8_MMA(1, 1, At, B1); PG8_BAR; PG8_SCHED;
;     ...
;         if constexpr (ALIGN_EPI) { if (wr == 0) PG8_BAR; }
	s_add_i32 s20, s49, s30
	v_lshl_add_u64 v[196:197], v[196:197], 0, s[50:51]
	s_mov_b32 m0, s20
	ds_read_b128 v[164:167], v238 offset:49152
	ds_read_b128 v[168:171], v238 offset:50176
	ds_read_b128 v[172:175], v238 offset:51200
	ds_read_b128 v[176:179], v238 offset:52224
	ds_read_b128 v[180:183], v238 offset:53248
	ds_read_b128 v[184:187], v238 offset:54272
	ds_read_b128 v[188:191], v238 offset:55296
	ds_read_b128 v[192:195], v238 offset:56320
	global_load_lds_dwordx4 v[196:197], off
	s_add_i32 m0, s20, 0x2000
	s_add_u32 s20, s22, 0x20080
	v_lshl_add_u64 v[196:197], v[210:211], 0, s[50:51]
	s_addc_u32 s21, s23, 0
	s_add_i32 s22, s52, s30
	global_load_lds_dwordx4 v[196:197], off
	v_lshl_add_u64 v[196:197], s[20:21], 0, v[202:203]
	s_mov_b32 m0, s22
	s_nop 0
	global_load_lds_dwordx4 v[196:197], off
	v_lshl_add_u64 v[196:197], s[20:21], 0, v[96:97]
	s_add_i32 m0, s22, 0x2000
	s_nop 0
	global_load_lds_dwordx4 v[196:197], off
	v_lshl_add_u64 v[196:197], v[212:213], 0, s[50:51]
	s_mov_b32 m0, s39
	s_nop 0
	global_load_lds_dwordx4 v[196:197], off
	v_lshl_add_u64 v[196:197], v[214:215], 0, s[50:51]
	s_mov_b32 m0, s40
	s_nop 0
	global_load_lds_dwordx4 v[196:197], off
	s_waitcnt vmcnt(8)
	s_waitcnt lgkmcnt(0)
	s_barrier
	s_setprio 1
	s_waitcnt lgkmcnt(0)
	v_mfma_f32_16x16x32_bf16 v[60:63], v[120:123], v[164:167], v[60:63]
	v_mfma_f32_16x16x32_bf16 v[56:59], v[132:135], v[164:167], v[56:59]
	v_mfma_f32_16x16x32_bf16 v[44:47], v[120:123], v[172:175], v[44:47]
	v_mfma_f32_16x16x32_bf16 v[40:43], v[132:135], v[172:175], v[40:43]
	v_mfma_f32_16x16x32_bf16 v[28:31], v[120:123], v[180:183], v[28:31]
	v_mfma_f32_16x16x32_bf16 v[24:27], v[132:135], v[180:183], v[24:27]
	v_mfma_f32_16x16x32_bf16 v[12:15], v[120:123], v[188:191], v[12:15]
	v_mfma_f32_16x16x32_bf16 v[8:11], v[132:135], v[188:191], v[8:11]
	v_mfma_f32_16x16x32_bf16 v[60:63], v[124:127], v[168:171], v[60:63]
	v_mfma_f32_16x16x32_bf16 v[56:59], v[136:139], v[168:171], v[56:59]
	v_mfma_f32_16x16x32_bf16 v[44:47], v[124:127], v[176:179], v[44:47]
	v_mfma_f32_16x16x32_bf16 v[40:43], v[136:139], v[176:179], v[40:43]
	v_mfma_f32_16x16x32_bf16 v[28:31], v[124:127], v[184:187], v[28:31]
	v_mfma_f32_16x16x32_bf16 v[24:27], v[136:139], v[184:187], v[24:27]
	v_mfma_f32_16x16x32_bf16 v[12:15], v[124:127], v[192:195], v[12:15]
	v_mfma_f32_16x16x32_bf16 v[8:11], v[136:139], v[192:195], v[8:11]
	v_mfma_f32_16x16x32_bf16 v[52:55], v[140:143], v[164:167], v[52:55]
	v_mfma_f32_16x16x32_bf16 v[48:51], v[152:155], v[164:167], v[48:51]
	v_mfma_f32_16x16x32_bf16 v[36:39], v[140:143], v[172:175], v[36:39]
	v_mfma_f32_16x16x32_bf16 v[32:35], v[152:155], v[172:175], v[32:35]
	v_mfma_f32_16x16x32_bf16 v[20:23], v[140:143], v[180:183], v[20:23]
	v_mfma_f32_16x16x32_bf16 v[16:19], v[152:155], v[180:183], v[16:19]
	v_mfma_f32_16x16x32_bf16 v[4:7], v[140:143], v[188:191], v[4:7]
	v_mfma_f32_16x16x32_bf16 v[0:3], v[152:155], v[188:191], v[0:3]
	v_mfma_f32_16x16x32_bf16 v[52:55], v[144:147], v[168:171], v[52:55]
	v_mfma_f32_16x16x32_bf16 v[48:51], v[156:159], v[168:171], v[48:51]
	v_mfma_f32_16x16x32_bf16 v[36:39], v[144:147], v[176:179], v[36:39]
	v_mfma_f32_16x16x32_bf16 v[32:35], v[156:159], v[176:179], v[32:35]
	v_mfma_f32_16x16x32_bf16 v[20:23], v[144:147], v[184:187], v[20:23]
	v_mfma_f32_16x16x32_bf16 v[16:19], v[156:159], v[184:187], v[16:19]
	v_mfma_f32_16x16x32_bf16 v[4:7], v[144:147], v[192:195], v[4:7]
	v_mfma_f32_16x16x32_bf16 v[0:3], v[156:159], v[192:195], v[0:3]
	s_setprio 0
	s_barrier
	s_add_i32 s48, s48, 2
	s_add_u32 s46, s46, 0x100
	s_addc_u32 s47, s47, 0
	s_cmp_gt_u32 s48, 5
	s_mov_b64 s[20:21], s[0:1]
	s_cbranch_scc0 .LBB0_615
	s_and_b64 vcc, exec, s[12:13]
	s_cbranch_vccz .LBB0_618
	s_barrier

; #define PG8_STAGE(bufoff, gbase, voff) do { _Pragma("unroll") for (int _i = 0; _i < 2; ++_i) \
;         __builtin_amdgcn_global_load_lds((const unsigned*)((const char*)(gbase) + (voff)[_i]), (PG8_LAS unsigned*)(lds + (bufoff) + ldsw + _i * 8192), 16, 0, 0); } while (0)
; #define PG8_LDA(dst, b, h) do { _Pragma("unroll") for (int m = 0; m < 4; ++m) _Pragma("unroll") for (int k = 0; k < 2; ++k) dst[m][k] = *(const PG8_LAS bf16x8*)(lds + PG8_SA(b, h) + aoff + m * 2048 + k * 1024); } while (0)
; #define PG8_LDB(dst, b, h) do { _Pragma("unroll") for (int n = 0; n < 2; ++n) _Pragma("unroll") for (int k = 0; k < 2; ++k) dst[n][k] = *(const PG8_LAS bf16x8*)(lds + PG8_SB(b, h) + boff + n * 2048 + k * 1024); } while (0)
; #define PG8_MMA(ai, bj, At, Bt) do { __builtin_amdgcn_s_setprio(1); _Pragma("unroll") for (int m = 0; m < 4; ++m) _Pragma("unroll") for (int n = 0; n < 2; ++n) _Pragma("unroll") for (int k = 0; k < 2; ++k) \
;         acc[ai][bj][m][n] = __builtin_amdgcn_mfma_f32_16x16x32_bf16(Bt[n][k], At[m][k], acc[ai][bj][m][n], 0, 0, 0); __builtin_amdgcn_s_setprio(0); } while (0)
; #define PG8_WAIT_V(n) asm volatile("s_waitcnt vmcnt(" #n ")" ::: "memory")
; #define PG8_WAIT_L(n) asm volatile("s_waitcnt lgkmcnt(" #n ")" ::: "memory")
; #define PG8_BAR __builtin_amdgcn_s_barrier()
; #define PG8_SCHED __builtin_amdgcn_sched_barrier(0)
; template <class Epi, class Sched, bool ALIGN_EPI = false, bool SP2 = false>
; __device__ __forceinline__ void gemm_phase(PG8_LAS unsigned char* lds, const Gemm g, const Sched& S, const Epi& E, const int tid_in) {
;     ...
;             const bool last = (t == nt - 2);
;             const char* a1 = cA + (size_t)(t + 1) * kstep;
;             const char* a2 = last ? nA : cA + (size_t)(t + 2) * kstep; const char* b2 = last ? nB : cB + (size_t)(t + 2) * kstep;
;             const char* a3 = a2 + kstep; const char* b3 = b2 + kstep;
;             if (last && has_next) S.a_ready(nxt);
;             if constexpr (SP2) {
;             PG8_LDB(B0, 0, 0); PG8_LDB(B1, 0, 1); PG8_SCHED; PG8_LDA(At, 0, 0); PG8_STAGE(PG8_SA(1, 1), a1 + hstepA, voffA);
;             PG8_WAIT_V(8); PG8_WAIT_L(0); PG8_BAR; PG8_MMA(0, 0, At, B0); PG8_MMA(0, 1, At, B1); PG8_BAR; PG8_SCHED;
;             PG8_LDA(At, 0, 1); PG8_STAGE(PG8_SB(0, 0), b2, voffB); PG8_STAGE(PG8_SB(0, 1), b2 + hstepB, voffB); PG8_STAGE(PG8_SA(0, 0), a2, voffA);
.LBB0_689:
	s_add_u32 s30, s28, 0xfffc0080
	s_addc_u32 s31, s29, -1
	s_add_i32 s62, 0, 0x10000
	s_cmp_eq_u32 s61, 12
	s_cselect_b32 s35, s23, s31
	s_cselect_b32 s34, s55, s30
	s_cselect_b32 s31, s21, s60
	s_cselect_b32 s30, s56, s57
	s_add_i32 s64, 0, 0x14000
	v_add_u32_e32 v144, s62, v180
	v_add_u32_e32 v166, s64, v180
	s_waitcnt lgkmcnt(0)
	ds_read_b128 v[132:135], v144
	ds_read_b128 v[136:139], v144 offset:1024
	ds_read_b128 v[140:143], v144 offset:2048
	ds_read_b128 v[144:147], v144 offset:3072
	ds_read_b128 v[154:157], v166
	ds_read_b128 v[158:161], v166 offset:1024
	ds_read_b128 v[162:165], v166 offset:2048
	ds_read_b128 v[166:169], v166 offset:3072
	v_lshl_add_u64 v[178:179], s[28:29], 0, v[150:151]
	s_add_i32 m0, s43, 0xc000
	ds_read_b128 v[170:173], v181
	ds_read_b128 v[174:177], v181 offset:1024
	ds_read_b128 v[182:185], v181 offset:2048
	ds_read_b128 v[186:189], v181 offset:3072
	ds_read_b128 v[190:193], v181 offset:4096
	ds_read_b128 v[200:203], v181 offset:5120
	ds_read_b128 v[204:207], v181 offset:6144
	ds_read_b128 v[208:211], v181 offset:7168
	global_load_lds_dwordx4 v[178:179], off
	v_lshl_add_u64 v[178:179], s[28:29], 0, v[152:153]
	s_add_i32 m0, s43, 0xe000
	s_nop 0
	global_load_lds_dwordx4 v[178:179], off
	s_waitcnt vmcnt(8)
	s_waitcnt lgkmcnt(0)
	s_barrier
	s_setprio 1
	s_waitcnt lgkmcnt(0)
	v_mfma_f32_16x16x32_bf16 v[128:131], v[132:135], v[170:173], v[128:131]
	v_mfma_f32_16x16x32_bf16 v[124:127], v[140:143], v[170:173], v[124:127]
	v_mfma_f32_16x16x32_bf16 v[112:115], v[132:135], v[182:185], v[112:115]
	v_mfma_f32_16x16x32_bf16 v[108:111], v[140:143], v[182:185], v[108:111]
	v_mfma_f32_16x16x32_bf16 v[92:95], v[132:135], v[190:193], v[92:95]
	v_mfma_f32_16x16x32_bf16 v[88:91], v[140:143], v[190:193], v[88:91]
	v_mfma_f32_16x16x32_bf16 v[76:79], v[132:135], v[204:207], v[76:79]
	v_mfma_f32_16x16x32_bf16 v[72:75], v[140:143], v[204:207], v[72:75]
	v_mfma_f32_16x16x32_bf16 v[128:131], v[136:139], v[174:177], v[128:131]
	v_mfma_f32_16x16x32_bf16 v[124:127], v[144:147], v[174:177], v[124:127]
	v_mfma_f32_16x16x32_bf16 v[112:115], v[136:139], v[186:189], v[112:115]
	v_mfma_f32_16x16x32_bf16 v[108:111], v[144:147], v[186:189], v[108:111]
	v_mfma_f32_16x16x32_bf16 v[92:95], v[136:139], v[200:203], v[92:95]
	v_mfma_f32_16x16x32_bf16 v[88:91], v[144:147], v[200:203], v[88:91]
	v_mfma_f32_16x16x32_bf16 v[76:79], v[136:139], v[208:211], v[76:79]
	v_mfma_f32_16x16x32_bf16 v[72:75], v[144:147], v[208:211], v[72:75]
	v_mfma_f32_16x16x32_bf16 v[120:123], v[154:157], v[170:173], v[120:123]
	v_mfma_f32_16x16x32_bf16 v[116:119], v[162:165], v[170:173], v[116:119]
	v_mfma_f32_16x16x32_bf16 v[104:107], v[154:157], v[182:185], v[104:107]
	v_mfma_f32_16x16x32_bf16 v[100:103], v[162:165], v[182:185], v[100:103]
	v_mfma_f32_16x16x32_bf16 v[84:87], v[154:157], v[190:193], v[84:87]
	v_mfma_f32_16x16x32_bf16 v[80:83], v[162:165], v[190:193], v[80:83]
	v_mfma_f32_16x16x32_bf16 v[68:71], v[154:157], v[204:207], v[68:71]
	v_mfma_f32_16x16x32_bf16 v[64:67], v[162:165], v[204:207], v[64:67]
	v_mfma_f32_16x16x32_bf16 v[120:123], v[158:161], v[174:177], v[120:123]
	v_mfma_f32_16x16x32_bf16 v[116:119], v[166:169], v[174:177], v[116:119]
	v_mfma_f32_16x16x32_bf16 v[104:107], v[158:161], v[186:189], v[104:107]
	v_mfma_f32_16x16x32_bf16 v[100:103], v[166:169], v[186:189], v[100:103]
	v_mfma_f32_16x16x32_bf16 v[84:87], v[158:161], v[200:203], v[84:87]
	v_mfma_f32_16x16x32_bf16 v[80:83], v[166:169], v[200:203], v[80:83]
	v_mfma_f32_16x16x32_bf16 v[68:71], v[158:161], v[208:211], v[68:71]
	v_mfma_f32_16x16x32_bf16 v[64:67], v[166:169], v[208:211], v[64:67]
	s_setprio 0
	s_barrier
	s_add_i32 s62, s62, s38
	v_lshl_add_u64 v[178:179], s[30:31], 0, v[148:149]
	s_mov_b32 m0, s62
	ds_read_b128 v[170:173], v181 offset:16384
	ds_read_b128 v[174:177], v181 offset:17408
	ds_read_b128 v[182:185], v181 offset:18432
	ds_read_b128 v[186:189], v181 offset:19456
	ds_read_b128 v[190:193], v181 offset:20480
	ds_read_b128 v[200:203], v181 offset:21504
	ds_read_b128 v[204:207], v181 offset:22528
	ds_read_b128 v[208:211], v181 offset:23552
	global_load_lds_dwordx4 v[178:179], off
	s_add_i32 m0, s62, 0x2000
	s_add_u32 s62, s30, 0x40000
	v_lshl_add_u64 v[194:195], s[30:31], 0, v[96:97]
	s_addc_u32 s63, s31, 0
	s_add_i32 s64, s64, s38
	global_load_lds_dwordx4 v[194:195], off
	v_lshl_add_u64 v[196:197], s[62:63], 0, v[148:149]
	s_mov_b32 m0, s64
	v_lshl_add_u64 v[212:213], s[34:35], 0, v[96:97]
	global_load_lds_dwordx4 v[196:197], off
	v_lshl_add_u64 v[196:197], s[62:63], 0, v[96:97]
	s_add_i32 m0, s64, 0x2000
	s_nop 0
	global_load_lds_dwordx4 v[196:197], off
	v_lshl_add_u64 v[196:197], s[34:35], 0, v[148:149]
	s_mov_b32 m0, s43
	s_nop 0
	global_load_lds_dwordx4 v[196:197], off
	s_mov_b32 m0, s44
	s_nop 0
	global_load_lds_dwordx4 v[212:213], off
	s_waitcnt vmcnt(8)
	s_waitcnt lgkmcnt(0)
	s_barrier
; #define PG8_STAGE(bufoff, gbase, voff) do { _Pragma("unroll") for (int _i = 0; _i < 2; ++_i) \
;         __builtin_amdgcn_global_load_lds((const unsigned*)((const char*)(gbase) + (voff)[_i]), (PG8_LAS unsigned*)(lds + (bufoff) + ldsw + _i * 8192), 16, 0, 0); } while (0)
; #define PG8_LDA(dst, b, h) do { _Pragma("unroll") for (int m = 0; m < 4; ++m) _Pragma("unroll") for (int k = 0; k < 2; ++k) dst[m][k] = *(const PG8_LAS bf16x8*)(lds + PG8_SA(b, h) + aoff + m * 2048 + k * 1024); } while (0)
; #define PG8_LDB(dst, b, h) do { _Pragma("unroll") for (int n = 0; n < 2; ++n) _Pragma("unroll") for (int k = 0; k < 2; ++k) dst[n][k] = *(const PG8_LAS bf16x8*)(lds + PG8_SB(b, h) + boff + n * 2048 + k * 1024); } while (0)
; #define PG8_MMA(ai, bj, At, Bt) do { __builtin_amdgcn_s_setprio(1); _Pragma("unroll") for (int m = 0; m < 4; ++m) _Pragma("unroll") for (int n = 0; n < 2; ++n) _Pragma("unroll") for (int k = 0; k < 2; ++k) \
;         acc[ai][bj][m][n] = __builtin_amdgcn_mfma_f32_16x16x32_bf16(Bt[n][k], At[m][k], acc[ai][bj][m][n], 0, 0, 0); __builtin_amdgcn_s_setprio(0); } while (0)
; #define PG8_WAIT_V(n) asm volatile("s_waitcnt vmcnt(" #n ")" ::: "memory")
; #define PG8_WAIT_L(n) asm volatile("s_waitcnt lgkmcnt(" #n ")" ::: "memory")
; #define PG8_BAR __builtin_amdgcn_s_barrier()
; #define PG8_SCHED __builtin_amdgcn_sched_barrier(0)
; template <class Epi, class Sched, bool ALIGN_EPI = false, bool SP2 = false>
; __device__ __forceinline__ void gemm_phase(PG8_LAS unsigned char* lds, const Gemm g, const Sched& S, const Epi& E, const int tid_in) {
;     ...
;             PG8_WAIT_V(8); PG8_WAIT_L(0); PG8_BAR; PG8_MMA(1, 0, At, B0); PG8_MMA(1, 1, At, B1); PG8_BAR; PG8_SCHED;
;             PG8_LDB(B0, 1, 0); PG8_LDB(B1, 1, 1); PG8_SCHED; PG8_LDA(At, 1, 0); PG8_STAGE(PG8_SA(0, 1), a2 + hstepA, voffA);
;             PG8_WAIT_V(8); PG8_WAIT_L(0); PG8_BAR; PG8_MMA(0, 0, At, B0); PG8_MMA(0, 1, At, B1); PG8_BAR; PG8_SCHED;
	s_setprio 1
	s_waitcnt lgkmcnt(0)
	v_mfma_f32_16x16x32_bf16 v[60:63], v[132:135], v[170:173], v[60:63]
	v_mfma_f32_16x16x32_bf16 v[56:59], v[140:143], v[170:173], v[56:59]
	v_mfma_f32_16x16x32_bf16 v[44:47], v[132:135], v[182:185], v[44:47]
	v_mfma_f32_16x16x32_bf16 v[40:43], v[140:143], v[182:185], v[40:43]
	v_mfma_f32_16x16x32_bf16 v[28:31], v[132:135], v[190:193], v[28:31]
	v_mfma_f32_16x16x32_bf16 v[24:27], v[140:143], v[190:193], v[24:27]
	v_mfma_f32_16x16x32_bf16 v[12:15], v[132:135], v[204:207], v[12:15]
	v_mfma_f32_16x16x32_bf16 v[8:11], v[140:143], v[204:207], v[8:11]
	v_mfma_f32_16x16x32_bf16 v[60:63], v[136:139], v[174:177], v[60:63]
	v_mfma_f32_16x16x32_bf16 v[56:59], v[144:147], v[174:177], v[56:59]
	v_mfma_f32_16x16x32_bf16 v[44:47], v[136:139], v[186:189], v[44:47]
	v_mfma_f32_16x16x32_bf16 v[40:43], v[144:147], v[186:189], v[40:43]
	v_mfma_f32_16x16x32_bf16 v[28:31], v[136:139], v[200:203], v[28:31]
	v_mfma_f32_16x16x32_bf16 v[24:27], v[144:147], v[200:203], v[24:27]
	v_mfma_f32_16x16x32_bf16 v[12:15], v[136:139], v[208:211], v[12:15]
	v_mfma_f32_16x16x32_bf16 v[8:11], v[144:147], v[208:211], v[8:11]
	v_mfma_f32_16x16x32_bf16 v[52:55], v[154:157], v[170:173], v[52:55]
	v_mfma_f32_16x16x32_bf16 v[48:51], v[162:165], v[170:173], v[48:51]
	v_mfma_f32_16x16x32_bf16 v[36:39], v[154:157], v[182:185], v[36:39]
	v_mfma_f32_16x16x32_bf16 v[32:35], v[162:165], v[182:185], v[32:35]
	v_mfma_f32_16x16x32_bf16 v[20:23], v[154:157], v[190:193], v[20:23]
	v_mfma_f32_16x16x32_bf16 v[16:19], v[162:165], v[190:193], v[16:19]
	v_mfma_f32_16x16x32_bf16 v[4:7], v[154:157], v[204:207], v[4:7]
	v_mfma_f32_16x16x32_bf16 v[0:3], v[162:165], v[204:207], v[0:3]
	v_mfma_f32_16x16x32_bf16 v[52:55], v[158:161], v[174:177], v[52:55]
	v_mfma_f32_16x16x32_bf16 v[48:51], v[166:169], v[174:177], v[48:51]
	v_mfma_f32_16x16x32_bf16 v[36:39], v[158:161], v[186:189], v[36:39]
	v_mfma_f32_16x16x32_bf16 v[32:35], v[166:169], v[186:189], v[32:35]
	v_mfma_f32_16x16x32_bf16 v[20:23], v[158:161], v[200:203], v[20:23]
	v_mfma_f32_16x16x32_bf16 v[16:19], v[166:169], v[200:203], v[16:19]
	v_mfma_f32_16x16x32_bf16 v[4:7], v[158:161], v[208:211], v[4:7]
	v_mfma_f32_16x16x32_bf16 v[0:3], v[166:169], v[208:211], v[0:3]
	s_setprio 0
	s_barrier
	s_add_i32 s62, 0, 0x18000
	s_add_i32 s63, 0, 0x1c000
	v_add_u32_e32 v144, s62, v180
	v_add_u32_e32 v166, s63, v180
	ds_read_b128 v[132:135], v144
	ds_read_b128 v[136:139], v144 offset:1024
	ds_read_b128 v[140:143], v144 offset:2048
	ds_read_b128 v[144:147], v144 offset:3072
	ds_read_b128 v[154:157], v166
	ds_read_b128 v[158:161], v166 offset:1024
	ds_read_b128 v[162:165], v166 offset:2048
	ds_read_b128 v[166:169], v166 offset:3072
	s_add_u32 s34, s34, 0x40000
	s_addc_u32 s35, s35, 0
	s_mov_b32 m0, s45
	v_lshl_add_u64 v[214:215], s[34:35], 0, v[148:149]
	ds_read_b128 v[170:173], v181 offset:32768
	ds_read_b128 v[174:177], v181 offset:33792
	ds_read_b128 v[182:185], v181 offset:34816
	ds_read_b128 v[186:189], v181 offset:35840
	ds_read_b128 v[190:193], v181 offset:36864
	ds_read_b128 v[200:203], v181 offset:37888
	ds_read_b128 v[204:207], v181 offset:38912
	ds_read_b128 v[208:211], v181 offset:39936
	global_load_lds_dwordx4 v[214:215], off
	v_lshl_add_u64 v[214:215], s[34:35], 0, v[96:97]
	s_mov_b32 m0, s46
	s_nop 0
	global_load_lds_dwordx4 v[214:215], off
	s_waitcnt vmcnt(8)
	s_waitcnt lgkmcnt(0)
	s_barrier
	s_setprio 1
	s_waitcnt lgkmcnt(0)
	v_mfma_f32_16x16x32_bf16 v[128:131], v[132:135], v[170:173], v[128:131]
	v_mfma_f32_16x16x32_bf16 v[124:127], v[140:143], v[170:173], v[124:127]
	v_mfma_f32_16x16x32_bf16 v[112:115], v[132:135], v[182:185], v[112:115]
	v_mfma_f32_16x16x32_bf16 v[108:111], v[140:143], v[182:185], v[108:111]
	v_mfma_f32_16x16x32_bf16 v[92:95], v[132:135], v[190:193], v[92:95]
	v_mfma_f32_16x16x32_bf16 v[88:91], v[140:143], v[190:193], v[88:91]
	v_mfma_f32_16x16x32_bf16 v[76:79], v[132:135], v[204:207], v[76:79]
	v_mfma_f32_16x16x32_bf16 v[72:75], v[140:143], v[204:207], v[72:75]
	v_mfma_f32_16x16x32_bf16 v[128:131], v[136:139], v[174:177], v[128:131]
	v_mfma_f32_16x16x32_bf16 v[124:127], v[144:147], v[174:177], v[124:127]
	v_mfma_f32_16x16x32_bf16 v[112:115], v[136:139], v[186:189], v[112:115]
	v_mfma_f32_16x16x32_bf16 v[108:111], v[144:147], v[186:189], v[108:111]
	v_mfma_f32_16x16x32_bf16 v[92:95], v[136:139], v[200:203], v[92:95]
	v_mfma_f32_16x16x32_bf16 v[88:91], v[144:147], v[200:203], v[88:91]
	v_mfma_f32_16x16x32_bf16 v[76:79], v[136:139], v[208:211], v[76:79]
	v_mfma_f32_16x16x32_bf16 v[72:75], v[144:147], v[208:211], v[72:75]
	v_mfma_f32_16x16x32_bf16 v[120:123], v[154:157], v[170:173], v[120:123]
	v_mfma_f32_16x16x32_bf16 v[116:119], v[162:165], v[170:173], v[116:119]
	v_mfma_f32_16x16x32_bf16 v[104:107], v[154:157], v[182:185], v[104:107]
	v_mfma_f32_16x16x32_bf16 v[100:103], v[162:165], v[182:185], v[100:103]
	v_mfma_f32_16x16x32_bf16 v[84:87], v[154:157], v[190:193], v[84:87]
	v_mfma_f32_16x16x32_bf16 v[80:83], v[162:165], v[190:193], v[80:83]
	v_mfma_f32_16x16x32_bf16 v[68:71], v[154:157], v[204:207], v[68:71]
	v_mfma_f32_16x16x32_bf16 v[64:67], v[162:165], v[204:207], v[64:67]
	v_mfma_f32_16x16x32_bf16 v[120:123], v[158:161], v[174:177], v[120:123]
	v_mfma_f32_16x16x32_bf16 v[116:119], v[166:169], v[174:177], v[116:119]
	v_mfma_f32_16x16x32_bf16 v[104:107], v[158:161], v[186:189], v[104:107]
	v_mfma_f32_16x16x32_bf16 v[100:103], v[166:169], v[186:189], v[100:103]
	v_mfma_f32_16x16x32_bf16 v[84:87], v[158:161], v[200:203], v[84:87]
	v_mfma_f32_16x16x32_bf16 v[80:83], v[166:169], v[200:203], v[80:83]
	v_mfma_f32_16x16x32_bf16 v[68:71], v[158:161], v[208:211], v[68:71]
	v_mfma_f32_16x16x32_bf16 v[64:67], v[166:169], v[208:211], v[64:67]
	s_setprio 0
	s_barrier
; #define PG8_STAGE(bufoff, gbase, voff) do { _Pragma("unroll") for (int _i = 0; _i < 2; ++_i) \
;         __builtin_amdgcn_global_load_lds((const unsigned*)((const char*)(gbase) + (voff)[_i]), (PG8_LAS unsigned*)(lds + (bufoff) + ldsw + _i * 8192), 16, 0, 0); } while (0)
; #define PG8_LDA(dst, b, h) do { _Pragma("unroll") for (int m = 0; m < 4; ++m) _Pragma("unroll") for (int k = 0; k < 2; ++k) dst[m][k] = *(const PG8_LAS bf16x8*)(lds + PG8_SA(b, h) + aoff + m * 2048 + k * 1024); } while (0)
; #define PG8_MMA(ai, bj, At, Bt) do { __builtin_amdgcn_s_setprio(1); _Pragma("unroll") for (int m = 0; m < 4; ++m) _Pragma("unroll") for (int n = 0; n < 2; ++n) _Pragma("unroll") for (int k = 0; k < 2; ++k) \
;         acc[ai][bj][m][n] = __builtin_amdgcn_mfma_f32_16x16x32_bf16(Bt[n][k], At[m][k], acc[ai][bj][m][n], 0, 0, 0); __builtin_amdgcn_s_setprio(0); } while (0)
; #define PG8_WAIT_V(n) asm volatile("s_waitcnt vmcnt(" #n ")" ::: "memory")
; #define PG8_WAIT_L(n) asm volatile("s_waitcnt lgkmcnt(" #n ")" ::: "memory")
; #define PG8_BAR __builtin_amdgcn_s_barrier()
; #define PG8_SCHED __builtin_amdgcn_sched_barrier(0)
; template <class Epi, class Sched, bool ALIGN_EPI = false, bool SP2 = false>
; __device__ __forceinline__ void gemm_phase(PG8_LAS unsigned char* lds, const Gemm g, const Sched& S, const Epi& E, const int tid_in) {
;     ...
;             PG8_LDA(At, 1, 1); PG8_STAGE(PG8_SB(1, 0), b3, voffB); PG8_STAGE(PG8_SB(1, 1), b3 + hstepB, voffB); PG8_STAGE(PG8_SA(1, 0), a3, voffA);
;             PG8_WAIT_V(8); PG8_WAIT_L(0); PG8_BAR; PG8_MMA(1, 0, At, B0); PG8_MMA(1, 1, At, B1); PG8_BAR; PG8_SCHED;
;     ...
;         if constexpr (ALIGN_EPI) { if (wr == 0) PG8_BAR; }
	s_add_i32 s34, s62, s38
	v_lshl_add_u64 v[178:179], v[178:179], 0, s[50:51]
	s_mov_b32 m0, s34
	ds_read_b128 v[170:173], v181 offset:49152
	ds_read_b128 v[174:177], v181 offset:50176
	ds_read_b128 v[182:185], v181 offset:51200
	ds_read_b128 v[186:189], v181 offset:52224
	ds_read_b128 v[190:193], v181 offset:53248
	ds_read_b128 v[200:203], v181 offset:54272
	ds_read_b128 v[204:207], v181 offset:55296
	ds_read_b128 v[208:211], v181 offset:56320
	global_load_lds_dwordx4 v[178:179], off
	s_add_i32 m0, s34, 0x2000
	s_add_u32 s30, s30, 0x40080
	v_lshl_add_u64 v[178:179], v[194:195], 0, s[50:51]
	s_addc_u32 s31, s31, 0
	s_add_i32 s34, s63, s38
	global_load_lds_dwordx4 v[178:179], off
	v_lshl_add_u64 v[178:179], s[30:31], 0, v[148:149]
	s_mov_b32 m0, s34
	s_nop 0
	global_load_lds_dwordx4 v[178:179], off
	v_lshl_add_u64 v[178:179], s[30:31], 0, v[96:97]
	s_add_i32 m0, s34, 0x2000
	s_nop 0
	global_load_lds_dwordx4 v[178:179], off
	v_lshl_add_u64 v[178:179], v[196:197], 0, s[50:51]
	s_mov_b32 m0, s52
	s_nop 0
	global_load_lds_dwordx4 v[178:179], off
	v_lshl_add_u64 v[178:179], v[212:213], 0, s[50:51]
	s_mov_b32 m0, s53
	s_nop 0
	global_load_lds_dwordx4 v[178:179], off
	s_waitcnt vmcnt(8)
	s_waitcnt lgkmcnt(0)
	s_barrier
	s_setprio 1
	s_waitcnt lgkmcnt(0)
	v_mfma_f32_16x16x32_bf16 v[60:63], v[132:135], v[170:173], v[60:63]
	v_mfma_f32_16x16x32_bf16 v[56:59], v[140:143], v[170:173], v[56:59]
	v_mfma_f32_16x16x32_bf16 v[44:47], v[132:135], v[182:185], v[44:47]
	v_mfma_f32_16x16x32_bf16 v[40:43], v[140:143], v[182:185], v[40:43]
	v_mfma_f32_16x16x32_bf16 v[28:31], v[132:135], v[190:193], v[28:31]
	v_mfma_f32_16x16x32_bf16 v[24:27], v[140:143], v[190:193], v[24:27]
	v_mfma_f32_16x16x32_bf16 v[12:15], v[132:135], v[204:207], v[12:15]
	v_mfma_f32_16x16x32_bf16 v[8:11], v[140:143], v[204:207], v[8:11]
	v_mfma_f32_16x16x32_bf16 v[60:63], v[136:139], v[174:177], v[60:63]
	v_mfma_f32_16x16x32_bf16 v[56:59], v[144:147], v[174:177], v[56:59]
	v_mfma_f32_16x16x32_bf16 v[44:47], v[136:139], v[186:189], v[44:47]
	v_mfma_f32_16x16x32_bf16 v[40:43], v[144:147], v[186:189], v[40:43]
	v_mfma_f32_16x16x32_bf16 v[28:31], v[136:139], v[200:203], v[28:31]
	v_mfma_f32_16x16x32_bf16 v[24:27], v[144:147], v[200:203], v[24:27]
	v_mfma_f32_16x16x32_bf16 v[12:15], v[136:139], v[208:211], v[12:15]
	v_mfma_f32_16x16x32_bf16 v[8:11], v[144:147], v[208:211], v[8:11]
	v_mfma_f32_16x16x32_bf16 v[52:55], v[154:157], v[170:173], v[52:55]
	v_mfma_f32_16x16x32_bf16 v[48:51], v[162:165], v[170:173], v[48:51]
	v_mfma_f32_16x16x32_bf16 v[36:39], v[154:157], v[182:185], v[36:39]
	v_mfma_f32_16x16x32_bf16 v[32:35], v[162:165], v[182:185], v[32:35]
	v_mfma_f32_16x16x32_bf16 v[20:23], v[154:157], v[190:193], v[20:23]
	v_mfma_f32_16x16x32_bf16 v[16:19], v[162:165], v[190:193], v[16:19]
	v_mfma_f32_16x16x32_bf16 v[4:7], v[154:157], v[204:207], v[4:7]
	v_mfma_f32_16x16x32_bf16 v[0:3], v[162:165], v[204:207], v[0:3]
	v_mfma_f32_16x16x32_bf16 v[52:55], v[158:161], v[174:177], v[52:55]
	v_mfma_f32_16x16x32_bf16 v[48:51], v[166:169], v[174:177], v[48:51]
	v_mfma_f32_16x16x32_bf16 v[36:39], v[158:161], v[186:189], v[36:39]
	v_mfma_f32_16x16x32_bf16 v[32:35], v[166:169], v[186:189], v[32:35]
	v_mfma_f32_16x16x32_bf16 v[20:23], v[158:161], v[200:203], v[20:23]
	v_mfma_f32_16x16x32_bf16 v[16:19], v[166:169], v[200:203], v[16:19]
	v_mfma_f32_16x16x32_bf16 v[4:7], v[158:161], v[208:211], v[4:7]
	v_mfma_f32_16x16x32_bf16 v[0:3], v[166:169], v[208:211], v[0:3]
	s_setprio 0
	s_barrier
	s_add_i32 s61, s61, 2
	s_add_u32 s28, s28, 0x100
	s_addc_u32 s29, s29, 0
	s_add_u32 s57, s57, 0x100
	s_addc_u32 s60, s60, 0
	s_cmp_gt_u32 s61, 13
	s_cbranch_scc0 .LBB0_689
	s_and_b64 vcc, exec, s[16:17]
	s_cbranch_vccz .LBB0_692
	s_barrier

; #define PG8_STAGE(bufoff, gbase, voff) do { _Pragma("unroll") for (int _i = 0; _i < 2; ++_i) \
;         __builtin_amdgcn_global_load_lds((const unsigned*)((const char*)(gbase) + (voff)[_i]), (PG8_LAS unsigned*)(lds + (bufoff) + ldsw + _i * 8192), 16, 0, 0); } while (0)
; #define PG8_LDA(dst, b, h) do { _Pragma("unroll") for (int m = 0; m < 4; ++m) _Pragma("unroll") for (int k = 0; k < 2; ++k) dst[m][k] = *(const PG8_LAS bf16x8*)(lds + PG8_SA(b, h) + aoff + m * 2048 + k * 1024); } while (0)
; #define PG8_LDB(dst, b, h) do { _Pragma("unroll") for (int n = 0; n < 2; ++n) _Pragma("unroll") for (int k = 0; k < 2; ++k) dst[n][k] = *(const PG8_LAS bf16x8*)(lds + PG8_SB(b, h) + boff + n * 2048 + k * 1024); } while (0)
; #define PG8_MMA(ai, bj, At, Bt) do { __builtin_amdgcn_s_setprio(1); _Pragma("unroll") for (int m = 0; m < 4; ++m) _Pragma("unroll") for (int n = 0; n < 2; ++n) _Pragma("unroll") for (int k = 0; k < 2; ++k) \
;         acc[ai][bj][m][n] = __builtin_amdgcn_mfma_f32_16x16x32_bf16(Bt[n][k], At[m][k], acc[ai][bj][m][n], 0, 0, 0); __builtin_amdgcn_s_setprio(0); } while (0)
; #define PG8_WAIT_V(n) asm volatile("s_waitcnt vmcnt(" #n ")" ::: "memory")
; #define PG8_WAIT_L(n) asm volatile("s_waitcnt lgkmcnt(" #n ")" ::: "memory")
; #define PG8_BAR __builtin_amdgcn_s_barrier()
; #define PG8_SCHED __builtin_amdgcn_sched_barrier(0)
; template <class Epi, class Sched, bool ALIGN_EPI = false, bool SP2 = false>
; __device__ __forceinline__ void gemm_phase(PG8_LAS unsigned char* lds, const Gemm g, const Sched& S, const Epi& E, const int tid_in) {
;     ...
;             const bool last = (t == nt - 2);
;             const char* a1 = cA + (size_t)(t + 1) * kstep;
;             const char* a2 = last ? nA : cA + (size_t)(t + 2) * kstep; const char* b2 = last ? nB : cB + (size_t)(t + 2) * kstep;
;             const char* a3 = a2 + kstep; const char* b3 = b2 + kstep;
;             if (last && has_next) S.a_ready(nxt);
;             if constexpr (SP2) {
;             PG8_LDB(B0, 0, 0); PG8_LDB(B1, 0, 1); PG8_SCHED; PG8_LDA(At, 0, 0); PG8_STAGE(PG8_SA(1, 1), a1 + hstepA, voffA);
;             PG8_WAIT_V(8); PG8_WAIT_L(0); PG8_BAR; PG8_MMA(0, 0, At, B0); PG8_MMA(0, 1, At, B1); PG8_BAR; PG8_SCHED;
;             PG8_LDA(At, 0, 1); PG8_STAGE(PG8_SB(0, 0), b2, voffB); PG8_STAGE(PG8_SB(0, 1), b2 + hstepB, voffB); PG8_STAGE(PG8_SA(0, 0), a2, voffA);
.LBB0_849:
	s_add_u32 s30, s28, 0xfffc0080
	s_addc_u32 s31, s29, -1
	s_add_i32 s60, 0, 0x10000
	s_cmp_eq_u32 s57, 12
	s_cselect_b32 s35, s23, s31
	s_cselect_b32 s34, s53, s30
	v_add_u32_e32 v142, s60, v143
	s_cselect_b32 s31, s21, s56
	s_cselect_b32 s30, s54, s55
	s_add_i32 s62, 0, 0x14000
	ds_read_b128 v[146:149], v142
	ds_read_b128 v[150:153], v142 offset:1024
	ds_read_b128 v[154:157], v142 offset:2048
	ds_read_b128 v[158:161], v142 offset:3072
	v_add_u32_e32 v142, s62, v143
	ds_read_b128 v[162:165], v142
	ds_read_b128 v[166:169], v142 offset:1024
	ds_read_b128 v[170:173], v142 offset:2048
	ds_read_b128 v[174:177], v142 offset:3072
	v_lshl_add_u64 v[212:213], s[28:29], 0, v[138:139]
	s_add_i32 m0, s41, 0xc000
	ds_read_b128 v[178:181], v145
	ds_read_b128 v[182:185], v145 offset:1024
	ds_read_b128 v[186:189], v145 offset:2048
	ds_read_b128 v[190:193], v145 offset:3072
	ds_read_b128 v[194:197], v145 offset:4096
	ds_read_b128 v[200:203], v145 offset:5120
	ds_read_b128 v[204:207], v145 offset:6144
	ds_read_b128 v[208:211], v145 offset:7168
	global_load_lds_dwordx4 v[212:213], off
	v_lshl_add_u64 v[212:213], s[28:29], 0, v[140:141]
	s_add_i32 m0, s41, 0xe000
	s_nop 0
	global_load_lds_dwordx4 v[212:213], off
	s_waitcnt vmcnt(8)
	s_waitcnt lgkmcnt(0)
	s_barrier
	s_setprio 1
	s_waitcnt lgkmcnt(0)
	v_mfma_f32_16x16x32_bf16 v[128:131], v[146:149], v[178:181], v[128:131]
	v_mfma_f32_16x16x32_bf16 v[124:127], v[154:157], v[178:181], v[124:127]
	v_mfma_f32_16x16x32_bf16 v[112:115], v[146:149], v[186:189], v[112:115]
	v_mfma_f32_16x16x32_bf16 v[108:111], v[154:157], v[186:189], v[108:111]
	v_mfma_f32_16x16x32_bf16 v[92:95], v[146:149], v[194:197], v[92:95]
	v_mfma_f32_16x16x32_bf16 v[88:91], v[154:157], v[194:197], v[88:91]
	v_mfma_f32_16x16x32_bf16 v[76:79], v[146:149], v[204:207], v[76:79]
	v_mfma_f32_16x16x32_bf16 v[72:75], v[154:157], v[204:207], v[72:75]
	v_mfma_f32_16x16x32_bf16 v[128:131], v[150:153], v[182:185], v[128:131]
	v_mfma_f32_16x16x32_bf16 v[124:127], v[158:161], v[182:185], v[124:127]
	v_mfma_f32_16x16x32_bf16 v[112:115], v[150:153], v[190:193], v[112:115]
	v_mfma_f32_16x16x32_bf16 v[108:111], v[158:161], v[190:193], v[108:111]
	v_mfma_f32_16x16x32_bf16 v[92:95], v[150:153], v[200:203], v[92:95]
	v_mfma_f32_16x16x32_bf16 v[88:91], v[158:161], v[200:203], v[88:91]
	v_mfma_f32_16x16x32_bf16 v[76:79], v[150:153], v[208:211], v[76:79]
	v_mfma_f32_16x16x32_bf16 v[72:75], v[158:161], v[208:211], v[72:75]
	v_mfma_f32_16x16x32_bf16 v[120:123], v[162:165], v[178:181], v[120:123]
	v_mfma_f32_16x16x32_bf16 v[116:119], v[170:173], v[178:181], v[116:119]
	v_mfma_f32_16x16x32_bf16 v[104:107], v[162:165], v[186:189], v[104:107]
	v_mfma_f32_16x16x32_bf16 v[100:103], v[170:173], v[186:189], v[100:103]
	v_mfma_f32_16x16x32_bf16 v[84:87], v[162:165], v[194:197], v[84:87]
	v_mfma_f32_16x16x32_bf16 v[80:83], v[170:173], v[194:197], v[80:83]
	v_mfma_f32_16x16x32_bf16 v[68:71], v[162:165], v[204:207], v[68:71]
	v_mfma_f32_16x16x32_bf16 v[64:67], v[170:173], v[204:207], v[64:67]
	v_mfma_f32_16x16x32_bf16 v[120:123], v[166:169], v[182:185], v[120:123]
	v_mfma_f32_16x16x32_bf16 v[116:119], v[174:177], v[182:185], v[116:119]
	v_mfma_f32_16x16x32_bf16 v[104:107], v[166:169], v[190:193], v[104:107]
	v_mfma_f32_16x16x32_bf16 v[100:103], v[174:177], v[190:193], v[100:103]
	v_mfma_f32_16x16x32_bf16 v[84:87], v[166:169], v[200:203], v[84:87]
	v_mfma_f32_16x16x32_bf16 v[80:83], v[174:177], v[200:203], v[80:83]
	v_mfma_f32_16x16x32_bf16 v[68:71], v[166:169], v[208:211], v[68:71]
	v_mfma_f32_16x16x32_bf16 v[64:67], v[174:177], v[208:211], v[64:67]
	s_setprio 0
	s_barrier
	s_add_i32 s60, s60, s40
	v_lshl_add_u64 v[212:213], s[30:31], 0, v[134:135]
	s_mov_b32 m0, s60
	ds_read_b128 v[178:181], v145 offset:16384
	ds_read_b128 v[182:185], v145 offset:17408
	ds_read_b128 v[186:189], v145 offset:18432
	ds_read_b128 v[190:193], v145 offset:19456
	ds_read_b128 v[194:197], v145 offset:20480
	ds_read_b128 v[200:203], v145 offset:21504
	ds_read_b128 v[204:207], v145 offset:22528
	ds_read_b128 v[208:211], v145 offset:23552
	global_load_lds_dwordx4 v[212:213], off
	s_add_i32 m0, s60, 0x2000
	s_add_u32 s60, s30, 0x40000
	v_lshl_add_u64 v[214:215], s[30:31], 0, v[96:97]
	s_addc_u32 s61, s31, 0
	s_add_i32 s62, s62, s40
	global_load_lds_dwordx4 v[214:215], off
	v_lshl_add_u64 v[216:217], s[60:61], 0, v[134:135]
	s_mov_b32 m0, s62
	v_lshl_add_u64 v[218:219], s[34:35], 0, v[132:133]
	global_load_lds_dwordx4 v[216:217], off
	v_lshl_add_u64 v[216:217], s[60:61], 0, v[96:97]
	s_add_i32 m0, s62, 0x2000
	s_nop 0
	global_load_lds_dwordx4 v[216:217], off
	v_lshl_add_u64 v[216:217], s[34:35], 0, v[136:137]
	s_mov_b32 m0, s41
	s_nop 0
	global_load_lds_dwordx4 v[216:217], off
	s_mov_b32 m0, s42
	s_nop 0
	global_load_lds_dwordx4 v[218:219], off
	s_waitcnt vmcnt(8)
	s_waitcnt lgkmcnt(0)
	s_barrier
; #define PG8_STAGE(bufoff, gbase, voff) do { _Pragma("unroll") for (int _i = 0; _i < 2; ++_i) \
;         __builtin_amdgcn_global_load_lds((const unsigned*)((const char*)(gbase) + (voff)[_i]), (PG8_LAS unsigned*)(lds + (bufoff) + ldsw + _i * 8192), 16, 0, 0); } while (0)
; #define PG8_LDA(dst, b, h) do { _Pragma("unroll") for (int m = 0; m < 4; ++m) _Pragma("unroll") for (int k = 0; k < 2; ++k) dst[m][k] = *(const PG8_LAS bf16x8*)(lds + PG8_SA(b, h) + aoff + m * 2048 + k * 1024); } while (0)
; #define PG8_LDB(dst, b, h) do { _Pragma("unroll") for (int n = 0; n < 2; ++n) _Pragma("unroll") for (int k = 0; k < 2; ++k) dst[n][k] = *(const PG8_LAS bf16x8*)(lds + PG8_SB(b, h) + boff + n * 2048 + k * 1024); } while (0)
; #define PG8_MMA(ai, bj, At, Bt) do { __builtin_amdgcn_s_setprio(1); _Pragma("unroll") for (int m = 0; m < 4; ++m) _Pragma("unroll") for (int n = 0; n < 2; ++n) _Pragma("unroll") for (int k = 0; k < 2; ++k) \
;         acc[ai][bj][m][n] = __builtin_amdgcn_mfma_f32_16x16x32_bf16(Bt[n][k], At[m][k], acc[ai][bj][m][n], 0, 0, 0); __builtin_amdgcn_s_setprio(0); } while (0)
; #define PG8_WAIT_V(n) asm volatile("s_waitcnt vmcnt(" #n ")" ::: "memory")
; #define PG8_WAIT_L(n) asm volatile("s_waitcnt lgkmcnt(" #n ")" ::: "memory")
; #define PG8_BAR __builtin_amdgcn_s_barrier()
; #define PG8_SCHED __builtin_amdgcn_sched_barrier(0)
; template <class Epi, class Sched, bool ALIGN_EPI = false, bool SP2 = false>
; __device__ __forceinline__ void gemm_phase(PG8_LAS unsigned char* lds, const Gemm g, const Sched& S, const Epi& E, const int tid_in) {
;     ...
;             PG8_WAIT_V(8); PG8_WAIT_L(0); PG8_BAR; PG8_MMA(1, 0, At, B0); PG8_MMA(1, 1, At, B1); PG8_BAR; PG8_SCHED;
;             PG8_LDB(B0, 1, 0); PG8_LDB(B1, 1, 1); PG8_SCHED; PG8_LDA(At, 1, 0); PG8_STAGE(PG8_SA(0, 1), a2 + hstepA, voffA);
;             PG8_WAIT_V(8); PG8_WAIT_L(0); PG8_BAR; PG8_MMA(0, 0, At, B0); PG8_MMA(0, 1, At, B1); PG8_BAR; PG8_SCHED;
	s_setprio 1
	s_waitcnt lgkmcnt(0)
	v_mfma_f32_16x16x32_bf16 v[60:63], v[146:149], v[178:181], v[60:63]
	v_mfma_f32_16x16x32_bf16 v[56:59], v[154:157], v[178:181], v[56:59]
	v_mfma_f32_16x16x32_bf16 v[52:55], v[146:149], v[186:189], v[52:55]
	v_mfma_f32_16x16x32_bf16 v[44:47], v[154:157], v[186:189], v[44:47]
	v_mfma_f32_16x16x32_bf16 v[36:39], v[146:149], v[194:197], v[36:39]
	v_mfma_f32_16x16x32_bf16 v[28:31], v[154:157], v[194:197], v[28:31]
	v_mfma_f32_16x16x32_bf16 v[20:23], v[146:149], v[204:207], v[20:23]
	v_mfma_f32_16x16x32_bf16 v[12:15], v[154:157], v[204:207], v[12:15]
	v_mfma_f32_16x16x32_bf16 v[60:63], v[150:153], v[182:185], v[60:63]
	v_mfma_f32_16x16x32_bf16 v[56:59], v[158:161], v[182:185], v[56:59]
	v_mfma_f32_16x16x32_bf16 v[52:55], v[150:153], v[190:193], v[52:55]
	v_mfma_f32_16x16x32_bf16 v[44:47], v[158:161], v[190:193], v[44:47]
	v_mfma_f32_16x16x32_bf16 v[36:39], v[150:153], v[200:203], v[36:39]
	v_mfma_f32_16x16x32_bf16 v[28:31], v[158:161], v[200:203], v[28:31]
	v_mfma_f32_16x16x32_bf16 v[20:23], v[150:153], v[208:211], v[20:23]
	v_mfma_f32_16x16x32_bf16 v[12:15], v[158:161], v[208:211], v[12:15]
	v_mfma_f32_16x16x32_bf16 v[48:51], v[162:165], v[178:181], v[48:51]
	v_mfma_f32_16x16x32_bf16 v[40:43], v[170:173], v[178:181], v[40:43]
	v_mfma_f32_16x16x32_bf16 v[32:35], v[162:165], v[186:189], v[32:35]
	v_mfma_f32_16x16x32_bf16 v[24:27], v[170:173], v[186:189], v[24:27]
	v_mfma_f32_16x16x32_bf16 v[16:19], v[162:165], v[194:197], v[16:19]
	v_mfma_f32_16x16x32_bf16 v[8:11], v[170:173], v[194:197], v[8:11]
	v_mfma_f32_16x16x32_bf16 v[4:7], v[162:165], v[204:207], v[4:7]
	v_mfma_f32_16x16x32_bf16 v[0:3], v[170:173], v[204:207], v[0:3]
	v_mfma_f32_16x16x32_bf16 v[48:51], v[166:169], v[182:185], v[48:51]
	v_mfma_f32_16x16x32_bf16 v[40:43], v[174:177], v[182:185], v[40:43]
	v_mfma_f32_16x16x32_bf16 v[32:35], v[166:169], v[190:193], v[32:35]
	v_mfma_f32_16x16x32_bf16 v[24:27], v[174:177], v[190:193], v[24:27]
	v_mfma_f32_16x16x32_bf16 v[16:19], v[166:169], v[200:203], v[16:19]
	v_mfma_f32_16x16x32_bf16 v[8:11], v[174:177], v[200:203], v[8:11]
	v_mfma_f32_16x16x32_bf16 v[4:7], v[166:169], v[208:211], v[4:7]
	v_mfma_f32_16x16x32_bf16 v[0:3], v[174:177], v[208:211], v[0:3]
	s_setprio 0
	s_barrier
	s_add_i32 s60, 0, 0x18000
	v_add_u32_e32 v142, s60, v143
	s_add_i32 s61, 0, 0x1c000
	ds_read_b128 v[146:149], v142
	ds_read_b128 v[150:153], v142 offset:1024
	ds_read_b128 v[154:157], v142 offset:2048
	ds_read_b128 v[158:161], v142 offset:3072
	v_add_u32_e32 v142, s61, v143
	ds_read_b128 v[162:165], v142
	ds_read_b128 v[166:169], v142 offset:1024
	ds_read_b128 v[170:173], v142 offset:2048
	ds_read_b128 v[174:177], v142 offset:3072
	s_add_u32 s34, s34, 0x40000
	s_addc_u32 s35, s35, 0
	s_mov_b32 m0, s43
	v_lshl_add_u64 v[220:221], s[34:35], 0, v[136:137]
	ds_read_b128 v[178:181], v145 offset:32768
	ds_read_b128 v[182:185], v145 offset:33792
	ds_read_b128 v[186:189], v145 offset:34816
	ds_read_b128 v[190:193], v145 offset:35840
	ds_read_b128 v[194:197], v145 offset:36864
	ds_read_b128 v[200:203], v145 offset:37888
	ds_read_b128 v[204:207], v145 offset:38912
	ds_read_b128 v[208:211], v145 offset:39936
	global_load_lds_dwordx4 v[220:221], off
	v_lshl_add_u64 v[220:221], s[34:35], 0, v[132:133]
	s_mov_b32 m0, s44
	s_nop 0
	global_load_lds_dwordx4 v[220:221], off
	s_waitcnt vmcnt(8)
	s_waitcnt lgkmcnt(0)
	s_barrier
	s_setprio 1
	s_waitcnt lgkmcnt(0)
	v_mfma_f32_16x16x32_bf16 v[128:131], v[146:149], v[178:181], v[128:131]
	v_mfma_f32_16x16x32_bf16 v[124:127], v[154:157], v[178:181], v[124:127]
	v_mfma_f32_16x16x32_bf16 v[112:115], v[146:149], v[186:189], v[112:115]
	v_mfma_f32_16x16x32_bf16 v[108:111], v[154:157], v[186:189], v[108:111]
	v_mfma_f32_16x16x32_bf16 v[92:95], v[146:149], v[194:197], v[92:95]
	v_mfma_f32_16x16x32_bf16 v[88:91], v[154:157], v[194:197], v[88:91]
	v_mfma_f32_16x16x32_bf16 v[76:79], v[146:149], v[204:207], v[76:79]
	v_mfma_f32_16x16x32_bf16 v[72:75], v[154:157], v[204:207], v[72:75]
	v_mfma_f32_16x16x32_bf16 v[128:131], v[150:153], v[182:185], v[128:131]
	v_mfma_f32_16x16x32_bf16 v[124:127], v[158:161], v[182:185], v[124:127]
	v_mfma_f32_16x16x32_bf16 v[112:115], v[150:153], v[190:193], v[112:115]
	v_mfma_f32_16x16x32_bf16 v[108:111], v[158:161], v[190:193], v[108:111]
	v_mfma_f32_16x16x32_bf16 v[92:95], v[150:153], v[200:203], v[92:95]
	v_mfma_f32_16x16x32_bf16 v[88:91], v[158:161], v[200:203], v[88:91]
	v_mfma_f32_16x16x32_bf16 v[76:79], v[150:153], v[208:211], v[76:79]
	v_mfma_f32_16x16x32_bf16 v[72:75], v[158:161], v[208:211], v[72:75]
	v_mfma_f32_16x16x32_bf16 v[120:123], v[162:165], v[178:181], v[120:123]
	v_mfma_f32_16x16x32_bf16 v[116:119], v[170:173], v[178:181], v[116:119]
	v_mfma_f32_16x16x32_bf16 v[104:107], v[162:165], v[186:189], v[104:107]
	v_mfma_f32_16x16x32_bf16 v[100:103], v[170:173], v[186:189], v[100:103]
	v_mfma_f32_16x16x32_bf16 v[84:87], v[162:165], v[194:197], v[84:87]
	v_mfma_f32_16x16x32_bf16 v[80:83], v[170:173], v[194:197], v[80:83]
	v_mfma_f32_16x16x32_bf16 v[68:71], v[162:165], v[204:207], v[68:71]
	v_mfma_f32_16x16x32_bf16 v[64:67], v[170:173], v[204:207], v[64:67]
	v_mfma_f32_16x16x32_bf16 v[120:123], v[166:169], v[182:185], v[120:123]
	v_mfma_f32_16x16x32_bf16 v[116:119], v[174:177], v[182:185], v[116:119]
	v_mfma_f32_16x16x32_bf16 v[104:107], v[166:169], v[190:193], v[104:107]
	v_mfma_f32_16x16x32_bf16 v[100:103], v[174:177], v[190:193], v[100:103]
	v_mfma_f32_16x16x32_bf16 v[84:87], v[166:169], v[200:203], v[84:87]
	v_mfma_f32_16x16x32_bf16 v[80:83], v[174:177], v[200:203], v[80:83]
	v_mfma_f32_16x16x32_bf16 v[68:71], v[166:169], v[208:211], v[68:71]
	v_mfma_f32_16x16x32_bf16 v[64:67], v[174:177], v[208:211], v[64:67]
	s_setprio 0
	s_barrier
; #define PG8_STAGE(bufoff, gbase, voff) do { _Pragma("unroll") for (int _i = 0; _i < 2; ++_i) \
;         __builtin_amdgcn_global_load_lds((const unsigned*)((const char*)(gbase) + (voff)[_i]), (PG8_LAS unsigned*)(lds + (bufoff) + ldsw + _i * 8192), 16, 0, 0); } while (0)
; #define PG8_LDA(dst, b, h) do { _Pragma("unroll") for (int m = 0; m < 4; ++m) _Pragma("unroll") for (int k = 0; k < 2; ++k) dst[m][k] = *(const PG8_LAS bf16x8*)(lds + PG8_SA(b, h) + aoff + m * 2048 + k * 1024); } while (0)
; #define PG8_MMA(ai, bj, At, Bt) do { __builtin_amdgcn_s_setprio(1); _Pragma("unroll") for (int m = 0; m < 4; ++m) _Pragma("unroll") for (int n = 0; n < 2; ++n) _Pragma("unroll") for (int k = 0; k < 2; ++k) \
;         acc[ai][bj][m][n] = __builtin_amdgcn_mfma_f32_16x16x32_bf16(Bt[n][k], At[m][k], acc[ai][bj][m][n], 0, 0, 0); __builtin_amdgcn_s_setprio(0); } while (0)
; #define PG8_WAIT_V(n) asm volatile("s_waitcnt vmcnt(" #n ")" ::: "memory")
; #define PG8_WAIT_L(n) asm volatile("s_waitcnt lgkmcnt(" #n ")" ::: "memory")
; #define PG8_BAR __builtin_amdgcn_s_barrier()
; #define PG8_SCHED __builtin_amdgcn_sched_barrier(0)
; template <class Epi, class Sched, bool ALIGN_EPI = false, bool SP2 = false>
; __device__ __forceinline__ void gemm_phase(PG8_LAS unsigned char* lds, const Gemm g, const Sched& S, const Epi& E, const int tid_in) {
;     ...
;             PG8_LDA(At, 1, 1); PG8_STAGE(PG8_SB(1, 0), b3, voffB); PG8_STAGE(PG8_SB(1, 1), b3 + hstepB, voffB); PG8_STAGE(PG8_SA(1, 0), a3, voffA);
;             PG8_WAIT_V(8); PG8_WAIT_L(0); PG8_BAR; PG8_MMA(1, 0, At, B0); PG8_MMA(1, 1, At, B1); PG8_BAR; PG8_SCHED;
;     ...
;         if constexpr (ALIGN_EPI) { if (wr == 0) PG8_BAR; }
	s_add_i32 s34, s60, s40
	v_lshl_add_u64 v[212:213], v[212:213], 0, s[50:51]
	s_mov_b32 m0, s34
	ds_read_b128 v[178:181], v145 offset:49152
	ds_read_b128 v[182:185], v145 offset:50176
	ds_read_b128 v[186:189], v145 offset:51200
	ds_read_b128 v[190:193], v145 offset:52224
	ds_read_b128 v[194:197], v145 offset:53248
	ds_read_b128 v[200:203], v145 offset:54272
	ds_read_b128 v[204:207], v145 offset:55296
	ds_read_b128 v[208:211], v145 offset:56320
	global_load_lds_dwordx4 v[212:213], off
	s_add_i32 m0, s34, 0x2000
	s_add_u32 s30, s30, 0x40080
	v_lshl_add_u64 v[212:213], v[214:215], 0, s[50:51]
	s_addc_u32 s31, s31, 0
	s_add_i32 s34, s61, s40
	global_load_lds_dwordx4 v[212:213], off
	v_lshl_add_u64 v[212:213], s[30:31], 0, v[134:135]
	s_mov_b32 m0, s34
	s_nop 0
	global_load_lds_dwordx4 v[212:213], off
	v_lshl_add_u64 v[212:213], s[30:31], 0, v[96:97]
	s_add_i32 m0, s34, 0x2000
	s_nop 0
	global_load_lds_dwordx4 v[212:213], off
	v_lshl_add_u64 v[212:213], v[216:217], 0, s[50:51]
	s_mov_b32 m0, s46
	s_nop 0
	global_load_lds_dwordx4 v[212:213], off
	v_lshl_add_u64 v[212:213], v[218:219], 0, s[50:51]
	s_mov_b32 m0, s47
	s_nop 0
	global_load_lds_dwordx4 v[212:213], off
	s_waitcnt vmcnt(8)
	s_waitcnt lgkmcnt(0)
	s_barrier
	s_setprio 1
	s_waitcnt lgkmcnt(0)
	v_mfma_f32_16x16x32_bf16 v[60:63], v[146:149], v[178:181], v[60:63]
	v_mfma_f32_16x16x32_bf16 v[56:59], v[154:157], v[178:181], v[56:59]
	v_mfma_f32_16x16x32_bf16 v[52:55], v[146:149], v[186:189], v[52:55]
	v_mfma_f32_16x16x32_bf16 v[44:47], v[154:157], v[186:189], v[44:47]
	v_mfma_f32_16x16x32_bf16 v[36:39], v[146:149], v[194:197], v[36:39]
	v_mfma_f32_16x16x32_bf16 v[28:31], v[154:157], v[194:197], v[28:31]
	v_mfma_f32_16x16x32_bf16 v[20:23], v[146:149], v[204:207], v[20:23]
	v_mfma_f32_16x16x32_bf16 v[12:15], v[154:157], v[204:207], v[12:15]
	v_mfma_f32_16x16x32_bf16 v[60:63], v[150:153], v[182:185], v[60:63]
	v_mfma_f32_16x16x32_bf16 v[56:59], v[158:161], v[182:185], v[56:59]
	v_mfma_f32_16x16x32_bf16 v[52:55], v[150:153], v[190:193], v[52:55]
	v_mfma_f32_16x16x32_bf16 v[44:47], v[158:161], v[190:193], v[44:47]
	v_mfma_f32_16x16x32_bf16 v[36:39], v[150:153], v[200:203], v[36:39]
	v_mfma_f32_16x16x32_bf16 v[28:31], v[158:161], v[200:203], v[28:31]
	v_mfma_f32_16x16x32_bf16 v[20:23], v[150:153], v[208:211], v[20:23]
	v_mfma_f32_16x16x32_bf16 v[12:15], v[158:161], v[208:211], v[12:15]
	v_mfma_f32_16x16x32_bf16 v[48:51], v[162:165], v[178:181], v[48:51]
	v_mfma_f32_16x16x32_bf16 v[40:43], v[170:173], v[178:181], v[40:43]
	v_mfma_f32_16x16x32_bf16 v[32:35], v[162:165], v[186:189], v[32:35]
	v_mfma_f32_16x16x32_bf16 v[24:27], v[170:173], v[186:189], v[24:27]
	v_mfma_f32_16x16x32_bf16 v[16:19], v[162:165], v[194:197], v[16:19]
	v_mfma_f32_16x16x32_bf16 v[8:11], v[170:173], v[194:197], v[8:11]
	v_mfma_f32_16x16x32_bf16 v[4:7], v[162:165], v[204:207], v[4:7]
	v_mfma_f32_16x16x32_bf16 v[0:3], v[170:173], v[204:207], v[0:3]
	v_mfma_f32_16x16x32_bf16 v[48:51], v[166:169], v[182:185], v[48:51]
	v_mfma_f32_16x16x32_bf16 v[40:43], v[174:177], v[182:185], v[40:43]
	v_mfma_f32_16x16x32_bf16 v[32:35], v[166:169], v[190:193], v[32:35]
	v_mfma_f32_16x16x32_bf16 v[24:27], v[174:177], v[190:193], v[24:27]
	v_mfma_f32_16x16x32_bf16 v[16:19], v[166:169], v[200:203], v[16:19]
	v_mfma_f32_16x16x32_bf16 v[8:11], v[174:177], v[200:203], v[8:11]
	v_mfma_f32_16x16x32_bf16 v[4:7], v[166:169], v[208:211], v[4:7]
	v_mfma_f32_16x16x32_bf16 v[0:3], v[174:177], v[208:211], v[0:3]
	s_setprio 0
	s_barrier
	s_add_i32 s57, s57, 2
	s_add_u32 s28, s28, 0x100
	s_addc_u32 s29, s29, 0
	s_add_u32 s55, s55, 0x100
	s_addc_u32 s56, s56, 0
	s_cmp_gt_u32 s57, 13
	s_cbranch_scc0 .LBB0_849
	s_and_b64 vcc, exec, s[18:19]
	s_cbranch_vccz .LBB0_852
	s_barrier

; #define PG8_STAGE(bufoff, gbase, voff) do { _Pragma("unroll") for (int _i = 0; _i < 2; ++_i) \
;         __builtin_amdgcn_global_load_lds((const unsigned*)((const char*)(gbase) + (voff)[_i]), (PG8_LAS unsigned*)(lds + (bufoff) + ldsw + _i * 8192), 16, 0, 0); } while (0)
; #define PG8_LDA(dst, b, h) do { _Pragma("unroll") for (int m = 0; m < 4; ++m) _Pragma("unroll") for (int k = 0; k < 2; ++k) dst[m][k] = *(const PG8_LAS bf16x8*)(lds + PG8_SA(b, h) + aoff + m * 2048 + k * 1024); } while (0)
; #define PG8_LDB(dst, b, h) do { _Pragma("unroll") for (int n = 0; n < 2; ++n) _Pragma("unroll") for (int k = 0; k < 2; ++k) dst[n][k] = *(const PG8_LAS bf16x8*)(lds + PG8_SB(b, h) + boff + n * 2048 + k * 1024); } while (0)
; #define PG8_MMA(ai, bj, At, Bt) do { __builtin_amdgcn_s_setprio(1); _Pragma("unroll") for (int m = 0; m < 4; ++m) _Pragma("unroll") for (int n = 0; n < 2; ++n) _Pragma("unroll") for (int k = 0; k < 2; ++k) \
;         acc[ai][bj][m][n] = __builtin_amdgcn_mfma_f32_16x16x32_bf16(Bt[n][k], At[m][k], acc[ai][bj][m][n], 0, 0, 0); __builtin_amdgcn_s_setprio(0); } while (0)
; #define PG8_WAIT_V(n) asm volatile("s_waitcnt vmcnt(" #n ")" ::: "memory")
; #define PG8_WAIT_L(n) asm volatile("s_waitcnt lgkmcnt(" #n ")" ::: "memory")
; #define PG8_BAR __builtin_amdgcn_s_barrier()
; #define PG8_SCHED __builtin_amdgcn_sched_barrier(0)
; template <class Epi, class Sched, bool ALIGN_EPI = false, bool SP2 = false>
; __device__ __forceinline__ void gemm_phase(PG8_LAS unsigned char* lds, const Gemm g, const Sched& S, const Epi& E, const int tid_in) {
;     ...
;             const bool last = (t == nt - 2);
;             const char* a1 = cA + (size_t)(t + 1) * kstep;
;             const char* a2 = last ? nA : cA + (size_t)(t + 2) * kstep; const char* b2 = last ? nB : cB + (size_t)(t + 2) * kstep;
;             const char* a3 = a2 + kstep; const char* b3 = b2 + kstep;
;             if (last && has_next) S.a_ready(nxt);
;             if constexpr (SP2) {
;             PG8_LDB(B0, 0, 0); PG8_LDB(B1, 0, 1); PG8_SCHED; PG8_LDA(At, 0, 0); PG8_STAGE(PG8_SA(1, 1), a1 + hstepA, voffA);
;             PG8_WAIT_V(8); PG8_WAIT_L(0); PG8_BAR; PG8_MMA(0, 0, At, B0); PG8_MMA(0, 1, At, B1); PG8_BAR; PG8_SCHED;
;             PG8_LDA(At, 0, 1); PG8_STAGE(PG8_SB(0, 0), b2, voffB); PG8_STAGE(PG8_SB(0, 1), b2 + hstepB, voffB); PG8_STAGE(PG8_SA(0, 0), a2, voffA);
.LBB0_988:
	s_add_u32 s20, s18, 0x100
	s_addc_u32 s21, s19, 0
	s_add_i32 s52, 0, 0x10000
	s_cmp_eq_u32 s49, 40
	s_cselect_b32 s25, s1, s21
	s_cselect_b32 s24, s0, s20
	s_cselect_b32 s23, s17, s48
	s_cselect_b32 s22, s16, s47
	s_add_i32 s53, 0, 0x14000
	v_add_u32_e32 v150, s52, v182
	v_add_u32_e32 v166, s53, v182
	ds_read_b128 v[138:141], v150
	ds_read_b128 v[142:145], v150 offset:1024
	ds_read_b128 v[146:149], v150 offset:2048
	ds_read_b128 v[150:153], v150 offset:3072
	ds_read_b128 v[154:157], v166
	ds_read_b128 v[158:161], v166 offset:1024
	ds_read_b128 v[162:165], v166 offset:2048
	ds_read_b128 v[166:169], v166 offset:3072
	v_lshl_add_u64 v[196:197], s[18:19], 0, v[134:135]
	s_add_i32 m0, s31, 0xc000
	ds_read_b128 v[170:173], v183
	ds_read_b128 v[174:177], v183 offset:1024
	ds_read_b128 v[178:181], v183 offset:2048
	ds_read_b128 v[184:187], v183 offset:3072
	ds_read_b128 v[188:191], v183 offset:4096
	ds_read_b128 v[192:195], v183 offset:5120
	ds_read_b128 v[200:203], v183 offset:6144
	ds_read_b128 v[204:207], v183 offset:7168
	global_load_lds_dwordx4 v[196:197], off
	v_lshl_add_u64 v[196:197], s[18:19], 0, v[136:137]
	s_add_i32 m0, s31, 0xe000
	s_nop 0
	global_load_lds_dwordx4 v[196:197], off
	s_waitcnt vmcnt(8)
	s_waitcnt lgkmcnt(0)
	s_barrier
	s_setprio 1
	s_waitcnt lgkmcnt(0)
	v_mfma_f32_16x16x32_bf16 v[128:131], v[138:141], v[170:173], v[128:131]
	v_mfma_f32_16x16x32_bf16 v[124:127], v[146:149], v[170:173], v[124:127]
	v_mfma_f32_16x16x32_bf16 v[112:115], v[138:141], v[178:181], v[112:115]
	v_mfma_f32_16x16x32_bf16 v[108:111], v[146:149], v[178:181], v[108:111]
	v_mfma_f32_16x16x32_bf16 v[92:95], v[138:141], v[188:191], v[92:95]
	v_mfma_f32_16x16x32_bf16 v[88:91], v[146:149], v[188:191], v[88:91]
	v_mfma_f32_16x16x32_bf16 v[76:79], v[138:141], v[200:203], v[76:79]
	v_mfma_f32_16x16x32_bf16 v[72:75], v[146:149], v[200:203], v[72:75]
	v_mfma_f32_16x16x32_bf16 v[128:131], v[142:145], v[174:177], v[128:131]
	v_mfma_f32_16x16x32_bf16 v[124:127], v[150:153], v[174:177], v[124:127]
	v_mfma_f32_16x16x32_bf16 v[112:115], v[142:145], v[184:187], v[112:115]
	v_mfma_f32_16x16x32_bf16 v[108:111], v[150:153], v[184:187], v[108:111]
	v_mfma_f32_16x16x32_bf16 v[92:95], v[142:145], v[192:195], v[92:95]
	v_mfma_f32_16x16x32_bf16 v[88:91], v[150:153], v[192:195], v[88:91]
	v_mfma_f32_16x16x32_bf16 v[76:79], v[142:145], v[204:207], v[76:79]
	v_mfma_f32_16x16x32_bf16 v[72:75], v[150:153], v[204:207], v[72:75]
	v_mfma_f32_16x16x32_bf16 v[120:123], v[154:157], v[170:173], v[120:123]
	v_mfma_f32_16x16x32_bf16 v[116:119], v[162:165], v[170:173], v[116:119]
	v_mfma_f32_16x16x32_bf16 v[104:107], v[154:157], v[178:181], v[104:107]
	v_mfma_f32_16x16x32_bf16 v[100:103], v[162:165], v[178:181], v[100:103]
	v_mfma_f32_16x16x32_bf16 v[84:87], v[154:157], v[188:191], v[84:87]
	v_mfma_f32_16x16x32_bf16 v[80:83], v[162:165], v[188:191], v[80:83]
	v_mfma_f32_16x16x32_bf16 v[68:71], v[154:157], v[200:203], v[68:71]
	v_mfma_f32_16x16x32_bf16 v[64:67], v[162:165], v[200:203], v[64:67]
	v_mfma_f32_16x16x32_bf16 v[120:123], v[158:161], v[174:177], v[120:123]
	v_mfma_f32_16x16x32_bf16 v[116:119], v[166:169], v[174:177], v[116:119]
	v_mfma_f32_16x16x32_bf16 v[104:107], v[158:161], v[184:187], v[104:107]
	v_mfma_f32_16x16x32_bf16 v[100:103], v[166:169], v[184:187], v[100:103]
	v_mfma_f32_16x16x32_bf16 v[84:87], v[158:161], v[192:195], v[84:87]
	v_mfma_f32_16x16x32_bf16 v[80:83], v[166:169], v[192:195], v[80:83]
	v_mfma_f32_16x16x32_bf16 v[68:71], v[158:161], v[204:207], v[68:71]
	v_mfma_f32_16x16x32_bf16 v[64:67], v[166:169], v[204:207], v[64:67]
	s_setprio 0
	s_barrier
	s_add_i32 s18, s52, s30
	v_lshl_add_u64 v[196:197], s[22:23], 0, v[132:133]
	s_mov_b32 m0, s18
	ds_read_b128 v[170:173], v183 offset:16384
	ds_read_b128 v[174:177], v183 offset:17408
	ds_read_b128 v[178:181], v183 offset:18432
	ds_read_b128 v[184:187], v183 offset:19456
	ds_read_b128 v[188:191], v183 offset:20480
	ds_read_b128 v[192:195], v183 offset:21504
	ds_read_b128 v[200:203], v183 offset:22528
	ds_read_b128 v[204:207], v183 offset:23552
	global_load_lds_dwordx4 v[196:197], off
	s_add_i32 m0, s18, 0x2000
	s_add_u32 s18, s22, 0xb0000
	v_lshl_add_u64 v[208:209], s[22:23], 0, v[96:97]
	s_addc_u32 s19, s23, 0
	s_add_i32 s52, s53, s30
	global_load_lds_dwordx4 v[208:209], off
	v_lshl_add_u64 v[210:211], s[18:19], 0, v[132:133]
	s_mov_b32 m0, s52
	v_lshl_add_u64 v[212:213], s[24:25], 0, v[96:97]
	global_load_lds_dwordx4 v[210:211], off
	v_lshl_add_u64 v[210:211], s[18:19], 0, v[96:97]
	s_add_i32 m0, s52, 0x2000
	s_nop 0
	global_load_lds_dwordx4 v[210:211], off
	v_lshl_add_u64 v[210:211], s[24:25], 0, v[132:133]
	s_mov_b32 m0, s31
	s_nop 0
	global_load_lds_dwordx4 v[210:211], off
	s_mov_b32 m0, s34
	s_nop 0
	global_load_lds_dwordx4 v[212:213], off
	s_waitcnt vmcnt(8)
	s_waitcnt lgkmcnt(0)
	s_barrier
; #define PG8_STAGE(bufoff, gbase, voff) do { _Pragma("unroll") for (int _i = 0; _i < 2; ++_i) \
;         __builtin_amdgcn_global_load_lds((const unsigned*)((const char*)(gbase) + (voff)[_i]), (PG8_LAS unsigned*)(lds + (bufoff) + ldsw + _i * 8192), 16, 0, 0); } while (0)
; #define PG8_LDA(dst, b, h) do { _Pragma("unroll") for (int m = 0; m < 4; ++m) _Pragma("unroll") for (int k = 0; k < 2; ++k) dst[m][k] = *(const PG8_LAS bf16x8*)(lds + PG8_SA(b, h) + aoff + m * 2048 + k * 1024); } while (0)
; #define PG8_LDB(dst, b, h) do { _Pragma("unroll") for (int n = 0; n < 2; ++n) _Pragma("unroll") for (int k = 0; k < 2; ++k) dst[n][k] = *(const PG8_LAS bf16x8*)(lds + PG8_SB(b, h) + boff + n * 2048 + k * 1024); } while (0)
; #define PG8_MMA(ai, bj, At, Bt) do { __builtin_amdgcn_s_setprio(1); _Pragma("unroll") for (int m = 0; m < 4; ++m) _Pragma("unroll") for (int n = 0; n < 2; ++n) _Pragma("unroll") for (int k = 0; k < 2; ++k) \
;         acc[ai][bj][m][n] = __builtin_amdgcn_mfma_f32_16x16x32_bf16(Bt[n][k], At[m][k], acc[ai][bj][m][n], 0, 0, 0); __builtin_amdgcn_s_setprio(0); } while (0)
; #define PG8_WAIT_V(n) asm volatile("s_waitcnt vmcnt(" #n ")" ::: "memory")
; #define PG8_WAIT_L(n) asm volatile("s_waitcnt lgkmcnt(" #n ")" ::: "memory")
; #define PG8_BAR __builtin_amdgcn_s_barrier()
; #define PG8_SCHED __builtin_amdgcn_sched_barrier(0)
; template <class Epi, class Sched, bool ALIGN_EPI = false, bool SP2 = false>
; __device__ __forceinline__ void gemm_phase(PG8_LAS unsigned char* lds, const Gemm g, const Sched& S, const Epi& E, const int tid_in) {
;     ...
;             PG8_WAIT_V(8); PG8_WAIT_L(0); PG8_BAR; PG8_MMA(1, 0, At, B0); PG8_MMA(1, 1, At, B1); PG8_BAR; PG8_SCHED;
;             PG8_LDB(B0, 1, 0); PG8_LDB(B1, 1, 1); PG8_SCHED; PG8_LDA(At, 1, 0); PG8_STAGE(PG8_SA(0, 1), a2 + hstepA, voffA);
;             PG8_WAIT_V(8); PG8_WAIT_L(0); PG8_BAR; PG8_MMA(0, 0, At, B0); PG8_MMA(0, 1, At, B1); PG8_BAR; PG8_SCHED;
	s_setprio 1
	s_waitcnt lgkmcnt(0)
	v_mfma_f32_16x16x32_bf16 v[60:63], v[138:141], v[170:173], v[60:63]
	v_mfma_f32_16x16x32_bf16 v[56:59], v[146:149], v[170:173], v[56:59]
	v_mfma_f32_16x16x32_bf16 v[44:47], v[138:141], v[178:181], v[44:47]
	v_mfma_f32_16x16x32_bf16 v[40:43], v[146:149], v[178:181], v[40:43]
	v_mfma_f32_16x16x32_bf16 v[28:31], v[138:141], v[188:191], v[28:31]
	v_mfma_f32_16x16x32_bf16 v[24:27], v[146:149], v[188:191], v[24:27]
	v_mfma_f32_16x16x32_bf16 v[12:15], v[138:141], v[200:203], v[12:15]
	v_mfma_f32_16x16x32_bf16 v[8:11], v[146:149], v[200:203], v[8:11]
	v_mfma_f32_16x16x32_bf16 v[60:63], v[142:145], v[174:177], v[60:63]
	v_mfma_f32_16x16x32_bf16 v[56:59], v[150:153], v[174:177], v[56:59]
	v_mfma_f32_16x16x32_bf16 v[44:47], v[142:145], v[184:187], v[44:47]
	v_mfma_f32_16x16x32_bf16 v[40:43], v[150:153], v[184:187], v[40:43]
	v_mfma_f32_16x16x32_bf16 v[28:31], v[142:145], v[192:195], v[28:31]
	v_mfma_f32_16x16x32_bf16 v[24:27], v[150:153], v[192:195], v[24:27]
	v_mfma_f32_16x16x32_bf16 v[12:15], v[142:145], v[204:207], v[12:15]
	v_mfma_f32_16x16x32_bf16 v[8:11], v[150:153], v[204:207], v[8:11]
	v_mfma_f32_16x16x32_bf16 v[52:55], v[154:157], v[170:173], v[52:55]
	v_mfma_f32_16x16x32_bf16 v[48:51], v[162:165], v[170:173], v[48:51]
	v_mfma_f32_16x16x32_bf16 v[36:39], v[154:157], v[178:181], v[36:39]
	v_mfma_f32_16x16x32_bf16 v[32:35], v[162:165], v[178:181], v[32:35]
	v_mfma_f32_16x16x32_bf16 v[20:23], v[154:157], v[188:191], v[20:23]
	v_mfma_f32_16x16x32_bf16 v[16:19], v[162:165], v[188:191], v[16:19]
	v_mfma_f32_16x16x32_bf16 v[4:7], v[154:157], v[200:203], v[4:7]
	v_mfma_f32_16x16x32_bf16 v[0:3], v[162:165], v[200:203], v[0:3]
	v_mfma_f32_16x16x32_bf16 v[52:55], v[158:161], v[174:177], v[52:55]
	v_mfma_f32_16x16x32_bf16 v[48:51], v[166:169], v[174:177], v[48:51]
	v_mfma_f32_16x16x32_bf16 v[36:39], v[158:161], v[184:187], v[36:39]
	v_mfma_f32_16x16x32_bf16 v[32:35], v[166:169], v[184:187], v[32:35]
	v_mfma_f32_16x16x32_bf16 v[20:23], v[158:161], v[192:195], v[20:23]
	v_mfma_f32_16x16x32_bf16 v[16:19], v[166:169], v[192:195], v[16:19]
	v_mfma_f32_16x16x32_bf16 v[4:7], v[158:161], v[204:207], v[4:7]
	v_mfma_f32_16x16x32_bf16 v[0:3], v[166:169], v[204:207], v[0:3]
	s_setprio 0
	s_barrier
	s_add_i32 s52, 0, 0x18000
	s_add_i32 s53, 0, 0x1c000
	v_add_u32_e32 v150, s52, v182
	v_add_u32_e32 v166, s53, v182
	ds_read_b128 v[138:141], v150
	ds_read_b128 v[142:145], v150 offset:1024
	ds_read_b128 v[146:149], v150 offset:2048
	ds_read_b128 v[150:153], v150 offset:3072
	ds_read_b128 v[154:157], v166
	ds_read_b128 v[158:161], v166 offset:1024
	ds_read_b128 v[162:165], v166 offset:2048
	ds_read_b128 v[166:169], v166 offset:3072
	s_add_u32 s18, s24, 0xb0000
	s_addc_u32 s19, s25, 0
	s_mov_b32 m0, s35
	v_lshl_add_u64 v[214:215], s[18:19], 0, v[132:133]
	ds_read_b128 v[170:173], v183 offset:32768
	ds_read_b128 v[174:177], v183 offset:33792
	ds_read_b128 v[178:181], v183 offset:34816
	ds_read_b128 v[184:187], v183 offset:35840
	ds_read_b128 v[188:191], v183 offset:36864
	ds_read_b128 v[192:195], v183 offset:37888
	ds_read_b128 v[200:203], v183 offset:38912
	ds_read_b128 v[204:207], v183 offset:39936
	global_load_lds_dwordx4 v[214:215], off
	v_lshl_add_u64 v[214:215], s[18:19], 0, v[96:97]
	s_mov_b32 m0, s36
	s_nop 0
	global_load_lds_dwordx4 v[214:215], off
	s_waitcnt vmcnt(8)
	s_waitcnt lgkmcnt(0)
	s_barrier
	s_setprio 1
	s_waitcnt lgkmcnt(0)
	v_mfma_f32_16x16x32_bf16 v[128:131], v[138:141], v[170:173], v[128:131]
	v_mfma_f32_16x16x32_bf16 v[124:127], v[146:149], v[170:173], v[124:127]
	v_mfma_f32_16x16x32_bf16 v[112:115], v[138:141], v[178:181], v[112:115]
	v_mfma_f32_16x16x32_bf16 v[108:111], v[146:149], v[178:181], v[108:111]
	v_mfma_f32_16x16x32_bf16 v[92:95], v[138:141], v[188:191], v[92:95]
	v_mfma_f32_16x16x32_bf16 v[88:91], v[146:149], v[188:191], v[88:91]
	v_mfma_f32_16x16x32_bf16 v[76:79], v[138:141], v[200:203], v[76:79]
	v_mfma_f32_16x16x32_bf16 v[72:75], v[146:149], v[200:203], v[72:75]
	v_mfma_f32_16x16x32_bf16 v[128:131], v[142:145], v[174:177], v[128:131]
	v_mfma_f32_16x16x32_bf16 v[124:127], v[150:153], v[174:177], v[124:127]
	v_mfma_f32_16x16x32_bf16 v[112:115], v[142:145], v[184:187], v[112:115]
	v_mfma_f32_16x16x32_bf16 v[108:111], v[150:153], v[184:187], v[108:111]
	v_mfma_f32_16x16x32_bf16 v[92:95], v[142:145], v[192:195], v[92:95]
	v_mfma_f32_16x16x32_bf16 v[88:91], v[150:153], v[192:195], v[88:91]
	v_mfma_f32_16x16x32_bf16 v[76:79], v[142:145], v[204:207], v[76:79]
	v_mfma_f32_16x16x32_bf16 v[72:75], v[150:153], v[204:207], v[72:75]
	v_mfma_f32_16x16x32_bf16 v[120:123], v[154:157], v[170:173], v[120:123]
	v_mfma_f32_16x16x32_bf16 v[116:119], v[162:165], v[170:173], v[116:119]
	v_mfma_f32_16x16x32_bf16 v[104:107], v[154:157], v[178:181], v[104:107]
	v_mfma_f32_16x16x32_bf16 v[100:103], v[162:165], v[178:181], v[100:103]
	v_mfma_f32_16x16x32_bf16 v[84:87], v[154:157], v[188:191], v[84:87]
	v_mfma_f32_16x16x32_bf16 v[80:83], v[162:165], v[188:191], v[80:83]
	v_mfma_f32_16x16x32_bf16 v[68:71], v[154:157], v[200:203], v[68:71]
	v_mfma_f32_16x16x32_bf16 v[64:67], v[162:165], v[200:203], v[64:67]
	v_mfma_f32_16x16x32_bf16 v[120:123], v[158:161], v[174:177], v[120:123]
	v_mfma_f32_16x16x32_bf16 v[116:119], v[166:169], v[174:177], v[116:119]
	v_mfma_f32_16x16x32_bf16 v[104:107], v[158:161], v[184:187], v[104:107]
	v_mfma_f32_16x16x32_bf16 v[100:103], v[166:169], v[184:187], v[100:103]
	v_mfma_f32_16x16x32_bf16 v[84:87], v[158:161], v[192:195], v[84:87]
	v_mfma_f32_16x16x32_bf16 v[80:83], v[166:169], v[192:195], v[80:83]
	v_mfma_f32_16x16x32_bf16 v[68:71], v[158:161], v[204:207], v[68:71]
	v_mfma_f32_16x16x32_bf16 v[64:67], v[166:169], v[204:207], v[64:67]
	s_setprio 0
	s_barrier
; #define PG8_STAGE(bufoff, gbase, voff) do { _Pragma("unroll") for (int _i = 0; _i < 2; ++_i) \
;         __builtin_amdgcn_global_load_lds((const unsigned*)((const char*)(gbase) + (voff)[_i]), (PG8_LAS unsigned*)(lds + (bufoff) + ldsw + _i * 8192), 16, 0, 0); } while (0)
; #define PG8_LDA(dst, b, h) do { _Pragma("unroll") for (int m = 0; m < 4; ++m) _Pragma("unroll") for (int k = 0; k < 2; ++k) dst[m][k] = *(const PG8_LAS bf16x8*)(lds + PG8_SA(b, h) + aoff + m * 2048 + k * 1024); } while (0)
; #define PG8_MMA(ai, bj, At, Bt) do { __builtin_amdgcn_s_setprio(1); _Pragma("unroll") for (int m = 0; m < 4; ++m) _Pragma("unroll") for (int n = 0; n < 2; ++n) _Pragma("unroll") for (int k = 0; k < 2; ++k) \
;         acc[ai][bj][m][n] = __builtin_amdgcn_mfma_f32_16x16x32_bf16(Bt[n][k], At[m][k], acc[ai][bj][m][n], 0, 0, 0); __builtin_amdgcn_s_setprio(0); } while (0)
; #define PG8_WAIT_V(n) asm volatile("s_waitcnt vmcnt(" #n ")" ::: "memory")
; #define PG8_WAIT_L(n) asm volatile("s_waitcnt lgkmcnt(" #n ")" ::: "memory")
; #define PG8_BAR __builtin_amdgcn_s_barrier()
; #define PG8_SCHED __builtin_amdgcn_sched_barrier(0)
; template <class Epi, class Sched, bool ALIGN_EPI = false, bool SP2 = false>
; __device__ __forceinline__ void gemm_phase(PG8_LAS unsigned char* lds, const Gemm g, const Sched& S, const Epi& E, const int tid_in) {
;     ...
;             PG8_LDA(At, 1, 1); PG8_STAGE(PG8_SB(1, 0), b3, voffB); PG8_STAGE(PG8_SB(1, 1), b3 + hstepB, voffB); PG8_STAGE(PG8_SA(1, 0), a3, voffA);
;             PG8_WAIT_V(8); PG8_WAIT_L(0); PG8_BAR; PG8_MMA(1, 0, At, B0); PG8_MMA(1, 1, At, B1); PG8_BAR; PG8_SCHED;
;     ...
;         if constexpr (ALIGN_EPI) { if (wr == 0) PG8_BAR; }
	s_add_i32 s18, s52, s30
	v_lshl_add_u64 v[196:197], v[196:197], 0, s[50:51]
	s_mov_b32 m0, s18
	ds_read_b128 v[170:173], v183 offset:49152
	ds_read_b128 v[174:177], v183 offset:50176
	ds_read_b128 v[178:181], v183 offset:51200
	ds_read_b128 v[184:187], v183 offset:52224
	ds_read_b128 v[188:191], v183 offset:53248
	ds_read_b128 v[192:195], v183 offset:54272
	ds_read_b128 v[200:203], v183 offset:55296
	ds_read_b128 v[204:207], v183 offset:56320
	global_load_lds_dwordx4 v[196:197], off
	s_add_i32 m0, s18, 0x2000
	s_add_u32 s18, s22, 0xb0080
	v_lshl_add_u64 v[196:197], v[208:209], 0, s[50:51]
	s_addc_u32 s19, s23, 0
	s_add_i32 s22, s53, s30
	global_load_lds_dwordx4 v[196:197], off
	v_lshl_add_u64 v[196:197], s[18:19], 0, v[132:133]
	s_mov_b32 m0, s22
	s_nop 0
	global_load_lds_dwordx4 v[196:197], off
	v_lshl_add_u64 v[196:197], s[18:19], 0, v[96:97]
	s_add_i32 m0, s22, 0x2000
	s_nop 0
	global_load_lds_dwordx4 v[196:197], off
	v_lshl_add_u64 v[196:197], v[210:211], 0, s[50:51]
	s_mov_b32 m0, s40
	s_nop 0
	global_load_lds_dwordx4 v[196:197], off
	v_lshl_add_u64 v[196:197], v[212:213], 0, s[50:51]
	s_mov_b32 m0, s41
	s_nop 0
	global_load_lds_dwordx4 v[196:197], off
	s_waitcnt vmcnt(8)
	s_waitcnt lgkmcnt(0)
	s_barrier
	s_setprio 1
	s_waitcnt lgkmcnt(0)
	v_mfma_f32_16x16x32_bf16 v[60:63], v[138:141], v[170:173], v[60:63]
	v_mfma_f32_16x16x32_bf16 v[56:59], v[146:149], v[170:173], v[56:59]
	v_mfma_f32_16x16x32_bf16 v[44:47], v[138:141], v[178:181], v[44:47]
	v_mfma_f32_16x16x32_bf16 v[40:43], v[146:149], v[178:181], v[40:43]
	v_mfma_f32_16x16x32_bf16 v[28:31], v[138:141], v[188:191], v[28:31]
	v_mfma_f32_16x16x32_bf16 v[24:27], v[146:149], v[188:191], v[24:27]
	v_mfma_f32_16x16x32_bf16 v[12:15], v[138:141], v[200:203], v[12:15]
	v_mfma_f32_16x16x32_bf16 v[8:11], v[146:149], v[200:203], v[8:11]
	v_mfma_f32_16x16x32_bf16 v[60:63], v[142:145], v[174:177], v[60:63]
	v_mfma_f32_16x16x32_bf16 v[56:59], v[150:153], v[174:177], v[56:59]
	v_mfma_f32_16x16x32_bf16 v[44:47], v[142:145], v[184:187], v[44:47]
	v_mfma_f32_16x16x32_bf16 v[40:43], v[150:153], v[184:187], v[40:43]
	v_mfma_f32_16x16x32_bf16 v[28:31], v[142:145], v[192:195], v[28:31]
	v_mfma_f32_16x16x32_bf16 v[24:27], v[150:153], v[192:195], v[24:27]
	v_mfma_f32_16x16x32_bf16 v[12:15], v[142:145], v[204:207], v[12:15]
	v_mfma_f32_16x16x32_bf16 v[8:11], v[150:153], v[204:207], v[8:11]
	v_mfma_f32_16x16x32_bf16 v[52:55], v[154:157], v[170:173], v[52:55]
	v_mfma_f32_16x16x32_bf16 v[48:51], v[162:165], v[170:173], v[48:51]
	v_mfma_f32_16x16x32_bf16 v[36:39], v[154:157], v[178:181], v[36:39]
	v_mfma_f32_16x16x32_bf16 v[32:35], v[162:165], v[178:181], v[32:35]
	v_mfma_f32_16x16x32_bf16 v[20:23], v[154:157], v[188:191], v[20:23]
	v_mfma_f32_16x16x32_bf16 v[16:19], v[162:165], v[188:191], v[16:19]
	v_mfma_f32_16x16x32_bf16 v[4:7], v[154:157], v[200:203], v[4:7]
	v_mfma_f32_16x16x32_bf16 v[0:3], v[162:165], v[200:203], v[0:3]
	v_mfma_f32_16x16x32_bf16 v[52:55], v[158:161], v[174:177], v[52:55]
	v_mfma_f32_16x16x32_bf16 v[48:51], v[166:169], v[174:177], v[48:51]
	v_mfma_f32_16x16x32_bf16 v[36:39], v[158:161], v[184:187], v[36:39]
	v_mfma_f32_16x16x32_bf16 v[32:35], v[166:169], v[184:187], v[32:35]
	v_mfma_f32_16x16x32_bf16 v[20:23], v[158:161], v[192:195], v[20:23]
	v_mfma_f32_16x16x32_bf16 v[16:19], v[166:169], v[192:195], v[16:19]
	v_mfma_f32_16x16x32_bf16 v[4:7], v[158:161], v[204:207], v[4:7]
	v_mfma_f32_16x16x32_bf16 v[0:3], v[166:169], v[204:207], v[0:3]
	s_setprio 0
	s_barrier
	s_add_i32 s49, s49, 2
	s_add_u32 s47, s47, 0x100
	s_addc_u32 s48, s48, 0
	s_cmp_gt_u32 s49, 41
	s_mov_b64 s[18:19], s[20:21]
	s_cbranch_scc0 .LBB0_988
	s_and_b64 vcc, exec, s[14:15]
	s_cbranch_vccz .LBB0_991
	s_barrier

; #define PG8_STAGE(bufoff, gbase, voff) do { _Pragma("unroll") for (int _i = 0; _i < 2; ++_i) \
;         __builtin_amdgcn_global_load_lds((const unsigned*)((const char*)(gbase) + (voff)[_i]), (PG8_LAS unsigned*)(lds + (bufoff) + ldsw + _i * 8192), 16, 0, 0); } while (0)
; #define PG8_LDA(dst, b, h) do { _Pragma("unroll") for (int m = 0; m < 4; ++m) _Pragma("unroll") for (int k = 0; k < 2; ++k) dst[m][k] = *(const PG8_LAS bf16x8*)(lds + PG8_SA(b, h) + aoff + m * 2048 + k * 1024); } while (0)
; #define PG8_LDB(dst, b, h) do { _Pragma("unroll") for (int n = 0; n < 2; ++n) _Pragma("unroll") for (int k = 0; k < 2; ++k) dst[n][k] = *(const PG8_LAS bf16x8*)(lds + PG8_SB(b, h) + boff + n * 2048 + k * 1024); } while (0)
; #define PG8_MMA(ai, bj, At, Bt) do { __builtin_amdgcn_s_setprio(1); _Pragma("unroll") for (int m = 0; m < 4; ++m) _Pragma("unroll") for (int n = 0; n < 2; ++n) _Pragma("unroll") for (int k = 0; k < 2; ++k) \
;         acc[ai][bj][m][n] = __builtin_amdgcn_mfma_f32_16x16x32_bf16(Bt[n][k], At[m][k], acc[ai][bj][m][n], 0, 0, 0); __builtin_amdgcn_s_setprio(0); } while (0)
; #define PG8_WAIT_V(n) asm volatile("s_waitcnt vmcnt(" #n ")" ::: "memory")
; #define PG8_WAIT_L(n) asm volatile("s_waitcnt lgkmcnt(" #n ")" ::: "memory")
; #define PG8_BAR __builtin_amdgcn_s_barrier()
; #define PG8_SCHED __builtin_amdgcn_sched_barrier(0)
; template <class Epi, class Sched, bool ALIGN_EPI = false, bool SP2 = false>
; __device__ __forceinline__ void gemm_phase(PG8_LAS unsigned char* lds, const Gemm g, const Sched& S, const Epi& E, const int tid_in) {
;     ...
;             const bool last = (t == nt - 2);
;             const char* a1 = cA + (size_t)(t + 1) * kstep;
;             const char* a2 = last ? nA : cA + (size_t)(t + 2) * kstep; const char* b2 = last ? nB : cB + (size_t)(t + 2) * kstep;
;             const char* a3 = a2 + kstep; const char* b3 = b2 + kstep;
;             if (last && has_next) S.a_ready(nxt);
;             if constexpr (SP2) {
;             PG8_LDB(B0, 0, 0); PG8_LDB(B1, 0, 1); PG8_SCHED; PG8_LDA(At, 0, 0); PG8_STAGE(PG8_SA(1, 1), a1 + hstepA, voffA);
;             PG8_WAIT_V(8); PG8_WAIT_L(0); PG8_BAR; PG8_MMA(0, 0, At, B0); PG8_MMA(0, 1, At, B1); PG8_BAR; PG8_SCHED;
;             PG8_LDA(At, 0, 1); PG8_STAGE(PG8_SB(0, 0), b2, voffB); PG8_STAGE(PG8_SB(0, 1), b2 + hstepB, voffB); PG8_STAGE(PG8_SA(0, 0), a2, voffA);
.LBB0_1131:
	s_add_u32 s22, s20, 0xfffc0080
	s_addc_u32 s23, s21, -1
	s_add_i32 s49, 0, 0x10000
	s_cmp_eq_u32 s48, 12
	s_cselect_b32 s25, s15, s23
	s_cselect_b32 s24, s44, s22
	v_add_u32_e32 v142, s49, v143
	s_cselect_b32 s23, s13, s47
	s_cselect_b32 s22, s45, s46
	s_add_i32 s54, 0, 0x14000
	ds_read_b128 v[148:151], v142
	ds_read_b128 v[152:155], v142 offset:1024
	ds_read_b128 v[156:159], v142 offset:2048
	ds_read_b128 v[160:163], v142 offset:3072
	v_add_u32_e32 v142, s54, v143
	ds_read_b128 v[164:167], v142
	ds_read_b128 v[168:171], v142 offset:1024
	ds_read_b128 v[172:175], v142 offset:2048
	ds_read_b128 v[176:179], v142 offset:3072
	v_lshl_add_u64 v[144:145], s[20:21], 0, v[138:139]
	s_add_i32 m0, s31, 0xc000
	ds_read_b128 v[180:183], v147
	ds_read_b128 v[184:187], v147 offset:1024
	ds_read_b128 v[188:191], v147 offset:2048
	ds_read_b128 v[192:195], v147 offset:3072
	ds_read_b128 v[200:203], v147 offset:4096
	ds_read_b128 v[204:207], v147 offset:5120
	ds_read_b128 v[208:211], v147 offset:6144
	ds_read_b128 v[212:215], v147 offset:7168
	global_load_lds_dwordx4 v[144:145], off
	v_lshl_add_u64 v[144:145], s[20:21], 0, v[140:141]
	s_add_i32 m0, s31, 0xe000
	s_nop 0
	global_load_lds_dwordx4 v[144:145], off
	s_waitcnt vmcnt(8)
	s_waitcnt lgkmcnt(0)
	s_barrier
	s_setprio 1
	s_waitcnt lgkmcnt(0)
	v_mfma_f32_16x16x32_bf16 v[128:131], v[148:151], v[180:183], v[128:131]
	v_mfma_f32_16x16x32_bf16 v[124:127], v[156:159], v[180:183], v[124:127]
	v_mfma_f32_16x16x32_bf16 v[112:115], v[148:151], v[188:191], v[112:115]
	v_mfma_f32_16x16x32_bf16 v[108:111], v[156:159], v[188:191], v[108:111]
	v_mfma_f32_16x16x32_bf16 v[92:95], v[148:151], v[200:203], v[92:95]
	v_mfma_f32_16x16x32_bf16 v[88:91], v[156:159], v[200:203], v[88:91]
	v_mfma_f32_16x16x32_bf16 v[76:79], v[148:151], v[208:211], v[76:79]
	v_mfma_f32_16x16x32_bf16 v[72:75], v[156:159], v[208:211], v[72:75]
	v_mfma_f32_16x16x32_bf16 v[128:131], v[152:155], v[184:187], v[128:131]
	v_mfma_f32_16x16x32_bf16 v[124:127], v[160:163], v[184:187], v[124:127]
	v_mfma_f32_16x16x32_bf16 v[112:115], v[152:155], v[192:195], v[112:115]
	v_mfma_f32_16x16x32_bf16 v[108:111], v[160:163], v[192:195], v[108:111]
	v_mfma_f32_16x16x32_bf16 v[92:95], v[152:155], v[204:207], v[92:95]
	v_mfma_f32_16x16x32_bf16 v[88:91], v[160:163], v[204:207], v[88:91]
	v_mfma_f32_16x16x32_bf16 v[76:79], v[152:155], v[212:215], v[76:79]
	v_mfma_f32_16x16x32_bf16 v[72:75], v[160:163], v[212:215], v[72:75]
	v_mfma_f32_16x16x32_bf16 v[120:123], v[164:167], v[180:183], v[120:123]
	v_mfma_f32_16x16x32_bf16 v[116:119], v[172:175], v[180:183], v[116:119]
	v_mfma_f32_16x16x32_bf16 v[104:107], v[164:167], v[188:191], v[104:107]
	v_mfma_f32_16x16x32_bf16 v[100:103], v[172:175], v[188:191], v[100:103]
	v_mfma_f32_16x16x32_bf16 v[84:87], v[164:167], v[200:203], v[84:87]
	v_mfma_f32_16x16x32_bf16 v[80:83], v[172:175], v[200:203], v[80:83]
	v_mfma_f32_16x16x32_bf16 v[68:71], v[164:167], v[208:211], v[68:71]
	v_mfma_f32_16x16x32_bf16 v[64:67], v[172:175], v[208:211], v[64:67]
	v_mfma_f32_16x16x32_bf16 v[120:123], v[168:171], v[184:187], v[120:123]
	v_mfma_f32_16x16x32_bf16 v[116:119], v[176:179], v[184:187], v[116:119]
	v_mfma_f32_16x16x32_bf16 v[104:107], v[168:171], v[192:195], v[104:107]
	v_mfma_f32_16x16x32_bf16 v[100:103], v[176:179], v[192:195], v[100:103]
	v_mfma_f32_16x16x32_bf16 v[84:87], v[168:171], v[204:207], v[84:87]
	v_mfma_f32_16x16x32_bf16 v[80:83], v[176:179], v[204:207], v[80:83]
	v_mfma_f32_16x16x32_bf16 v[68:71], v[168:171], v[212:215], v[68:71]
	v_mfma_f32_16x16x32_bf16 v[64:67], v[176:179], v[212:215], v[64:67]
	s_setprio 0
	s_barrier
	s_add_i32 s49, s49, s30
	v_lshl_add_u64 v[144:145], s[22:23], 0, v[134:135]
	s_mov_b32 m0, s49
	ds_read_b128 v[180:183], v147 offset:16384
	ds_read_b128 v[184:187], v147 offset:17408
	ds_read_b128 v[188:191], v147 offset:18432
	ds_read_b128 v[192:195], v147 offset:19456
	ds_read_b128 v[200:203], v147 offset:20480
	ds_read_b128 v[204:207], v147 offset:21504
	ds_read_b128 v[208:211], v147 offset:22528
	ds_read_b128 v[212:215], v147 offset:23552
	global_load_lds_dwordx4 v[144:145], off
	s_add_i32 m0, s49, 0x2000
	s_add_u32 s52, s22, 0x40000
	v_lshl_add_u64 v[196:197], s[22:23], 0, v[96:97]
	s_addc_u32 s53, s23, 0
	s_add_i32 s49, s54, s30
	global_load_lds_dwordx4 v[196:197], off
	v_lshl_add_u64 v[216:217], s[52:53], 0, v[134:135]
	s_mov_b32 m0, s49
	v_lshl_add_u64 v[218:219], s[24:25], 0, v[132:133]
	global_load_lds_dwordx4 v[216:217], off
	v_lshl_add_u64 v[216:217], s[52:53], 0, v[96:97]
	s_add_i32 m0, s49, 0x2000
	s_nop 0
	global_load_lds_dwordx4 v[216:217], off
	v_lshl_add_u64 v[216:217], s[24:25], 0, v[136:137]
	s_mov_b32 m0, s31
	s_nop 0
	global_load_lds_dwordx4 v[216:217], off
	s_mov_b32 m0, s34
	s_nop 0
	global_load_lds_dwordx4 v[218:219], off
	s_waitcnt vmcnt(8)
	s_waitcnt lgkmcnt(0)
	s_barrier
; #define PG8_STAGE(bufoff, gbase, voff) do { _Pragma("unroll") for (int _i = 0; _i < 2; ++_i) \
;         __builtin_amdgcn_global_load_lds((const unsigned*)((const char*)(gbase) + (voff)[_i]), (PG8_LAS unsigned*)(lds + (bufoff) + ldsw + _i * 8192), 16, 0, 0); } while (0)
; #define PG8_LDA(dst, b, h) do { _Pragma("unroll") for (int m = 0; m < 4; ++m) _Pragma("unroll") for (int k = 0; k < 2; ++k) dst[m][k] = *(const PG8_LAS bf16x8*)(lds + PG8_SA(b, h) + aoff + m * 2048 + k * 1024); } while (0)
; #define PG8_LDB(dst, b, h) do { _Pragma("unroll") for (int n = 0; n < 2; ++n) _Pragma("unroll") for (int k = 0; k < 2; ++k) dst[n][k] = *(const PG8_LAS bf16x8*)(lds + PG8_SB(b, h) + boff + n * 2048 + k * 1024); } while (0)
; #define PG8_MMA(ai, bj, At, Bt) do { __builtin_amdgcn_s_setprio(1); _Pragma("unroll") for (int m = 0; m < 4; ++m) _Pragma("unroll") for (int n = 0; n < 2; ++n) _Pragma("unroll") for (int k = 0; k < 2; ++k) \
;         acc[ai][bj][m][n] = __builtin_amdgcn_mfma_f32_16x16x32_bf16(Bt[n][k], At[m][k], acc[ai][bj][m][n], 0, 0, 0); __builtin_amdgcn_s_setprio(0); } while (0)
; #define PG8_WAIT_V(n) asm volatile("s_waitcnt vmcnt(" #n ")" ::: "memory")
; #define PG8_WAIT_L(n) asm volatile("s_waitcnt lgkmcnt(" #n ")" ::: "memory")
; #define PG8_BAR __builtin_amdgcn_s_barrier()
; #define PG8_SCHED __builtin_amdgcn_sched_barrier(0)
; template <class Epi, class Sched, bool ALIGN_EPI = false, bool SP2 = false>
; __device__ __forceinline__ void gemm_phase(PG8_LAS unsigned char* lds, const Gemm g, const Sched& S, const Epi& E, const int tid_in) {
;     ...
;             PG8_WAIT_V(8); PG8_WAIT_L(0); PG8_BAR; PG8_MMA(1, 0, At, B0); PG8_MMA(1, 1, At, B1); PG8_BAR; PG8_SCHED;
;             PG8_LDB(B0, 1, 0); PG8_LDB(B1, 1, 1); PG8_SCHED; PG8_LDA(At, 1, 0); PG8_STAGE(PG8_SA(0, 1), a2 + hstepA, voffA);
;             PG8_WAIT_V(8); PG8_WAIT_L(0); PG8_BAR; PG8_MMA(0, 0, At, B0); PG8_MMA(0, 1, At, B1); PG8_BAR; PG8_SCHED;
	s_setprio 1
	s_waitcnt lgkmcnt(0)
	v_mfma_f32_16x16x32_bf16 v[60:63], v[148:151], v[180:183], v[60:63]
	v_mfma_f32_16x16x32_bf16 v[56:59], v[156:159], v[180:183], v[56:59]
	v_mfma_f32_16x16x32_bf16 v[44:47], v[148:151], v[188:191], v[44:47]
	v_mfma_f32_16x16x32_bf16 v[40:43], v[156:159], v[188:191], v[40:43]
	v_mfma_f32_16x16x32_bf16 v[28:31], v[148:151], v[200:203], v[28:31]
	v_mfma_f32_16x16x32_bf16 v[24:27], v[156:159], v[200:203], v[24:27]
	v_mfma_f32_16x16x32_bf16 v[12:15], v[148:151], v[208:211], v[12:15]
	v_mfma_f32_16x16x32_bf16 v[8:11], v[156:159], v[208:211], v[8:11]
	v_mfma_f32_16x16x32_bf16 v[60:63], v[152:155], v[184:187], v[60:63]
	v_mfma_f32_16x16x32_bf16 v[56:59], v[160:163], v[184:187], v[56:59]
	v_mfma_f32_16x16x32_bf16 v[44:47], v[152:155], v[192:195], v[44:47]
	v_mfma_f32_16x16x32_bf16 v[40:43], v[160:163], v[192:195], v[40:43]
	v_mfma_f32_16x16x32_bf16 v[28:31], v[152:155], v[204:207], v[28:31]
	v_mfma_f32_16x16x32_bf16 v[24:27], v[160:163], v[204:207], v[24:27]
	v_mfma_f32_16x16x32_bf16 v[12:15], v[152:155], v[212:215], v[12:15]
	v_mfma_f32_16x16x32_bf16 v[8:11], v[160:163], v[212:215], v[8:11]
	v_mfma_f32_16x16x32_bf16 v[52:55], v[164:167], v[180:183], v[52:55]
	v_mfma_f32_16x16x32_bf16 v[48:51], v[172:175], v[180:183], v[48:51]
	v_mfma_f32_16x16x32_bf16 v[36:39], v[164:167], v[188:191], v[36:39]
	v_mfma_f32_16x16x32_bf16 v[32:35], v[172:175], v[188:191], v[32:35]
	v_mfma_f32_16x16x32_bf16 v[20:23], v[164:167], v[200:203], v[20:23]
	v_mfma_f32_16x16x32_bf16 v[16:19], v[172:175], v[200:203], v[16:19]
	v_mfma_f32_16x16x32_bf16 v[4:7], v[164:167], v[208:211], v[4:7]
	v_mfma_f32_16x16x32_bf16 v[0:3], v[172:175], v[208:211], v[0:3]
	v_mfma_f32_16x16x32_bf16 v[52:55], v[168:171], v[184:187], v[52:55]
	v_mfma_f32_16x16x32_bf16 v[48:51], v[176:179], v[184:187], v[48:51]
	v_mfma_f32_16x16x32_bf16 v[36:39], v[168:171], v[192:195], v[36:39]
	v_mfma_f32_16x16x32_bf16 v[32:35], v[176:179], v[192:195], v[32:35]
	v_mfma_f32_16x16x32_bf16 v[20:23], v[168:171], v[204:207], v[20:23]
	v_mfma_f32_16x16x32_bf16 v[16:19], v[176:179], v[204:207], v[16:19]
	v_mfma_f32_16x16x32_bf16 v[4:7], v[168:171], v[212:215], v[4:7]
	v_mfma_f32_16x16x32_bf16 v[0:3], v[176:179], v[212:215], v[0:3]
	s_setprio 0
	s_barrier
	s_add_i32 s49, 0, 0x18000
	v_add_u32_e32 v142, s49, v143
	s_add_i32 s52, 0, 0x1c000
	ds_read_b128 v[148:151], v142
	ds_read_b128 v[152:155], v142 offset:1024
	ds_read_b128 v[156:159], v142 offset:2048
	ds_read_b128 v[160:163], v142 offset:3072
	v_add_u32_e32 v142, s52, v143
	ds_read_b128 v[164:167], v142
	ds_read_b128 v[168:171], v142 offset:1024
	ds_read_b128 v[172:175], v142 offset:2048
	ds_read_b128 v[176:179], v142 offset:3072
	s_add_u32 s24, s24, 0x40000
	s_addc_u32 s25, s25, 0
	s_mov_b32 m0, s35
	v_lshl_add_u64 v[220:221], s[24:25], 0, v[136:137]
	ds_read_b128 v[180:183], v147 offset:32768
	ds_read_b128 v[184:187], v147 offset:33792
	ds_read_b128 v[188:191], v147 offset:34816
	ds_read_b128 v[192:195], v147 offset:35840
	ds_read_b128 v[200:203], v147 offset:36864
	ds_read_b128 v[204:207], v147 offset:37888
	ds_read_b128 v[208:211], v147 offset:38912
	ds_read_b128 v[212:215], v147 offset:39936
	global_load_lds_dwordx4 v[220:221], off
	v_lshl_add_u64 v[220:221], s[24:25], 0, v[132:133]
	s_mov_b32 m0, s36
	s_nop 0
	global_load_lds_dwordx4 v[220:221], off
	s_waitcnt vmcnt(8)
	s_waitcnt lgkmcnt(0)
	s_barrier
	s_setprio 1
	s_waitcnt lgkmcnt(0)
	v_mfma_f32_16x16x32_bf16 v[128:131], v[148:151], v[180:183], v[128:131]
	v_mfma_f32_16x16x32_bf16 v[124:127], v[156:159], v[180:183], v[124:127]
	v_mfma_f32_16x16x32_bf16 v[112:115], v[148:151], v[188:191], v[112:115]
	v_mfma_f32_16x16x32_bf16 v[108:111], v[156:159], v[188:191], v[108:111]
	v_mfma_f32_16x16x32_bf16 v[92:95], v[148:151], v[200:203], v[92:95]
	v_mfma_f32_16x16x32_bf16 v[88:91], v[156:159], v[200:203], v[88:91]
	v_mfma_f32_16x16x32_bf16 v[76:79], v[148:151], v[208:211], v[76:79]
	v_mfma_f32_16x16x32_bf16 v[72:75], v[156:159], v[208:211], v[72:75]
	v_mfma_f32_16x16x32_bf16 v[128:131], v[152:155], v[184:187], v[128:131]
	v_mfma_f32_16x16x32_bf16 v[124:127], v[160:163], v[184:187], v[124:127]
	v_mfma_f32_16x16x32_bf16 v[112:115], v[152:155], v[192:195], v[112:115]
	v_mfma_f32_16x16x32_bf16 v[108:111], v[160:163], v[192:195], v[108:111]
	v_mfma_f32_16x16x32_bf16 v[92:95], v[152:155], v[204:207], v[92:95]
	v_mfma_f32_16x16x32_bf16 v[88:91], v[160:163], v[204:207], v[88:91]
	v_mfma_f32_16x16x32_bf16 v[76:79], v[152:155], v[212:215], v[76:79]
	v_mfma_f32_16x16x32_bf16 v[72:75], v[160:163], v[212:215], v[72:75]
	v_mfma_f32_16x16x32_bf16 v[120:123], v[164:167], v[180:183], v[120:123]
	v_mfma_f32_16x16x32_bf16 v[116:119], v[172:175], v[180:183], v[116:119]
	v_mfma_f32_16x16x32_bf16 v[104:107], v[164:167], v[188:191], v[104:107]
	v_mfma_f32_16x16x32_bf16 v[100:103], v[172:175], v[188:191], v[100:103]
	v_mfma_f32_16x16x32_bf16 v[84:87], v[164:167], v[200:203], v[84:87]
	v_mfma_f32_16x16x32_bf16 v[80:83], v[172:175], v[200:203], v[80:83]
	v_mfma_f32_16x16x32_bf16 v[68:71], v[164:167], v[208:211], v[68:71]
	v_mfma_f32_16x16x32_bf16 v[64:67], v[172:175], v[208:211], v[64:67]
	v_mfma_f32_16x16x32_bf16 v[120:123], v[168:171], v[184:187], v[120:123]
	v_mfma_f32_16x16x32_bf16 v[116:119], v[176:179], v[184:187], v[116:119]
	v_mfma_f32_16x16x32_bf16 v[104:107], v[168:171], v[192:195], v[104:107]
	v_mfma_f32_16x16x32_bf16 v[100:103], v[176:179], v[192:195], v[100:103]
	v_mfma_f32_16x16x32_bf16 v[84:87], v[168:171], v[204:207], v[84:87]
	v_mfma_f32_16x16x32_bf16 v[80:83], v[176:179], v[204:207], v[80:83]
	v_mfma_f32_16x16x32_bf16 v[68:71], v[168:171], v[212:215], v[68:71]
	v_mfma_f32_16x16x32_bf16 v[64:67], v[176:179], v[212:215], v[64:67]
	s_setprio 0
	s_barrier
; #define PG8_STAGE(bufoff, gbase, voff) do { _Pragma("unroll") for (int _i = 0; _i < 2; ++_i) \
;         __builtin_amdgcn_global_load_lds((const unsigned*)((const char*)(gbase) + (voff)[_i]), (PG8_LAS unsigned*)(lds + (bufoff) + ldsw + _i * 8192), 16, 0, 0); } while (0)
; #define PG8_LDA(dst, b, h) do { _Pragma("unroll") for (int m = 0; m < 4; ++m) _Pragma("unroll") for (int k = 0; k < 2; ++k) dst[m][k] = *(const PG8_LAS bf16x8*)(lds + PG8_SA(b, h) + aoff + m * 2048 + k * 1024); } while (0)
; #define PG8_MMA(ai, bj, At, Bt) do { __builtin_amdgcn_s_setprio(1); _Pragma("unroll") for (int m = 0; m < 4; ++m) _Pragma("unroll") for (int n = 0; n < 2; ++n) _Pragma("unroll") for (int k = 0; k < 2; ++k) \
;         acc[ai][bj][m][n] = __builtin_amdgcn_mfma_f32_16x16x32_bf16(Bt[n][k], At[m][k], acc[ai][bj][m][n], 0, 0, 0); __builtin_amdgcn_s_setprio(0); } while (0)
; #define PG8_WAIT_V(n) asm volatile("s_waitcnt vmcnt(" #n ")" ::: "memory")
; #define PG8_WAIT_L(n) asm volatile("s_waitcnt lgkmcnt(" #n ")" ::: "memory")
; #define PG8_BAR __builtin_amdgcn_s_barrier()
; #define PG8_SCHED __builtin_amdgcn_sched_barrier(0)
; template <class Epi, class Sched, bool ALIGN_EPI = false, bool SP2 = false>
; __device__ __forceinline__ void gemm_phase(PG8_LAS unsigned char* lds, const Gemm g, const Sched& S, const Epi& E, const int tid_in) {
;     ...
;             PG8_LDA(At, 1, 1); PG8_STAGE(PG8_SB(1, 0), b3, voffB); PG8_STAGE(PG8_SB(1, 1), b3 + hstepB, voffB); PG8_STAGE(PG8_SA(1, 0), a3, voffA);
;             PG8_WAIT_V(8); PG8_WAIT_L(0); PG8_BAR; PG8_MMA(1, 0, At, B0); PG8_MMA(1, 1, At, B1); PG8_BAR; PG8_SCHED;
;     ...
;         if constexpr (ALIGN_EPI) { if (wr == 0) PG8_BAR; }
	s_add_i32 s24, s49, s30
	v_lshl_add_u64 v[144:145], v[144:145], 0, s[50:51]
	s_mov_b32 m0, s24
	ds_read_b128 v[180:183], v147 offset:49152
	ds_read_b128 v[184:187], v147 offset:50176
	ds_read_b128 v[188:191], v147 offset:51200
	ds_read_b128 v[192:195], v147 offset:52224
	ds_read_b128 v[200:203], v147 offset:53248
	ds_read_b128 v[204:207], v147 offset:54272
	ds_read_b128 v[208:211], v147 offset:55296
	ds_read_b128 v[212:215], v147 offset:56320
	global_load_lds_dwordx4 v[144:145], off
	s_add_i32 m0, s24, 0x2000
	s_add_u32 s22, s22, 0x40080
	v_lshl_add_u64 v[144:145], v[196:197], 0, s[50:51]
	s_addc_u32 s23, s23, 0
	s_add_i32 s24, s52, s30
	global_load_lds_dwordx4 v[144:145], off
	v_lshl_add_u64 v[144:145], s[22:23], 0, v[134:135]
	s_mov_b32 m0, s24
	s_nop 0
	global_load_lds_dwordx4 v[144:145], off
	v_lshl_add_u64 v[144:145], s[22:23], 0, v[96:97]
	s_add_i32 m0, s24, 0x2000
	s_nop 0
	global_load_lds_dwordx4 v[144:145], off
	v_lshl_add_u64 v[144:145], v[216:217], 0, s[50:51]
	s_mov_b32 m0, s39
	s_nop 0
	global_load_lds_dwordx4 v[144:145], off
	v_lshl_add_u64 v[144:145], v[218:219], 0, s[50:51]
	s_mov_b32 m0, s40
	s_nop 0
	global_load_lds_dwordx4 v[144:145], off
	s_waitcnt vmcnt(8)
	s_waitcnt lgkmcnt(0)
	s_barrier
	s_setprio 1
	s_waitcnt lgkmcnt(0)
	v_mfma_f32_16x16x32_bf16 v[60:63], v[148:151], v[180:183], v[60:63]
	v_mfma_f32_16x16x32_bf16 v[56:59], v[156:159], v[180:183], v[56:59]
	v_mfma_f32_16x16x32_bf16 v[44:47], v[148:151], v[188:191], v[44:47]
	v_mfma_f32_16x16x32_bf16 v[40:43], v[156:159], v[188:191], v[40:43]
	v_mfma_f32_16x16x32_bf16 v[28:31], v[148:151], v[200:203], v[28:31]
	v_mfma_f32_16x16x32_bf16 v[24:27], v[156:159], v[200:203], v[24:27]
	v_mfma_f32_16x16x32_bf16 v[12:15], v[148:151], v[208:211], v[12:15]
	v_mfma_f32_16x16x32_bf16 v[8:11], v[156:159], v[208:211], v[8:11]
	v_mfma_f32_16x16x32_bf16 v[60:63], v[152:155], v[184:187], v[60:63]
	v_mfma_f32_16x16x32_bf16 v[56:59], v[160:163], v[184:187], v[56:59]
	v_mfma_f32_16x16x32_bf16 v[44:47], v[152:155], v[192:195], v[44:47]
	v_mfma_f32_16x16x32_bf16 v[40:43], v[160:163], v[192:195], v[40:43]
	v_mfma_f32_16x16x32_bf16 v[28:31], v[152:155], v[204:207], v[28:31]
	v_mfma_f32_16x16x32_bf16 v[24:27], v[160:163], v[204:207], v[24:27]
	v_mfma_f32_16x16x32_bf16 v[12:15], v[152:155], v[212:215], v[12:15]
	v_mfma_f32_16x16x32_bf16 v[8:11], v[160:163], v[212:215], v[8:11]
	v_mfma_f32_16x16x32_bf16 v[52:55], v[164:167], v[180:183], v[52:55]
	v_mfma_f32_16x16x32_bf16 v[48:51], v[172:175], v[180:183], v[48:51]
	v_mfma_f32_16x16x32_bf16 v[36:39], v[164:167], v[188:191], v[36:39]
	v_mfma_f32_16x16x32_bf16 v[32:35], v[172:175], v[188:191], v[32:35]
	v_mfma_f32_16x16x32_bf16 v[20:23], v[164:167], v[200:203], v[20:23]
	v_mfma_f32_16x16x32_bf16 v[16:19], v[172:175], v[200:203], v[16:19]
	v_mfma_f32_16x16x32_bf16 v[4:7], v[164:167], v[208:211], v[4:7]
	v_mfma_f32_16x16x32_bf16 v[0:3], v[172:175], v[208:211], v[0:3]
	v_mfma_f32_16x16x32_bf16 v[52:55], v[168:171], v[184:187], v[52:55]
	v_mfma_f32_16x16x32_bf16 v[48:51], v[176:179], v[184:187], v[48:51]
	v_mfma_f32_16x16x32_bf16 v[36:39], v[168:171], v[192:195], v[36:39]
	v_mfma_f32_16x16x32_bf16 v[32:35], v[176:179], v[192:195], v[32:35]
	v_mfma_f32_16x16x32_bf16 v[20:23], v[168:171], v[204:207], v[20:23]
	v_mfma_f32_16x16x32_bf16 v[16:19], v[176:179], v[204:207], v[16:19]
	v_mfma_f32_16x16x32_bf16 v[4:7], v[168:171], v[212:215], v[4:7]
	v_mfma_f32_16x16x32_bf16 v[0:3], v[176:179], v[212:215], v[0:3]
	s_setprio 0
	s_barrier
	s_add_i32 s48, s48, 2
	s_add_u32 s20, s20, 0x100
	s_addc_u32 s21, s21, 0
	s_add_u32 s46, s46, 0x100
	s_addc_u32 s47, s47, 0
	s_cmp_gt_u32 s48, 13
	s_cbranch_scc0 .LBB0_1131
	s_and_b64 vcc, exec, s[10:11]
	s_cbranch_vccz .LBB0_1134
	s_barrier

; #define PG8_STAGE(bufoff, gbase, voff) do { _Pragma("unroll") for (int _i = 0; _i < 2; ++_i) \
;         __builtin_amdgcn_global_load_lds((const unsigned*)((const char*)(gbase) + (voff)[_i]), (PG8_LAS unsigned*)(lds + (bufoff) + ldsw + _i * 8192), 16, 0, 0); } while (0)
; #define PG8_LDA(dst, b, h) do { _Pragma("unroll") for (int m = 0; m < 4; ++m) _Pragma("unroll") for (int k = 0; k < 2; ++k) dst[m][k] = *(const PG8_LAS bf16x8*)(lds + PG8_SA(b, h) + aoff + m * 2048 + k * 1024); } while (0)
; #define PG8_LDB(dst, b, h) do { _Pragma("unroll") for (int n = 0; n < 2; ++n) _Pragma("unroll") for (int k = 0; k < 2; ++k) dst[n][k] = *(const PG8_LAS bf16x8*)(lds + PG8_SB(b, h) + boff + n * 2048 + k * 1024); } while (0)
; #define PG8_MMA(ai, bj, At, Bt) do { __builtin_amdgcn_s_setprio(1); _Pragma("unroll") for (int m = 0; m < 4; ++m) _Pragma("unroll") for (int n = 0; n < 2; ++n) _Pragma("unroll") for (int k = 0; k < 2; ++k) \
;         acc[ai][bj][m][n] = __builtin_amdgcn_mfma_f32_16x16x32_bf16(Bt[n][k], At[m][k], acc[ai][bj][m][n], 0, 0, 0); __builtin_amdgcn_s_setprio(0); } while (0)
; template <class Epi, class Sched, bool ALIGN_EPI = false, bool SP2 = false>
; __device__ __forceinline__ void gemm_phase(PG8_LAS unsigned char* lds, const Gemm g, const Sched& S, const Epi& E, const int tid_in) {
;     ...
;         const bool has_next = S.next(ui + 1, nxt);
;         const char* nA = has_next ? (const char*)g.A + (size_t)nxt.pm * tstepA : cA; const char* nB = has_next ? (const char*)g.Bt + (size_t)nxt.pn * tstepB : cB;
;         for (int t = 0; t < nt; t += 2) {
;             const bool last = (t == nt - 2);
;             const char* a1 = cA + (size_t)(t + 1) * kstep;
;             const char* a2 = last ? nA : cA + (size_t)(t + 2) * kstep; const char* b2 = last ? nB : cB + (size_t)(t + 2) * kstep;
;             const char* a3 = a2 + kstep; const char* b3 = b2 + kstep;
;             if (last && has_next) S.a_ready(nxt);
;             if constexpr (SP2) {
;             PG8_LDB(B0, 0, 0); PG8_LDB(B1, 0, 1); PG8_SCHED; PG8_LDA(At, 0, 0); PG8_STAGE(PG8_SA(1, 1), a1 + hstepA, voffA);
;             PG8_WAIT_V(8); PG8_WAIT_L(0); PG8_BAR; PG8_MMA(0, 0, At, B0); PG8_MMA(0, 1, At, B1); PG8_BAR; PG8_SCHED;
;             PG8_LDA(At, 0, 1); PG8_STAGE(PG8_SB(0, 0), b2, voffB); PG8_STAGE(PG8_SB(0, 1), b2 + hstepB, voffB); PG8_STAGE(PG8_SA(0, 0), a2, voffA);
.LBB0_1150:
	s_ashr_i32 s29, s28, 31
	s_lshl_b64 s[30:31], s[28:29], 17
	s_add_u32 s30, s42, s30
	s_addc_u32 s31, s43, s31
	s_and_b64 s[34:35], s[6:7], exec
	s_cselect_b32 s41, s31, s11
	s_cselect_b32 s40, s30, s10
	s_ashr_i32 s27, s26, 31
	s_lshl_b64 s[34:35], s[26:27], 17
	s_add_u32 s34, s44, s34
	s_addc_u32 s35, s45, s35
	s_and_b64 s[38:39], s[6:7], exec
	s_cselect_b32 s39, s35, s13
	s_cselect_b32 s38, s34, s12
	s_add_i32 s27, 0, 0x10000
	s_add_i32 s29, 0, 0x14000
	v_add_u32_e32 v214, s27, v99
	v_add_u32_e32 v215, s29, v99
	s_waitcnt lgkmcnt(0)
	ds_read_b128 v[4:7], v214
	ds_read_b128 v[8:11], v214 offset:1024
	ds_read_b128 v[12:15], v214 offset:2048
	ds_read_b128 v[16:19], v214 offset:3072
	ds_read_b128 v[20:23], v215
	ds_read_b128 v[24:27], v215 offset:1024
	ds_read_b128 v[28:31], v215 offset:2048
	ds_read_b128 v[32:35], v215 offset:3072
	v_mov_b64_e32 v[198:199], 0x200
	s_add_u32 s60, s10, 0x10080
	s_addc_u32 s61, s11, 0
	s_add_i32 s62, s47, 0xc000
	v_lshl_add_u64 v[68:69], s[60:61], 0, v[136:137]
	s_mov_b32 m0, s62
	s_add_i32 s9, s47, 0xe000
	ds_read_b128 v[36:39], v222
	ds_read_b128 v[40:43], v222 offset:1024
	ds_read_b128 v[44:47], v222 offset:2048
	ds_read_b128 v[48:51], v222 offset:3072
	ds_read_b128 v[52:55], v222 offset:4096
	ds_read_b128 v[56:59], v222 offset:5120
	ds_read_b128 v[60:63], v222 offset:6144
	ds_read_b128 v[64:67], v222 offset:7168
	global_load_lds_dwordx4 v[68:69], off
	v_lshl_add_u64 v[68:69], s[60:61], 0, v[96:97]
	s_mov_b32 m0, s9
	s_nop 0
	global_load_lds_dwordx4 v[68:69], off
	s_waitcnt vmcnt(8)
	s_waitcnt lgkmcnt(0)
	s_barrier
	s_setprio 1
	s_waitcnt lgkmcnt(0)
	v_mfma_f32_16x16x32_bf16 v[68:71], v[4:7], v[36:39], v[0:3]
	v_mfma_f32_16x16x32_bf16 v[72:75], v[12:15], v[36:39], v[0:3]
	v_mfma_f32_16x16x32_bf16 v[76:79], v[4:7], v[44:47], v[0:3]
	v_mfma_f32_16x16x32_bf16 v[80:83], v[12:15], v[44:47], v[0:3]
	v_mfma_f32_16x16x32_bf16 v[84:87], v[4:7], v[52:55], v[0:3]
	v_mfma_f32_16x16x32_bf16 v[88:91], v[12:15], v[52:55], v[0:3]
	v_mfma_f32_16x16x32_bf16 v[92:95], v[4:7], v[60:63], v[0:3]
	v_mfma_f32_16x16x32_bf16 v[100:103], v[12:15], v[60:63], v[0:3]
	v_mfma_f32_16x16x32_bf16 v[68:71], v[8:11], v[40:43], v[68:71]
	v_mfma_f32_16x16x32_bf16 v[72:75], v[16:19], v[40:43], v[72:75]
	v_mfma_f32_16x16x32_bf16 v[76:79], v[8:11], v[48:51], v[76:79]
	v_mfma_f32_16x16x32_bf16 v[80:83], v[16:19], v[48:51], v[80:83]
	v_mfma_f32_16x16x32_bf16 v[84:87], v[8:11], v[56:59], v[84:87]
	v_mfma_f32_16x16x32_bf16 v[88:91], v[16:19], v[56:59], v[88:91]
	v_mfma_f32_16x16x32_bf16 v[92:95], v[8:11], v[64:67], v[92:95]
	v_mfma_f32_16x16x32_bf16 v[100:103], v[16:19], v[64:67], v[100:103]
	v_mfma_f32_16x16x32_bf16 v[104:107], v[20:23], v[36:39], v[0:3]
	v_mfma_f32_16x16x32_bf16 v[36:39], v[28:31], v[36:39], v[0:3]
	v_mfma_f32_16x16x32_bf16 v[104:107], v[24:27], v[40:43], v[104:107]
	v_mfma_f32_16x16x32_bf16 v[36:39], v[32:35], v[40:43], v[36:39]
	v_mfma_f32_16x16x32_bf16 v[40:43], v[20:23], v[44:47], v[0:3]
	v_mfma_f32_16x16x32_bf16 v[44:47], v[28:31], v[44:47], v[0:3]
	v_mfma_f32_16x16x32_bf16 v[40:43], v[24:27], v[48:51], v[40:43]
	v_mfma_f32_16x16x32_bf16 v[44:47], v[32:35], v[48:51], v[44:47]
	v_mfma_f32_16x16x32_bf16 v[48:51], v[20:23], v[52:55], v[0:3]
	v_mfma_f32_16x16x32_bf16 v[52:55], v[28:31], v[52:55], v[0:3]
	v_mfma_f32_16x16x32_bf16 v[48:51], v[24:27], v[56:59], v[48:51]
	v_mfma_f32_16x16x32_bf16 v[52:55], v[32:35], v[56:59], v[52:55]
	v_mfma_f32_16x16x32_bf16 v[56:59], v[20:23], v[60:63], v[0:3]
	v_mfma_f32_16x16x32_bf16 v[60:63], v[28:31], v[60:63], v[0:3]
	v_mfma_f32_16x16x32_bf16 v[56:59], v[24:27], v[64:67], v[56:59]
	v_mfma_f32_16x16x32_bf16 v[60:63], v[32:35], v[64:67], v[60:63]
	s_setprio 0
	s_barrier
	s_add_i32 s60, s27, s46
	v_lshl_add_u64 v[194:195], s[12:13], 0, v[136:137]
	s_add_i32 s27, s60, 0x2000
	v_lshl_add_u64 v[138:139], v[194:195], 0, s[76:77]
	s_mov_b32 m0, s60
	v_lshl_add_u64 v[196:197], s[12:13], 0, v[96:97]
	s_add_u32 s64, s12, 0x10100
	ds_read_b128 v[64:67], v222 offset:16384
	ds_read_b128 v[108:111], v222 offset:17408
	ds_read_b128 v[112:115], v222 offset:18432
	ds_read_b128 v[116:119], v222 offset:19456
	ds_read_b128 v[120:123], v222 offset:20480
	ds_read_b128 v[124:127], v222 offset:21504
	ds_read_b128 v[128:131], v222 offset:22528
	ds_read_b128 v[132:135], v222 offset:23552
	global_load_lds_dwordx4 v[138:139], off
	v_lshl_add_u64 v[138:139], v[196:197], 0, s[76:77]
	s_mov_b32 m0, s27
	s_addc_u32 s65, s13, 0
	s_add_i32 s29, s29, s46
	global_load_lds_dwordx4 v[138:139], off
	v_lshl_add_u64 v[138:139], s[64:65], 0, v[136:137]
	s_mov_b32 m0, s29
	s_add_i32 s37, s29, 0x2000
	global_load_lds_dwordx4 v[138:139], off
	v_lshl_add_u64 v[138:139], s[64:65], 0, v[96:97]
	s_mov_b32 m0, s37
	v_lshl_add_u64 v[208:209], s[10:11], 0, v[136:137]
	global_load_lds_dwordx4 v[138:139], off
	v_lshl_add_u64 v[138:139], v[208:209], 0, s[76:77]
	s_mov_b32 m0, s47
	v_lshl_add_u64 v[210:211], s[10:11], 0, v[96:97]
	global_load_lds_dwordx4 v[138:139], off
	v_lshl_add_u64 v[138:139], v[210:211], 0, s[76:77]
	s_mov_b32 m0, s48
	s_nop 0
	global_load_lds_dwordx4 v[138:139], off
	s_waitcnt vmcnt(8)
	s_waitcnt lgkmcnt(0)
	s_barrier
; #define PG8_STAGE(bufoff, gbase, voff) do { _Pragma("unroll") for (int _i = 0; _i < 2; ++_i) \
;         __builtin_amdgcn_global_load_lds((const unsigned*)((const char*)(gbase) + (voff)[_i]), (PG8_LAS unsigned*)(lds + (bufoff) + ldsw + _i * 8192), 16, 0, 0); } while (0)
; #define PG8_LDA(dst, b, h) do { _Pragma("unroll") for (int m = 0; m < 4; ++m) _Pragma("unroll") for (int k = 0; k < 2; ++k) dst[m][k] = *(const PG8_LAS bf16x8*)(lds + PG8_SA(b, h) + aoff + m * 2048 + k * 1024); } while (0)
; #define PG8_LDB(dst, b, h) do { _Pragma("unroll") for (int n = 0; n < 2; ++n) _Pragma("unroll") for (int k = 0; k < 2; ++k) dst[n][k] = *(const PG8_LAS bf16x8*)(lds + PG8_SB(b, h) + boff + n * 2048 + k * 1024); } while (0)
; #define PG8_MMA(ai, bj, At, Bt) do { __builtin_amdgcn_s_setprio(1); _Pragma("unroll") for (int m = 0; m < 4; ++m) _Pragma("unroll") for (int n = 0; n < 2; ++n) _Pragma("unroll") for (int k = 0; k < 2; ++k) \
;         acc[ai][bj][m][n] = __builtin_amdgcn_mfma_f32_16x16x32_bf16(Bt[n][k], At[m][k], acc[ai][bj][m][n], 0, 0, 0); __builtin_amdgcn_s_setprio(0); } while (0)
; #define PG8_WAIT_V(n) asm volatile("s_waitcnt vmcnt(" #n ")" ::: "memory")
; #define PG8_WAIT_L(n) asm volatile("s_waitcnt lgkmcnt(" #n ")" ::: "memory")
; #define PG8_BAR __builtin_amdgcn_s_barrier()
; #define PG8_SCHED __builtin_amdgcn_sched_barrier(0)
; template <class Epi, class Sched, bool ALIGN_EPI = false, bool SP2 = false>
; __device__ __forceinline__ void gemm_phase(PG8_LAS unsigned char* lds, const Gemm g, const Sched& S, const Epi& E, const int tid_in) {
;     ...
;             PG8_WAIT_V(8); PG8_WAIT_L(0); PG8_BAR; PG8_MMA(1, 0, At, B0); PG8_MMA(1, 1, At, B1); PG8_BAR; PG8_SCHED;
;             PG8_LDB(B0, 1, 0); PG8_LDB(B1, 1, 1); PG8_SCHED; PG8_LDA(At, 1, 0); PG8_STAGE(PG8_SA(0, 1), a2 + hstepA, voffA);
;             PG8_WAIT_V(8); PG8_WAIT_L(0); PG8_BAR; PG8_MMA(0, 0, At, B0); PG8_MMA(0, 1, At, B1); PG8_BAR; PG8_SCHED;
	s_setprio 1
	s_waitcnt lgkmcnt(0)
	v_mfma_f32_16x16x32_bf16 v[138:141], v[4:7], v[64:67], v[0:3]
	v_mfma_f32_16x16x32_bf16 v[146:149], v[4:7], v[112:115], v[0:3]
	v_mfma_f32_16x16x32_bf16 v[154:157], v[4:7], v[120:123], v[0:3]
	v_mfma_f32_16x16x32_bf16 v[4:7], v[4:7], v[128:131], v[0:3]
	v_mfma_f32_16x16x32_bf16 v[138:141], v[8:11], v[108:111], v[138:141]
	v_mfma_f32_16x16x32_bf16 v[146:149], v[8:11], v[116:119], v[146:149]
	v_mfma_f32_16x16x32_bf16 v[154:157], v[8:11], v[124:127], v[154:157]
	v_mfma_f32_16x16x32_bf16 v[4:7], v[8:11], v[132:135], v[4:7]
	v_mfma_f32_16x16x32_bf16 v[8:11], v[12:15], v[128:131], v[0:3]
	v_mfma_f32_16x16x32_bf16 v[142:145], v[12:15], v[64:67], v[0:3]
	v_mfma_f32_16x16x32_bf16 v[150:153], v[12:15], v[112:115], v[0:3]
	v_mfma_f32_16x16x32_bf16 v[158:161], v[12:15], v[120:123], v[0:3]
	v_mfma_f32_16x16x32_bf16 v[8:11], v[16:19], v[132:135], v[8:11]
	v_mfma_f32_16x16x32_bf16 v[142:145], v[16:19], v[108:111], v[142:145]
	v_mfma_f32_16x16x32_bf16 v[150:153], v[16:19], v[116:119], v[150:153]
	v_mfma_f32_16x16x32_bf16 v[158:161], v[16:19], v[124:127], v[158:161]
	v_mfma_f32_16x16x32_bf16 v[12:15], v[20:23], v[64:67], v[0:3]
	v_mfma_f32_16x16x32_bf16 v[16:19], v[28:31], v[64:67], v[0:3]
	v_mfma_f32_16x16x32_bf16 v[12:15], v[24:27], v[108:111], v[12:15]
	v_mfma_f32_16x16x32_bf16 v[16:19], v[32:35], v[108:111], v[16:19]
	v_mfma_f32_16x16x32_bf16 v[64:67], v[20:23], v[112:115], v[0:3]
	v_mfma_f32_16x16x32_bf16 v[108:111], v[28:31], v[112:115], v[0:3]
	v_mfma_f32_16x16x32_bf16 v[112:115], v[20:23], v[120:123], v[0:3]
	v_mfma_f32_16x16x32_bf16 v[20:23], v[20:23], v[128:131], v[0:3]
	v_mfma_f32_16x16x32_bf16 v[64:67], v[24:27], v[116:119], v[64:67]
	v_mfma_f32_16x16x32_bf16 v[108:111], v[32:35], v[116:119], v[108:111]
	v_mfma_f32_16x16x32_bf16 v[112:115], v[24:27], v[124:127], v[112:115]
	v_mfma_f32_16x16x32_bf16 v[116:119], v[28:31], v[120:123], v[0:3]
	v_mfma_f32_16x16x32_bf16 v[20:23], v[24:27], v[132:135], v[20:23]
	v_mfma_f32_16x16x32_bf16 v[24:27], v[28:31], v[128:131], v[0:3]
	v_mfma_f32_16x16x32_bf16 v[116:119], v[32:35], v[124:127], v[116:119]
	v_mfma_f32_16x16x32_bf16 v[24:27], v[32:35], v[132:135], v[24:27]
	s_setprio 0
	s_barrier
	s_add_i32 s63, 0, 0x18000
	s_add_i32 s66, 0, 0x1c000
	v_add_u32_e32 v223, s63, v99
	v_add_u32_e32 v224, s66, v99
	ds_read_b128 v[28:31], v223
	ds_read_b128 v[32:35], v223 offset:1024
	ds_read_b128 v[120:123], v223 offset:2048
	ds_read_b128 v[124:127], v223 offset:3072
	ds_read_b128 v[128:131], v224
	ds_read_b128 v[132:135], v224 offset:1024
	ds_read_b128 v[162:165], v224 offset:2048
	ds_read_b128 v[166:169], v224 offset:3072
	s_add_u32 s64, s10, 0x10100
	s_addc_u32 s65, s11, 0
	s_mov_b32 m0, s49
	v_lshl_add_u64 v[212:213], s[64:65], 0, v[136:137]
	ds_read_b128 v[170:173], v222 offset:32768
	ds_read_b128 v[174:177], v222 offset:33792
	ds_read_b128 v[178:181], v222 offset:34816
	ds_read_b128 v[182:185], v222 offset:35840
	ds_read_b128 v[186:189], v222 offset:36864
	ds_read_b128 v[190:193], v222 offset:37888
	ds_read_b128 v[200:203], v222 offset:38912
	ds_read_b128 v[204:207], v222 offset:39936
	global_load_lds_dwordx4 v[212:213], off
	v_lshl_add_u64 v[212:213], s[64:65], 0, v[96:97]
	s_mov_b32 m0, s52
	s_nop 0
	global_load_lds_dwordx4 v[212:213], off
	s_waitcnt vmcnt(8)
	s_waitcnt lgkmcnt(0)
	s_barrier
	s_setprio 1
	s_waitcnt lgkmcnt(0)
	v_mfma_f32_16x16x32_bf16 v[68:71], v[28:31], v[170:173], v[68:71]
	v_mfma_f32_16x16x32_bf16 v[72:75], v[120:123], v[170:173], v[72:75]
	v_mfma_f32_16x16x32_bf16 v[76:79], v[28:31], v[178:181], v[76:79]
	v_mfma_f32_16x16x32_bf16 v[80:83], v[120:123], v[178:181], v[80:83]
	v_mfma_f32_16x16x32_bf16 v[84:87], v[28:31], v[186:189], v[84:87]
	v_mfma_f32_16x16x32_bf16 v[88:91], v[120:123], v[186:189], v[88:91]
	v_mfma_f32_16x16x32_bf16 v[92:95], v[28:31], v[200:203], v[92:95]
	v_mfma_f32_16x16x32_bf16 v[100:103], v[120:123], v[200:203], v[100:103]
	v_mfma_f32_16x16x32_bf16 v[68:71], v[32:35], v[174:177], v[68:71]
	v_mfma_f32_16x16x32_bf16 v[72:75], v[124:127], v[174:177], v[72:75]
	v_mfma_f32_16x16x32_bf16 v[76:79], v[32:35], v[182:185], v[76:79]
	v_mfma_f32_16x16x32_bf16 v[80:83], v[124:127], v[182:185], v[80:83]
	v_mfma_f32_16x16x32_bf16 v[84:87], v[32:35], v[190:193], v[84:87]
	v_mfma_f32_16x16x32_bf16 v[88:91], v[124:127], v[190:193], v[88:91]
	v_mfma_f32_16x16x32_bf16 v[92:95], v[32:35], v[204:207], v[92:95]
	v_mfma_f32_16x16x32_bf16 v[100:103], v[124:127], v[204:207], v[100:103]
	v_mfma_f32_16x16x32_bf16 v[104:107], v[128:131], v[170:173], v[104:107]
	v_mfma_f32_16x16x32_bf16 v[36:39], v[162:165], v[170:173], v[36:39]
	v_mfma_f32_16x16x32_bf16 v[40:43], v[128:131], v[178:181], v[40:43]
	v_mfma_f32_16x16x32_bf16 v[44:47], v[162:165], v[178:181], v[44:47]
	v_mfma_f32_16x16x32_bf16 v[48:51], v[128:131], v[186:189], v[48:51]
	v_mfma_f32_16x16x32_bf16 v[52:55], v[162:165], v[186:189], v[52:55]
	v_mfma_f32_16x16x32_bf16 v[56:59], v[128:131], v[200:203], v[56:59]
	v_mfma_f32_16x16x32_bf16 v[60:63], v[162:165], v[200:203], v[60:63]
	v_mfma_f32_16x16x32_bf16 v[104:107], v[132:135], v[174:177], v[104:107]
	v_mfma_f32_16x16x32_bf16 v[36:39], v[166:169], v[174:177], v[36:39]
	v_mfma_f32_16x16x32_bf16 v[40:43], v[132:135], v[182:185], v[40:43]
	v_mfma_f32_16x16x32_bf16 v[44:47], v[166:169], v[182:185], v[44:47]
	v_mfma_f32_16x16x32_bf16 v[48:51], v[132:135], v[190:193], v[48:51]
	v_mfma_f32_16x16x32_bf16 v[52:55], v[166:169], v[190:193], v[52:55]
	v_mfma_f32_16x16x32_bf16 v[56:59], v[132:135], v[204:207], v[56:59]
	v_mfma_f32_16x16x32_bf16 v[60:63], v[166:169], v[204:207], v[60:63]
	s_setprio 0
	s_barrier
; #define PG8_STAGE(bufoff, gbase, voff) do { _Pragma("unroll") for (int _i = 0; _i < 2; ++_i) \
;         __builtin_amdgcn_global_load_lds((const unsigned*)((const char*)(gbase) + (voff)[_i]), (PG8_LAS unsigned*)(lds + (bufoff) + ldsw + _i * 8192), 16, 0, 0); } while (0)
; #define PG8_LDA(dst, b, h) do { _Pragma("unroll") for (int m = 0; m < 4; ++m) _Pragma("unroll") for (int k = 0; k < 2; ++k) dst[m][k] = *(const PG8_LAS bf16x8*)(lds + PG8_SA(b, h) + aoff + m * 2048 + k * 1024); } while (0)
; #define PG8_LDB(dst, b, h) do { _Pragma("unroll") for (int n = 0; n < 2; ++n) _Pragma("unroll") for (int k = 0; k < 2; ++k) dst[n][k] = *(const PG8_LAS bf16x8*)(lds + PG8_SB(b, h) + boff + n * 2048 + k * 1024); } while (0)
; #define PG8_MMA(ai, bj, At, Bt) do { __builtin_amdgcn_s_setprio(1); _Pragma("unroll") for (int m = 0; m < 4; ++m) _Pragma("unroll") for (int n = 0; n < 2; ++n) _Pragma("unroll") for (int k = 0; k < 2; ++k) \
;         acc[ai][bj][m][n] = __builtin_amdgcn_mfma_f32_16x16x32_bf16(Bt[n][k], At[m][k], acc[ai][bj][m][n], 0, 0, 0); __builtin_amdgcn_s_setprio(0); } while (0)
; #define PG8_BAR __builtin_amdgcn_s_barrier()
; template <class Epi, class Sched, bool ALIGN_EPI = false, bool SP2 = false>
; __device__ __forceinline__ void gemm_phase(PG8_LAS unsigned char* lds, const Gemm g, const Sched& S, const Epi& E, const int tid_in) {
;     ...
;             PG8_LDB(B0, 0, 0); PG8_LDB(B1, 0, 1); PG8_SCHED; PG8_LDA(At, 0, 0); PG8_STAGE(PG8_SA(1, 1), a1 + hstepA, voffA);
;             PG8_WAIT_V(8); PG8_WAIT_L(0); PG8_BAR; PG8_MMA(0, 0, At, B0); PG8_MMA(0, 1, At, B1); PG8_BAR; PG8_SCHED;
;             PG8_LDA(At, 0, 1); PG8_STAGE(PG8_SB(0, 0), b2, voffB); PG8_STAGE(PG8_SB(0, 1), b2 + hstepB, voffB); PG8_STAGE(PG8_SA(0, 0), a2, voffA);
;             PG8_WAIT_V(8); PG8_WAIT_L(0); PG8_BAR; PG8_MMA(1, 0, At, B0); PG8_MMA(1, 1, At, B1); PG8_BAR; PG8_SCHED;
;             PG8_LDB(B0, 1, 0); PG8_LDB(B1, 1, 1); PG8_SCHED; PG8_LDA(At, 1, 0); PG8_STAGE(PG8_SA(0, 1), a2 + hstepA, voffA);
;             PG8_WAIT_V(8); PG8_WAIT_L(0); PG8_BAR; PG8_MMA(0, 0, At, B0); PG8_MMA(0, 1, At, B1); PG8_BAR; PG8_SCHED;
;             PG8_LDA(At, 1, 1); PG8_STAGE(PG8_SB(1, 0), b3, voffB); PG8_STAGE(PG8_SB(1, 1), b3 + hstepB, voffB); PG8_STAGE(PG8_SA(1, 0), a3, voffA);
;             PG8_WAIT_V(8); PG8_WAIT_L(0); PG8_BAR; PG8_MMA(1, 0, At, B0); PG8_MMA(1, 1, At, B1); PG8_BAR; PG8_SCHED;
	s_add_i32 s63, s63, s46
	s_mov_b64 s[80:81], 0x180
	s_add_i32 s61, s63, 0x2000
	v_lshl_add_u64 v[194:195], v[194:195], 0, s[80:81]
	s_mov_b32 m0, s63
	s_add_u32 s64, s12, 0x10180
	ds_read_b128 v[170:173], v222 offset:49152
	ds_read_b128 v[174:177], v222 offset:50176
	ds_read_b128 v[178:181], v222 offset:51200
	ds_read_b128 v[182:185], v222 offset:52224
	ds_read_b128 v[186:189], v222 offset:53248
	ds_read_b128 v[190:193], v222 offset:54272
	ds_read_b128 v[200:203], v222 offset:55296
	ds_read_b128 v[204:207], v222 offset:56320
	global_load_lds_dwordx4 v[194:195], off
	v_lshl_add_u64 v[194:195], v[196:197], 0, s[80:81]
	s_mov_b32 m0, s61
	s_addc_u32 s65, s13, 0
	s_add_i32 s12, s66, s46
	global_load_lds_dwordx4 v[194:195], off
	v_lshl_add_u64 v[194:195], s[64:65], 0, v[136:137]
	s_mov_b32 m0, s12
	s_add_i32 s13, s12, 0x2000
	global_load_lds_dwordx4 v[194:195], off
	v_lshl_add_u64 v[194:195], s[64:65], 0, v[96:97]
	s_mov_b32 m0, s13
	s_nop 0
	global_load_lds_dwordx4 v[194:195], off
	v_lshl_add_u64 v[194:195], v[208:209], 0, s[80:81]
	s_mov_b32 m0, s56
	s_nop 0
	global_load_lds_dwordx4 v[194:195], off
	v_lshl_add_u64 v[194:195], v[210:211], 0, s[80:81]
	s_mov_b32 m0, s57
	s_nop 0
	global_load_lds_dwordx4 v[194:195], off
	s_waitcnt vmcnt(8)
	s_waitcnt lgkmcnt(0)
	s_barrier
	s_setprio 1
	s_waitcnt lgkmcnt(0)
	v_mfma_f32_16x16x32_bf16 v[4:7], v[28:31], v[200:203], v[4:7]
	v_mfma_f32_16x16x32_bf16 v[8:11], v[120:123], v[200:203], v[8:11]
	v_mfma_f32_16x16x32_bf16 v[138:141], v[28:31], v[170:173], v[138:141]
	v_mfma_f32_16x16x32_bf16 v[142:145], v[120:123], v[170:173], v[142:145]
	v_mfma_f32_16x16x32_bf16 v[146:149], v[28:31], v[178:181], v[146:149]
	v_mfma_f32_16x16x32_bf16 v[150:153], v[120:123], v[178:181], v[150:153]
	v_mfma_f32_16x16x32_bf16 v[154:157], v[28:31], v[186:189], v[154:157]
	v_mfma_f32_16x16x32_bf16 v[158:161], v[120:123], v[186:189], v[158:161]
	v_mfma_f32_16x16x32_bf16 v[4:7], v[32:35], v[204:207], v[4:7]
	v_mfma_f32_16x16x32_bf16 v[8:11], v[124:127], v[204:207], v[8:11]
	v_mfma_f32_16x16x32_bf16 v[138:141], v[32:35], v[174:177], v[138:141]
	v_mfma_f32_16x16x32_bf16 v[142:145], v[124:127], v[174:177], v[142:145]
	v_mfma_f32_16x16x32_bf16 v[146:149], v[32:35], v[182:185], v[146:149]
	v_mfma_f32_16x16x32_bf16 v[150:153], v[124:127], v[182:185], v[150:153]
	v_mfma_f32_16x16x32_bf16 v[154:157], v[32:35], v[190:193], v[154:157]
	v_mfma_f32_16x16x32_bf16 v[158:161], v[124:127], v[190:193], v[158:161]
	v_mfma_f32_16x16x32_bf16 v[12:15], v[128:131], v[170:173], v[12:15]
	v_mfma_f32_16x16x32_bf16 v[16:19], v[162:165], v[170:173], v[16:19]
	v_mfma_f32_16x16x32_bf16 v[28:31], v[128:131], v[178:181], v[64:67]
	v_mfma_f32_16x16x32_bf16 v[32:35], v[162:165], v[178:181], v[108:111]
	v_mfma_f32_16x16x32_bf16 v[64:67], v[128:131], v[186:189], v[112:115]
	v_mfma_f32_16x16x32_bf16 v[108:111], v[162:165], v[186:189], v[116:119]
	v_mfma_f32_16x16x32_bf16 v[20:23], v[128:131], v[200:203], v[20:23]
	v_mfma_f32_16x16x32_bf16 v[24:27], v[162:165], v[200:203], v[24:27]
	v_mfma_f32_16x16x32_bf16 v[12:15], v[132:135], v[174:177], v[12:15]
	v_mfma_f32_16x16x32_bf16 v[16:19], v[166:169], v[174:177], v[16:19]
	v_mfma_f32_16x16x32_bf16 v[28:31], v[132:135], v[182:185], v[28:31]
	v_mfma_f32_16x16x32_bf16 v[32:35], v[166:169], v[182:185], v[32:35]
	v_mfma_f32_16x16x32_bf16 v[64:67], v[132:135], v[190:193], v[64:67]
	v_mfma_f32_16x16x32_bf16 v[108:111], v[166:169], v[190:193], v[108:111]
	v_mfma_f32_16x16x32_bf16 v[20:23], v[132:135], v[204:207], v[20:23]
	v_mfma_f32_16x16x32_bf16 v[24:27], v[166:169], v[204:207], v[24:27]
	s_setprio 0
	s_barrier
	ds_read_b128 v[112:115], v214
	ds_read_b128 v[116:119], v214 offset:1024
	ds_read_b128 v[120:123], v214 offset:2048
	ds_read_b128 v[124:127], v214 offset:3072
	ds_read_b128 v[128:131], v215
	ds_read_b128 v[132:135], v215 offset:1024
	ds_read_b128 v[162:165], v215 offset:2048
	ds_read_b128 v[166:169], v215 offset:3072
	s_add_u32 s10, s10, 0x10180
	s_addc_u32 s11, s11, 0
	s_mov_b32 m0, s62
	v_lshl_add_u64 v[194:195], s[10:11], 0, v[136:137]
	ds_read_b128 v[170:173], v222
	ds_read_b128 v[174:177], v222 offset:1024
	ds_read_b128 v[178:181], v222 offset:2048
	ds_read_b128 v[182:185], v222 offset:3072
	ds_read_b128 v[186:189], v222 offset:4096
	ds_read_b128 v[190:193], v222 offset:5120
	ds_read_b128 v[200:203], v222 offset:6144
	ds_read_b128 v[204:207], v222 offset:7168
	global_load_lds_dwordx4 v[194:195], off
	v_lshl_add_u64 v[194:195], s[10:11], 0, v[96:97]
	s_mov_b32 m0, s9
	s_nop 0
	global_load_lds_dwordx4 v[194:195], off
	s_waitcnt vmcnt(8)
	s_waitcnt lgkmcnt(0)
	s_barrier
; #define PG8_STAGE(bufoff, gbase, voff) do { _Pragma("unroll") for (int _i = 0; _i < 2; ++_i) \
;         __builtin_amdgcn_global_load_lds((const unsigned*)((const char*)(gbase) + (voff)[_i]), (PG8_LAS unsigned*)(lds + (bufoff) + ldsw + _i * 8192), 16, 0, 0); } while (0)
; #define PG8_LDA(dst, b, h) do { _Pragma("unroll") for (int m = 0; m < 4; ++m) _Pragma("unroll") for (int k = 0; k < 2; ++k) dst[m][k] = *(const PG8_LAS bf16x8*)(lds + PG8_SA(b, h) + aoff + m * 2048 + k * 1024); } while (0)
; #define PG8_MMA(ai, bj, At, Bt) do { __builtin_amdgcn_s_setprio(1); _Pragma("unroll") for (int m = 0; m < 4; ++m) _Pragma("unroll") for (int n = 0; n < 2; ++n) _Pragma("unroll") for (int k = 0; k < 2; ++k) \
;         acc[ai][bj][m][n] = __builtin_amdgcn_mfma_f32_16x16x32_bf16(Bt[n][k], At[m][k], acc[ai][bj][m][n], 0, 0, 0); __builtin_amdgcn_s_setprio(0); } while (0)
; #define PG8_WAIT_V(n) asm volatile("s_waitcnt vmcnt(" #n ")" ::: "memory")
; #define PG8_WAIT_L(n) asm volatile("s_waitcnt lgkmcnt(" #n ")" ::: "memory")
; #define PG8_BAR __builtin_amdgcn_s_barrier()
; #define PG8_SCHED __builtin_amdgcn_sched_barrier(0)
; template <class Epi, class Sched, bool ALIGN_EPI = false, bool SP2 = false>
; __device__ __forceinline__ void gemm_phase(PG8_LAS unsigned char* lds, const Gemm g, const Sched& S, const Epi& E, const int tid_in) {
;     ...
;             PG8_WAIT_V(8); PG8_WAIT_L(0); PG8_BAR; PG8_MMA(0, 0, At, B0); PG8_MMA(0, 1, At, B1); PG8_BAR; PG8_SCHED;
;             PG8_LDA(At, 0, 1); PG8_STAGE(PG8_SB(0, 0), b2, voffB); PG8_STAGE(PG8_SB(0, 1), b2 + hstepB, voffB); PG8_STAGE(PG8_SA(0, 0), a2, voffA);
;             PG8_WAIT_V(8); PG8_WAIT_L(0); PG8_BAR; PG8_MMA(1, 0, At, B0); PG8_MMA(1, 1, At, B1); PG8_BAR; PG8_SCHED;
	s_setprio 1
	s_waitcnt lgkmcnt(0)
	v_mfma_f32_16x16x32_bf16 v[68:71], v[112:115], v[170:173], v[68:71]
	v_mfma_f32_16x16x32_bf16 v[72:75], v[120:123], v[170:173], v[72:75]
	v_mfma_f32_16x16x32_bf16 v[76:79], v[112:115], v[178:181], v[76:79]
	v_mfma_f32_16x16x32_bf16 v[80:83], v[120:123], v[178:181], v[80:83]
	v_mfma_f32_16x16x32_bf16 v[84:87], v[112:115], v[186:189], v[84:87]
	v_mfma_f32_16x16x32_bf16 v[88:91], v[120:123], v[186:189], v[88:91]
	v_mfma_f32_16x16x32_bf16 v[92:95], v[112:115], v[200:203], v[92:95]
	v_mfma_f32_16x16x32_bf16 v[68:71], v[116:119], v[174:177], v[68:71]
	v_mfma_f32_16x16x32_bf16 v[72:75], v[124:127], v[174:177], v[72:75]
	v_mfma_f32_16x16x32_bf16 v[76:79], v[116:119], v[182:185], v[76:79]
	v_mfma_f32_16x16x32_bf16 v[80:83], v[124:127], v[182:185], v[80:83]
	v_mfma_f32_16x16x32_bf16 v[84:87], v[116:119], v[190:193], v[84:87]
	v_mfma_f32_16x16x32_bf16 v[88:91], v[124:127], v[190:193], v[88:91]
	v_mfma_f32_16x16x32_bf16 v[208:211], v[116:119], v[204:207], v[92:95]
	v_mfma_f32_16x16x32_bf16 v[92:95], v[120:123], v[200:203], v[100:103]
	v_mfma_f32_16x16x32_bf16 v[212:215], v[124:127], v[204:207], v[92:95]
	v_mfma_f32_16x16x32_bf16 v[92:95], v[128:131], v[170:173], v[104:107]
	v_mfma_f32_16x16x32_bf16 v[36:39], v[162:165], v[170:173], v[36:39]
	v_mfma_f32_16x16x32_bf16 v[40:43], v[128:131], v[178:181], v[40:43]
	v_mfma_f32_16x16x32_bf16 v[44:47], v[162:165], v[178:181], v[44:47]
	v_mfma_f32_16x16x32_bf16 v[48:51], v[128:131], v[186:189], v[48:51]
	v_mfma_f32_16x16x32_bf16 v[52:55], v[162:165], v[186:189], v[52:55]
	v_mfma_f32_16x16x32_bf16 v[56:59], v[128:131], v[200:203], v[56:59]
	v_mfma_f32_16x16x32_bf16 v[60:63], v[162:165], v[200:203], v[60:63]
	v_mfma_f32_16x16x32_bf16 v[104:107], v[132:135], v[174:177], v[92:95]
	v_mfma_f32_16x16x32_bf16 v[36:39], v[166:169], v[174:177], v[36:39]
	v_mfma_f32_16x16x32_bf16 v[40:43], v[132:135], v[182:185], v[40:43]
	v_mfma_f32_16x16x32_bf16 v[44:47], v[166:169], v[182:185], v[44:47]
	v_mfma_f32_16x16x32_bf16 v[48:51], v[132:135], v[190:193], v[48:51]
	v_mfma_f32_16x16x32_bf16 v[52:55], v[166:169], v[190:193], v[52:55]
	v_mfma_f32_16x16x32_bf16 v[56:59], v[132:135], v[204:207], v[56:59]
	v_mfma_f32_16x16x32_bf16 v[60:63], v[166:169], v[204:207], v[60:63]
	s_setprio 0
	s_barrier
	s_mov_b32 m0, s60
	v_lshl_add_u64 v[220:221], s[38:39], 0, v[136:137]
	s_add_u32 s10, s38, 0x10000
	ds_read_b128 v[92:95], v222 offset:16384
	ds_read_b128 v[100:103], v222 offset:17408
	ds_read_b128 v[170:173], v222 offset:18432
	ds_read_b128 v[174:177], v222 offset:19456
	ds_read_b128 v[178:181], v222 offset:20480
	ds_read_b128 v[182:185], v222 offset:21504
	ds_read_b128 v[186:189], v222 offset:22528
	ds_read_b128 v[190:193], v222 offset:23552
	global_load_lds_dwordx4 v[220:221], off
	v_lshl_add_u64 v[250:251], s[38:39], 0, v[96:97]
	s_mov_b32 m0, s27
	s_addc_u32 s11, s39, 0
	global_load_lds_dwordx4 v[250:251], off
	v_lshl_add_u64 v[194:195], s[10:11], 0, v[136:137]
	s_mov_b32 m0, s29
	v_lshl_add_u64 v[232:233], s[40:41], 0, v[136:137]
	global_load_lds_dwordx4 v[194:195], off
	v_lshl_add_u64 v[194:195], s[10:11], 0, v[96:97]
	s_mov_b32 m0, s37
	v_lshl_add_u64 v[236:237], s[40:41], 0, v[96:97]
	global_load_lds_dwordx4 v[194:195], off
	s_mov_b32 m0, s47
	s_nop 0
	global_load_lds_dwordx4 v[232:233], off
	s_mov_b32 m0, s48
	s_nop 0
	global_load_lds_dwordx4 v[236:237], off
	s_waitcnt vmcnt(8)
	s_waitcnt lgkmcnt(0)
	s_barrier
	s_setprio 1
	s_waitcnt lgkmcnt(0)
	v_mfma_f32_16x16x32_bf16 v[4:7], v[112:115], v[186:189], v[4:7]
	v_mfma_f32_16x16x32_bf16 v[8:11], v[120:123], v[186:189], v[8:11]
	v_mfma_f32_16x16x32_bf16 v[138:141], v[112:115], v[92:95], v[138:141]
	v_mfma_f32_16x16x32_bf16 v[142:145], v[120:123], v[92:95], v[142:145]
	v_mfma_f32_16x16x32_bf16 v[146:149], v[112:115], v[170:173], v[146:149]
	v_mfma_f32_16x16x32_bf16 v[150:153], v[120:123], v[170:173], v[150:153]
	v_mfma_f32_16x16x32_bf16 v[154:157], v[112:115], v[178:181], v[154:157]
	v_mfma_f32_16x16x32_bf16 v[158:161], v[120:123], v[178:181], v[158:161]
	v_mfma_f32_16x16x32_bf16 v[4:7], v[116:119], v[190:193], v[4:7]
	v_mfma_f32_16x16x32_bf16 v[8:11], v[124:127], v[190:193], v[8:11]
	v_mfma_f32_16x16x32_bf16 v[138:141], v[116:119], v[100:103], v[138:141]
	v_mfma_f32_16x16x32_bf16 v[142:145], v[124:127], v[100:103], v[142:145]
	v_mfma_f32_16x16x32_bf16 v[146:149], v[116:119], v[174:177], v[146:149]
	v_mfma_f32_16x16x32_bf16 v[150:153], v[124:127], v[174:177], v[150:153]
	v_mfma_f32_16x16x32_bf16 v[154:157], v[116:119], v[182:185], v[154:157]
	v_mfma_f32_16x16x32_bf16 v[158:161], v[124:127], v[182:185], v[158:161]
	v_mfma_f32_16x16x32_bf16 v[12:15], v[128:131], v[92:95], v[12:15]
	v_mfma_f32_16x16x32_bf16 v[200:203], v[132:135], v[100:103], v[12:15]
	v_mfma_f32_16x16x32_bf16 v[12:15], v[162:165], v[92:95], v[16:19]
	v_mfma_f32_16x16x32_bf16 v[204:207], v[166:169], v[100:103], v[12:15]
	v_mfma_f32_16x16x32_bf16 v[12:15], v[128:131], v[170:173], v[28:31]
	v_mfma_f32_16x16x32_bf16 v[216:219], v[132:135], v[174:177], v[12:15]
	v_mfma_f32_16x16x32_bf16 v[12:15], v[162:165], v[170:173], v[32:35]
	v_mfma_f32_16x16x32_bf16 v[170:173], v[166:169], v[174:177], v[12:15]
	v_mfma_f32_16x16x32_bf16 v[12:15], v[128:131], v[178:181], v[64:67]
	v_mfma_f32_16x16x32_bf16 v[174:177], v[132:135], v[182:185], v[12:15]
	v_mfma_f32_16x16x32_bf16 v[12:15], v[162:165], v[178:181], v[108:111]
	v_mfma_f32_16x16x32_bf16 v[178:181], v[166:169], v[182:185], v[12:15]
	v_mfma_f32_16x16x32_bf16 v[12:15], v[128:131], v[186:189], v[20:23]
	v_mfma_f32_16x16x32_bf16 v[182:185], v[132:135], v[190:193], v[12:15]
	v_mfma_f32_16x16x32_bf16 v[12:15], v[162:165], v[186:189], v[24:27]
	v_mfma_f32_16x16x32_bf16 v[162:165], v[166:169], v[190:193], v[12:15]
	s_setprio 0
	s_barrier
; #define PG8_STAGE(bufoff, gbase, voff) do { _Pragma("unroll") for (int _i = 0; _i < 2; ++_i) \
;         __builtin_amdgcn_global_load_lds((const unsigned*)((const char*)(gbase) + (voff)[_i]), (PG8_LAS unsigned*)(lds + (bufoff) + ldsw + _i * 8192), 16, 0, 0); } while (0)
; #define PG8_LDA(dst, b, h) do { _Pragma("unroll") for (int m = 0; m < 4; ++m) _Pragma("unroll") for (int k = 0; k < 2; ++k) dst[m][k] = *(const PG8_LAS bf16x8*)(lds + PG8_SA(b, h) + aoff + m * 2048 + k * 1024); } while (0)
; #define PG8_LDB(dst, b, h) do { _Pragma("unroll") for (int n = 0; n < 2; ++n) _Pragma("unroll") for (int k = 0; k < 2; ++k) dst[n][k] = *(const PG8_LAS bf16x8*)(lds + PG8_SB(b, h) + boff + n * 2048 + k * 1024); } while (0)
; #define PG8_MMA(ai, bj, At, Bt) do { __builtin_amdgcn_s_setprio(1); _Pragma("unroll") for (int m = 0; m < 4; ++m) _Pragma("unroll") for (int n = 0; n < 2; ++n) _Pragma("unroll") for (int k = 0; k < 2; ++k) \
;         acc[ai][bj][m][n] = __builtin_amdgcn_mfma_f32_16x16x32_bf16(Bt[n][k], At[m][k], acc[ai][bj][m][n], 0, 0, 0); __builtin_amdgcn_s_setprio(0); } while (0)
; #define PG8_WAIT_V(n) asm volatile("s_waitcnt vmcnt(" #n ")" ::: "memory")
; #define PG8_WAIT_L(n) asm volatile("s_waitcnt lgkmcnt(" #n ")" ::: "memory")
; #define PG8_BAR __builtin_amdgcn_s_barrier()
; #define PG8_SCHED __builtin_amdgcn_sched_barrier(0)
; template <class Epi, class Sched, bool ALIGN_EPI = false, bool SP2 = false>
; __device__ __forceinline__ void gemm_phase(PG8_LAS unsigned char* lds, const Gemm g, const Sched& S, const Epi& E, const int tid_in) {
;     ...
;             PG8_LDB(B0, 1, 0); PG8_LDB(B1, 1, 1); PG8_SCHED; PG8_LDA(At, 1, 0); PG8_STAGE(PG8_SA(0, 1), a2 + hstepA, voffA);
;             PG8_WAIT_V(8); PG8_WAIT_L(0); PG8_BAR; PG8_MMA(0, 0, At, B0); PG8_MMA(0, 1, At, B1); PG8_BAR; PG8_SCHED;
;             PG8_LDA(At, 1, 1); PG8_STAGE(PG8_SB(1, 0), b3, voffB); PG8_STAGE(PG8_SB(1, 1), b3 + hstepB, voffB); PG8_STAGE(PG8_SA(1, 0), a3, voffA);
;             PG8_WAIT_V(8); PG8_WAIT_L(0); PG8_BAR; PG8_MMA(1, 0, At, B0); PG8_MMA(1, 1, At, B1); PG8_BAR; PG8_SCHED;
;     ...
;         if constexpr (ALIGN_EPI) { if (wr == 0) PG8_BAR; }
	s_nop 4
	ds_read_b128 v[12:15], v223
	ds_read_b128 v[16:19], v223 offset:1024
	ds_read_b128 v[20:23], v223 offset:2048
	ds_read_b128 v[24:27], v223 offset:3072
	ds_read_b128 v[166:169], v224
	ds_read_b128 v[186:189], v224 offset:1024
	ds_read_b128 v[190:193], v224 offset:2048
	ds_read_b128 v[224:227], v224 offset:3072
	s_add_u32 s10, s40, 0x10000
	s_addc_u32 s11, s41, 0
	s_mov_b32 m0, s49
	v_lshl_add_u64 v[92:93], s[10:11], 0, v[136:137]
	ds_read_b128 v[28:31], v222 offset:32768
	ds_read_b128 v[32:35], v222 offset:33792
	ds_read_b128 v[64:67], v222 offset:34816
	ds_read_b128 v[238:241], v222 offset:35840
	ds_read_b128 v[242:245], v222 offset:36864
	ds_read_b128 v[246:249], v222 offset:37888
	ds_read_b128 v[228:231], v222 offset:38912
	ds_read_b128 v[194:197], v222 offset:39936
	global_load_lds_dwordx4 v[92:93], off
	v_lshl_add_u64 v[92:93], s[10:11], 0, v[96:97]
	s_mov_b32 m0, s52
	s_nop 0
	global_load_lds_dwordx4 v[92:93], off
	s_waitcnt vmcnt(8)
	s_waitcnt lgkmcnt(0)
	s_barrier
	s_setprio 1
	s_waitcnt lgkmcnt(0)
	v_mfma_f32_16x16x32_bf16 v[68:71], v[12:15], v[28:31], v[68:71]
	v_mfma_f32_16x16x32_bf16 v[132:135], v[16:19], v[32:35], v[68:71]
	v_mfma_f32_16x16x32_bf16 v[68:71], v[20:23], v[28:31], v[72:75]
	v_mfma_f32_16x16x32_bf16 v[128:131], v[24:27], v[32:35], v[68:71]
	v_mfma_f32_16x16x32_bf16 v[68:71], v[12:15], v[64:67], v[76:79]
	v_mfma_f32_16x16x32_bf16 v[116:119], v[16:19], v[238:241], v[68:71]
	v_mfma_f32_16x16x32_bf16 v[68:71], v[20:23], v[64:67], v[80:83]
	v_mfma_f32_16x16x32_bf16 v[112:115], v[24:27], v[238:241], v[68:71]
	v_mfma_f32_16x16x32_bf16 v[68:71], v[12:15], v[242:245], v[84:87]
	v_mfma_f32_16x16x32_bf16 v[100:103], v[16:19], v[246:249], v[68:71]
	v_mfma_f32_16x16x32_bf16 v[68:71], v[20:23], v[242:245], v[88:91]
	v_mfma_f32_16x16x32_bf16 v[92:95], v[24:27], v[246:249], v[68:71]
	v_mfma_f32_16x16x32_bf16 v[68:71], v[12:15], v[228:231], v[208:211]
	v_mfma_f32_16x16x32_bf16 v[80:83], v[16:19], v[194:197], v[68:71]
	v_mfma_f32_16x16x32_bf16 v[68:71], v[20:23], v[228:231], v[212:215]
	v_mfma_f32_16x16x32_bf16 v[76:79], v[24:27], v[194:197], v[68:71]
	v_mfma_f32_16x16x32_bf16 v[68:71], v[166:169], v[28:31], v[104:107]
	v_mfma_f32_16x16x32_bf16 v[28:31], v[190:193], v[28:31], v[36:39]
	v_mfma_f32_16x16x32_bf16 v[120:123], v[224:227], v[32:35], v[28:31]
	v_mfma_f32_16x16x32_bf16 v[28:31], v[166:169], v[64:67], v[40:43]
	v_mfma_f32_16x16x32_bf16 v[108:111], v[186:189], v[238:241], v[28:31]
	v_mfma_f32_16x16x32_bf16 v[28:31], v[190:193], v[64:67], v[44:47]
	v_mfma_f32_16x16x32_bf16 v[104:107], v[224:227], v[238:241], v[28:31]
	v_mfma_f32_16x16x32_bf16 v[28:31], v[166:169], v[242:245], v[48:51]
	v_mfma_f32_16x16x32_bf16 v[88:91], v[186:189], v[246:249], v[28:31]
	v_mfma_f32_16x16x32_bf16 v[28:31], v[190:193], v[242:245], v[52:55]
	v_mfma_f32_16x16x32_bf16 v[84:87], v[224:227], v[246:249], v[28:31]
	v_mfma_f32_16x16x32_bf16 v[28:31], v[166:169], v[228:231], v[56:59]
	v_mfma_f32_16x16x32_bf16 v[72:75], v[186:189], v[194:197], v[28:31]
	v_mfma_f32_16x16x32_bf16 v[28:31], v[190:193], v[228:231], v[60:63]
	v_mfma_f32_16x16x32_bf16 v[124:127], v[186:189], v[32:35], v[68:71]
	v_mfma_f32_16x16x32_bf16 v[68:71], v[224:227], v[194:197], v[28:31]
	s_setprio 0
	s_barrier
	s_mov_b32 m0, s63
	s_nop 2
	v_lshl_add_u64 v[28:29], v[220:221], 0, s[50:51]
	s_add_u32 s10, s38, 0x10080
	ds_read_b128 v[36:39], v222 offset:49152
	ds_read_b128 v[40:43], v222 offset:50176
	ds_read_b128 v[194:197], v222 offset:51200
	ds_read_b128 v[208:211], v222 offset:52224
	ds_read_b128 v[212:215], v222 offset:53248
	ds_read_b128 v[228:231], v222 offset:54272
	ds_read_b128 v[238:241], v222 offset:55296
	ds_read_b128 v[242:245], v222 offset:56320
	global_load_lds_dwordx4 v[28:29], off
	v_lshl_add_u64 v[28:29], v[250:251], 0, s[50:51]
	s_mov_b32 m0, s61
	s_addc_u32 s11, s39, 0
	global_load_lds_dwordx4 v[28:29], off
	v_lshl_add_u64 v[28:29], s[10:11], 0, v[136:137]
	s_mov_b32 m0, s12
	s_nop 0
	global_load_lds_dwordx4 v[28:29], off
	v_lshl_add_u64 v[28:29], s[10:11], 0, v[96:97]
	s_mov_b32 m0, s13
	s_nop 0
	global_load_lds_dwordx4 v[28:29], off
	v_lshl_add_u64 v[28:29], v[232:233], 0, s[50:51]
	s_mov_b32 m0, s56
	s_nop 0
	global_load_lds_dwordx4 v[28:29], off
	v_lshl_add_u64 v[28:29], v[236:237], 0, s[50:51]
	s_mov_b32 m0, s57
	s_nop 0
	global_load_lds_dwordx4 v[28:29], off
	s_waitcnt vmcnt(8)
	s_waitcnt lgkmcnt(0)
	s_barrier
	s_setprio 1
	s_waitcnt lgkmcnt(0)
	v_mfma_f32_16x16x32_bf16 v[28:31], v[12:15], v[36:39], v[138:141]
	v_mfma_f32_16x16x32_bf16 v[64:67], v[16:19], v[40:43], v[28:31]
	v_mfma_f32_16x16x32_bf16 v[28:31], v[20:23], v[36:39], v[142:145]
	v_mfma_f32_16x16x32_bf16 v[60:63], v[24:27], v[40:43], v[28:31]
	v_mfma_f32_16x16x32_bf16 v[28:31], v[12:15], v[194:197], v[146:149]
	v_mfma_f32_16x16x32_bf16 v[48:51], v[16:19], v[208:211], v[28:31]
	v_mfma_f32_16x16x32_bf16 v[28:31], v[20:23], v[194:197], v[150:153]
	v_mfma_f32_16x16x32_bf16 v[44:47], v[24:27], v[208:211], v[28:31]
	v_mfma_f32_16x16x32_bf16 v[28:31], v[12:15], v[212:215], v[154:157]
	v_mfma_f32_16x16x32_bf16 v[4:7], v[12:15], v[238:241], v[4:7]
	v_mfma_f32_16x16x32_bf16 v[32:35], v[16:19], v[228:231], v[28:31]
	v_mfma_f32_16x16x32_bf16 v[28:31], v[20:23], v[212:215], v[158:161]
	v_mfma_f32_16x16x32_bf16 v[16:19], v[16:19], v[242:245], v[4:7]
	v_mfma_f32_16x16x32_bf16 v[4:7], v[20:23], v[238:241], v[8:11]
	v_mfma_f32_16x16x32_bf16 v[28:31], v[24:27], v[228:231], v[28:31]
	v_mfma_f32_16x16x32_bf16 v[12:15], v[24:27], v[242:245], v[4:7]
	v_mfma_f32_16x16x32_bf16 v[4:7], v[166:169], v[36:39], v[200:203]
	v_mfma_f32_16x16x32_bf16 v[56:59], v[186:189], v[40:43], v[4:7]
	v_mfma_f32_16x16x32_bf16 v[4:7], v[190:193], v[36:39], v[204:207]
	v_mfma_f32_16x16x32_bf16 v[52:55], v[224:227], v[40:43], v[4:7]
	v_mfma_f32_16x16x32_bf16 v[4:7], v[166:169], v[194:197], v[216:219]
	v_mfma_f32_16x16x32_bf16 v[40:43], v[186:189], v[208:211], v[4:7]
	v_mfma_f32_16x16x32_bf16 v[4:7], v[190:193], v[194:197], v[170:173]
	v_mfma_f32_16x16x32_bf16 v[36:39], v[224:227], v[208:211], v[4:7]
	v_mfma_f32_16x16x32_bf16 v[4:7], v[166:169], v[212:215], v[174:177]
	v_mfma_f32_16x16x32_bf16 v[24:27], v[186:189], v[228:231], v[4:7]
	v_mfma_f32_16x16x32_bf16 v[4:7], v[190:193], v[212:215], v[178:181]
	v_mfma_f32_16x16x32_bf16 v[20:23], v[224:227], v[228:231], v[4:7]
	v_mfma_f32_16x16x32_bf16 v[4:7], v[166:169], v[238:241], v[182:185]
	v_mfma_f32_16x16x32_bf16 v[8:11], v[186:189], v[242:245], v[4:7]
	v_mfma_f32_16x16x32_bf16 v[4:7], v[190:193], v[238:241], v[162:165]
	v_mfma_f32_16x16x32_bf16 v[4:7], v[224:227], v[242:245], v[4:7]
	s_setprio 0
	s_barrier
	s_andn2_b64 vcc, exec, s[18:19]
	s_cbranch_vccnz .LBB0_1152
	s_barrier
